# silu in FFN-up / SSD-in GEMM epilogues: x*rcp(1+exp(-x)) (f32 v_rcp) instead of the IEEE division expansion
# speedup vs baseline: 1.0139x; 1.0094x over previous
.LBB0_1029:
	v_mul_f32_e32 v74, v49, v49
	v_fmac_f32_e32 v74, v48, v48
	v_fmac_f32_e32 v74, v50, v50
	v_fmac_f32_e32 v74, v51, v51
	v_fmac_f32_e32 v74, v52, v52
	v_fmac_f32_e32 v74, v53, v53
	v_fmac_f32_e32 v74, v54, v54
	v_fmac_f32_e32 v74, v55, v55
	v_fmac_f32_e32 v74, v56, v56
	v_fmac_f32_e32 v74, v57, v57
	v_fmac_f32_e32 v74, v58, v58
	v_fmac_f32_e32 v74, v59, v59
	v_fmac_f32_e32 v74, v60, v60
	v_fmac_f32_e32 v74, v61, v61
	v_fmac_f32_e32 v74, v62, v62
	v_fmac_f32_e32 v74, v63, v63
	v_fmac_f32_e32 v74, v32, v32
	v_fmac_f32_e32 v74, v33, v33
	v_fmac_f32_e32 v74, v34, v34
	v_fmac_f32_e32 v74, v35, v35
	v_fmac_f32_e32 v74, v36, v36
	v_fmac_f32_e32 v74, v37, v37
	v_fmac_f32_e32 v74, v38, v38
	v_fmac_f32_e32 v74, v39, v39
	v_fmac_f32_e32 v74, v40, v40
	v_fmac_f32_e32 v74, v41, v41
	v_fmac_f32_e32 v74, v42, v42
	v_fmac_f32_e32 v74, v43, v43
	v_fmac_f32_e32 v74, v44, v44
	v_fmac_f32_e32 v74, v45, v45
	v_fmac_f32_e32 v74, v46, v46
	v_fmac_f32_e32 v74, v47, v47
	v_fmac_f32_e32 v74, v16, v16
	v_fmac_f32_e32 v74, v17, v17
	v_fmac_f32_e32 v74, v18, v18
	v_fmac_f32_e32 v74, v19, v19
	v_fmac_f32_e32 v74, v20, v20
	v_fmac_f32_e32 v74, v21, v21
	v_fmac_f32_e32 v74, v22, v22
	v_fmac_f32_e32 v74, v23, v23
	v_fmac_f32_e32 v74, v24, v24
	v_fmac_f32_e32 v74, v25, v25
	v_fmac_f32_e32 v74, v26, v26
	v_fmac_f32_e32 v74, v27, v27
	v_fmac_f32_e32 v74, v28, v28
	v_fmac_f32_e32 v74, v29, v29
	v_fmac_f32_e32 v74, v30, v30
	v_fmac_f32_e32 v74, v31, v31
	v_fmac_f32_e32 v74, v0, v0
	v_fmac_f32_e32 v74, v1, v1
	v_fmac_f32_e32 v74, v2, v2
	v_fmac_f32_e32 v74, v3, v3
	v_fmac_f32_e32 v74, v4, v4
	v_fmac_f32_e32 v74, v5, v5
	v_pk_mul_f32 v[72:73], v[6:7], v[6:7]
	v_pk_mul_f32 v[70:71], v[8:9], v[8:9]
	v_add_f32_e32 v72, v72, v74
	v_add_f32_e32 v72, v73, v72
	v_add_f32_e32 v70, v70, v72
	v_pk_mul_f32 v[68:69], v[10:11], v[10:11]
	v_add_f32_e32 v70, v71, v70
	v_add_f32_e32 v68, v68, v70
	v_pk_mul_f32 v[66:67], v[12:13], v[12:13]
	v_add_f32_e32 v68, v69, v68
	v_add_f32_e32 v66, v66, v68
	v_pk_mul_f32 v[64:65], v[14:15], v[14:15]
	v_add_f32_e32 v66, v67, v66
	v_add_f32_e32 v64, v64, v66
	v_add_f32_e32 v64, v65, v64
	v_mov_b32_e32 v65, v221
	global_load_dwordx4 v[80:83], v[154:155], off
	global_load_dwordx4 v[84:87], v[154:155], off offset:32
	global_load_dwordx4 v[88:91], v[154:155], off offset:64
	global_load_dwordx4 v[92:95], v[154:155], off offset:96
	global_load_dwordx4 v[96:99], v[154:155], off offset:128
	global_load_dwordx4 v[100:103], v[154:155], off offset:160
	global_load_dwordx4 v[104:107], v[154:155], off offset:192
	global_load_dwordx4 v[108:111], v[154:155], off offset:224
	global_load_dwordx4 v[112:115], v[154:155], off offset:256
	global_load_dwordx4 v[116:119], v[154:155], off offset:288
	global_load_dwordx4 v[120:123], v[154:155], off offset:320
	global_load_dwordx4 v[124:127], v[154:155], off offset:352
	global_load_dwordx4 v[130:133], v[154:155], off offset:384
	global_load_dwordx4 v[134:137], v[154:155], off offset:416
	global_load_dwordx4 v[138:141], v[154:155], off offset:448
	global_load_dwordx4 v[142:145], v[154:155], off offset:480
	v_lshlrev_b32_e32 v65, 2, v65
	v_xor_b32_e32 v65, 0x80, v65
	ds_bpermute_b32 v65, v65, v64
	s_mov_b32 s2, 0x800000
	v_lshl_add_u64 v[66:67], v[172:173], 1, s[0:1]
	s_lshl_b32 s18, s14, 1
	v_lshl_add_u64 v[66:67], v[66:67], 0, s[18:19]
	s_waitcnt lgkmcnt(0)
	v_add_f32_e32 v64, v64, v65
	v_fmamk_f32 v64, v64, 0x3c000000, v162
	v_cmp_gt_f32_e32 vcc, s2, v64
	v_mul_f32_e32 v65, 0x4b800000, v64
	v_mov_b32_e32 v169, v129
	v_cndmask_b32_e32 v64, v64, v65, vcc
	v_rsq_f32_e32 v64, v64
	v_lshl_add_u64 v[66:67], v[66:67], 0, v[168:169]
	s_mov_b32 s3, s19
	v_writelane_b32 v252, s2, 12
	v_mul_f32_e32 v65, 0x45800000, v64
	v_cndmask_b32_e32 v64, v64, v65, vcc
	v_writelane_b32 v252, s3, 13
	v_mul_f32_e32 v64, v190, v64
	v_readlane_b32 s2, v252, 2
	s_add_i32 s16, s16, s2
	s_cmpk_gt_i32 s16, 0x3ff
	v_pk_mul_f32 v[0:1], v[0:1], v[64:65] op_sel_hi:[1,0]
	v_pk_mul_f32 v[2:3], v[2:3], v[64:65] op_sel_hi:[1,0]
	v_pk_mul_f32 v[4:5], v[4:5], v[64:65] op_sel_hi:[1,0]
	v_pk_mul_f32 v[6:7], v[6:7], v[64:65] op_sel_hi:[1,0]
	v_pk_mul_f32 v[8:9], v[8:9], v[64:65] op_sel_hi:[1,0]
	v_pk_mul_f32 v[10:11], v[10:11], v[64:65] op_sel_hi:[1,0]
	v_pk_mul_f32 v[12:13], v[12:13], v[64:65] op_sel_hi:[1,0]
	v_pk_mul_f32 v[14:15], v[14:15], v[64:65] op_sel_hi:[1,0]
	v_pk_mul_f32 v[16:17], v[16:17], v[64:65] op_sel_hi:[1,0]
	v_pk_mul_f32 v[18:19], v[18:19], v[64:65] op_sel_hi:[1,0]
	v_pk_mul_f32 v[20:21], v[20:21], v[64:65] op_sel_hi:[1,0]
	v_pk_mul_f32 v[22:23], v[22:23], v[64:65] op_sel_hi:[1,0]
	v_pk_mul_f32 v[24:25], v[24:25], v[64:65] op_sel_hi:[1,0]
	v_pk_mul_f32 v[26:27], v[26:27], v[64:65] op_sel_hi:[1,0]
	v_pk_mul_f32 v[28:29], v[28:29], v[64:65] op_sel_hi:[1,0]
	v_pk_mul_f32 v[30:31], v[30:31], v[64:65] op_sel_hi:[1,0]
	v_pk_mul_f32 v[32:33], v[32:33], v[64:65] op_sel_hi:[1,0]
	v_pk_mul_f32 v[34:35], v[34:35], v[64:65] op_sel_hi:[1,0]
	v_pk_mul_f32 v[36:37], v[36:37], v[64:65] op_sel_hi:[1,0]
	v_pk_mul_f32 v[38:39], v[38:39], v[64:65] op_sel_hi:[1,0]
	v_pk_mul_f32 v[40:41], v[40:41], v[64:65] op_sel_hi:[1,0]
	v_pk_mul_f32 v[42:43], v[42:43], v[64:65] op_sel_hi:[1,0]
	v_pk_mul_f32 v[44:45], v[44:45], v[64:65] op_sel_hi:[1,0]
	v_pk_mul_f32 v[46:47], v[46:47], v[64:65] op_sel_hi:[1,0]
	v_pk_mul_f32 v[48:49], v[48:49], v[64:65] op_sel_hi:[1,0]
	v_pk_mul_f32 v[50:51], v[50:51], v[64:65] op_sel_hi:[1,0]
	v_pk_mul_f32 v[52:53], v[52:53], v[64:65] op_sel_hi:[1,0]
	v_pk_mul_f32 v[54:55], v[54:55], v[64:65] op_sel_hi:[1,0]
	v_pk_mul_f32 v[56:57], v[56:57], v[64:65] op_sel_hi:[1,0]
	v_pk_mul_f32 v[58:59], v[58:59], v[64:65] op_sel_hi:[1,0]
	v_pk_mul_f32 v[60:61], v[60:61], v[64:65] op_sel_hi:[1,0]
	v_pk_mul_f32 v[62:63], v[62:63], v[64:65] op_sel_hi:[1,0]
	s_waitcnt vmcnt(0)
	v_pk_mul_f32 v[48:49], v[80:81], v[48:49]
	v_pk_mul_f32 v[50:51], v[82:83], v[50:51]
	v_cvt_pk_bf16_f32 v48, v48, v49
	v_cvt_pk_bf16_f32 v49, v50, v51
	global_store_dwordx2 v[66:67], v[48:49], off
	v_pk_mul_f32 v[52:53], v[84:85], v[52:53]
	v_pk_mul_f32 v[54:55], v[86:87], v[54:55]
	v_cvt_pk_bf16_f32 v52, v52, v53
	v_cvt_pk_bf16_f32 v53, v54, v55
	global_store_dwordx2 v[66:67], v[52:53], off offset:16
	v_pk_mul_f32 v[56:57], v[88:89], v[56:57]
	v_pk_mul_f32 v[58:59], v[90:91], v[58:59]
	v_cvt_pk_bf16_f32 v56, v56, v57
	v_cvt_pk_bf16_f32 v57, v58, v59
	global_store_dwordx2 v[66:67], v[56:57], off offset:32
	v_pk_mul_f32 v[60:61], v[92:93], v[60:61]
	v_pk_mul_f32 v[62:63], v[94:95], v[62:63]
	v_cvt_pk_bf16_f32 v60, v60, v61
	v_cvt_pk_bf16_f32 v61, v62, v63
	global_store_dwordx2 v[66:67], v[60:61], off offset:48
	v_pk_mul_f32 v[32:33], v[96:97], v[32:33]
	v_pk_mul_f32 v[34:35], v[98:99], v[34:35]
	v_cvt_pk_bf16_f32 v32, v32, v33
	v_cvt_pk_bf16_f32 v33, v34, v35
	global_store_dwordx2 v[66:67], v[32:33], off offset:64
	v_pk_mul_f32 v[36:37], v[100:101], v[36:37]
	v_pk_mul_f32 v[38:39], v[102:103], v[38:39]
	v_cvt_pk_bf16_f32 v36, v36, v37
	v_cvt_pk_bf16_f32 v37, v38, v39
	global_store_dwordx2 v[66:67], v[36:37], off offset:80
	v_pk_mul_f32 v[40:41], v[104:105], v[40:41]
	v_pk_mul_f32 v[42:43], v[106:107], v[42:43]
	v_cvt_pk_bf16_f32 v40, v40, v41
	v_cvt_pk_bf16_f32 v41, v42, v43
	global_store_dwordx2 v[66:67], v[40:41], off offset:96
	v_pk_mul_f32 v[44:45], v[108:109], v[44:45]
	v_pk_mul_f32 v[46:47], v[110:111], v[46:47]
	v_cvt_pk_bf16_f32 v44, v44, v45
	v_cvt_pk_bf16_f32 v45, v46, v47
	global_store_dwordx2 v[66:67], v[44:45], off offset:112
	v_pk_mul_f32 v[16:17], v[112:113], v[16:17]
	v_pk_mul_f32 v[18:19], v[114:115], v[18:19]
	v_cvt_pk_bf16_f32 v16, v16, v17
	v_cvt_pk_bf16_f32 v17, v18, v19
	global_store_dwordx2 v[66:67], v[16:17], off offset:128
	v_pk_mul_f32 v[20:21], v[116:117], v[20:21]
	v_pk_mul_f32 v[22:23], v[118:119], v[22:23]
	v_cvt_pk_bf16_f32 v20, v20, v21
	v_cvt_pk_bf16_f32 v21, v22, v23
	global_store_dwordx2 v[66:67], v[20:21], off offset:144
	v_pk_mul_f32 v[24:25], v[120:121], v[24:25]
	v_pk_mul_f32 v[26:27], v[122:123], v[26:27]
	v_cvt_pk_bf16_f32 v24, v24, v25
	v_cvt_pk_bf16_f32 v25, v26, v27
	global_store_dwordx2 v[66:67], v[24:25], off offset:160
	v_pk_mul_f32 v[28:29], v[124:125], v[28:29]
	v_pk_mul_f32 v[30:31], v[126:127], v[30:31]
	v_cvt_pk_bf16_f32 v28, v28, v29
	v_cvt_pk_bf16_f32 v29, v30, v31
	global_store_dwordx2 v[66:67], v[28:29], off offset:176
	v_pk_mul_f32 v[0:1], v[130:131], v[0:1]
	v_pk_mul_f32 v[2:3], v[132:133], v[2:3]
	v_cvt_pk_bf16_f32 v0, v0, v1
	v_cvt_pk_bf16_f32 v1, v2, v3
	global_store_dwordx2 v[66:67], v[0:1], off offset:192
	v_pk_mul_f32 v[4:5], v[134:135], v[4:5]
	v_pk_mul_f32 v[6:7], v[136:137], v[6:7]
	v_cvt_pk_bf16_f32 v4, v4, v5
	v_cvt_pk_bf16_f32 v5, v6, v7
	global_store_dwordx2 v[66:67], v[4:5], off offset:208
	v_pk_mul_f32 v[8:9], v[138:139], v[8:9]
	v_pk_mul_f32 v[10:11], v[140:141], v[10:11]
	v_cvt_pk_bf16_f32 v8, v8, v9
	v_cvt_pk_bf16_f32 v9, v10, v11
	global_store_dwordx2 v[66:67], v[8:9], off offset:224
	v_pk_mul_f32 v[12:13], v[142:143], v[12:13]
	v_pk_mul_f32 v[14:15], v[144:145], v[14:15]
	v_cvt_pk_bf16_f32 v12, v12, v13
	v_cvt_pk_bf16_f32 v13, v14, v15
	global_store_dwordx2 v[66:67], v[12:13], off offset:240
	s_cbranch_scc1 .LBB0_1047

.LBB0_1169:
	s_or_b64 exec, exec, s[0:1]
	v_cvt_pk_bf16_f32 v131, v131, s0
	v_lshl_add_u64 v[136:137], v[136:137], 0, v[138:139]
	global_store_short v[136:137], v131, off
	v_mov_b32_e32 v131, v221
	v_mov_b32_e32 v136, v221
	v_lshlrev_b32_e32 v131, 2, v131
	v_xor_b32_e32 v131, 0x80, v131
	ds_bpermute_b32 v135, v131, v112
	v_mov_b32_e32 v131, v221
	v_mov_b32_e32 v139, v112
	v_lshlrev_b32_e32 v131, 2, v131
	v_xor_b32_e32 v131, 0x80, v131
	ds_bpermute_b32 v131, v131, v115
	v_lshlrev_b32_e32 v136, 2, v136
	v_xor_b32_e32 v136, 0x80, v136
	ds_bpermute_b32 v136, v136, v116
	v_pk_mov_b32 v[140:141], v[114:115], v[114:115] op_sel:[1,0]
	s_waitcnt lgkmcnt(1)
	v_cndmask_b32_e64 v138, v131, 0, s[4:5]
	s_waitcnt vmcnt(1)
	v_pk_fma_f32 v[138:139], v[188:189], v[138:139], v[190:191] op_sel_hi:[0,1,0]
	v_pk_fma_f32 v[138:139], v[134:135], v[112:113], v[138:139] op_sel_hi:[0,1,1]
	v_mov_b32_e32 v142, v113
	v_mov_b32_e32 v143, v141
	v_pk_fma_f32 v[138:139], v[186:187], v[142:143], v[138:139] op_sel_hi:[0,1,1]
	s_waitcnt lgkmcnt(0)
	v_cndmask_b32_e64 v146, v136, v135, s[4:5]
	v_mul_f32_e32 v135, 0xbfb8aa3b, v138
	v_exp_f32_e32 v144, v135
	v_mul_f32_e32 v135, 0xbfb8aa3b, v139
	v_exp_f32_e32 v145, v135
	s_cmpk_gt_u32 s24, 0xfff
	s_cselect_b64 s[26:27], -1, 0
	s_cmpk_lt_u32 s24, 0x1400
	v_pk_add_f32 v[144:145], v[144:145], 1.0 op_sel_hi:[1,0]
	s_cselect_b64 s[24:25], -1, 0
	v_rcp_f32_e32 v137, v145
	s_nop 0
	v_mul_f32_e32 v135, v139, v137
	v_rcp_f32_e32 v139, v144
	s_nop 0
	v_mul_f32_e32 v137, v138, v139
	v_pk_fma_f32 v[138:139], v[188:189], v[142:143], v[190:191] op_sel_hi:[0,1,0]
	v_pk_fma_f32 v[138:139], v[114:115], v[134:135], v[138:139] op_sel_hi:[1,0,1]
	v_mov_b32_e32 v141, v146
	v_pk_fma_f32 v[140:141], v[140:141], v[186:187], v[138:139] op_sel_hi:[1,0,1]
	s_nop 0
	v_mul_f32_e32 v138, 0xbfb8aa3b, v140
	v_mul_f32_e32 v139, 0xbfb8aa3b, v141
	v_exp_f32_e32 v138, v138
	v_exp_f32_e32 v139, v139
	s_nop 0
	v_pk_add_f32 v[142:143], v[138:139], 1.0 op_sel_hi:[1,0]
	s_nop 0
	v_rcp_f32_e32 v139, v143
	s_nop 0
	v_mul_f32_e32 v138, v141, v139
	v_rcp_f32_e32 v141, v142
	s_mov_b64 s[0:1], -1
	v_mul_f32_e32 v139, v140, v141
	s_and_b64 vcc, exec, s[26:27]
	s_cbranch_vccz .LBB0_1171
	s_and_b64 s[0:1], s[24:25], exec
	v_or_b32_e32 v140, v239, v158
	v_readlane_b32 s0, v252, 45
	v_readlane_b32 s28, v252, 47
	v_ashrrev_i32_e32 v141, 31, v140
	v_readlane_b32 s1, v252, 46
	v_readlane_b32 s29, v252, 48
	v_lshlrev_b64 v[140:141], 11, v[140:141]
	s_cselect_b32 s1, s1, s29
	s_cselect_b32 s0, s0, s28
	v_readlane_b32 s36, v252, 26
	s_movk_i32 s28, 0xf000
	v_readlane_b32 s37, v252, 27
	v_lshl_add_u64 v[140:141], s[0:1], 0, v[140:141]
	s_mov_b32 s29, s37
	s_cselect_b32 s28, s28, 0xffffe800
	v_lshl_add_u64 v[140:141], v[128:129], 1, v[140:141]
	s_mov_b32 s1, s37
	v_writelane_b32 v252, s0, 26
	v_lshl_add_u64 v[140:141], v[140:141], 0, s[28:29]
	s_nop 0
	v_cvt_pk_bf16_f32 v142, v137, s0
	global_store_short v[140:141], v142, off
	v_cvt_pk_bf16_f32 v142, v135, s0
	global_store_short v[140:141], v142, off offset:2048
	v_add_co_u32_e32 v140, vcc, 0x1000, v140
	v_cvt_pk_bf16_f32 v142, v139, s0
	s_nop 0
	v_addc_co_u32_e32 v141, vcc, 0, v141, vcc
	global_store_short v[140:141], v142, off
	v_cvt_pk_bf16_f32 v142, v138, s0
	v_writelane_b32 v252, s1, 27
	global_store_short v[140:141], v142, off offset:2048
	s_mov_b64 s[0:1], 0

.LBB0_1173:
	v_mov_b32_e32 v133, v221
	v_mov_b32_e32 v189, v188
	v_lshlrev_b32_e32 v133, 2, v133
	v_xor_b32_e32 v133, 0x80, v133
	ds_bpermute_b32 v138, v133, v119
	v_mov_b32_e32 v191, v190
	v_mov_b32_e32 v141, v116
	v_mov_b32_e32 v135, v134
	v_mov_b32_e32 v187, v186
	s_waitcnt lgkmcnt(0)
	v_cndmask_b32_e64 v140, v138, v131, s[4:5]
	v_pk_fma_f32 v[140:141], v[188:189], v[140:141], v[190:191]
	v_mov_b32_e32 v142, v117
	v_pk_fma_f32 v[140:141], v[116:117], v[134:135], v[140:141]
	v_mov_b32_e32 v143, v118
	v_pk_fma_f32 v[140:141], v[142:143], v[186:187], v[140:141]
	v_mov_b32_e32 v133, v221
	v_mul_f32_e32 v131, 0xbfb8aa3b, v140
	v_exp_f32_e32 v144, v131
	v_mul_f32_e32 v131, 0xbfb8aa3b, v141
	v_exp_f32_e32 v145, v131
	v_or_b32_e32 v182, v239, v204
	v_lshlrev_b32_e32 v133, 2, v133
	v_xor_b32_e32 v133, 0x80, v133
	v_pk_add_f32 v[144:145], v[144:145], 1.0 op_sel_hi:[1,0]
	ds_bpermute_b32 v139, v133, v120
	v_rcp_f32_e32 v133, v145
	s_mov_b64 s[28:29], -1
	s_waitcnt lgkmcnt(0)
	v_cndmask_b32_e64 v137, v139, v136, s[4:5]
	v_ashrrev_i32_e32 v183, 31, v182
	v_mul_f32_e32 v131, v141, v133
	v_rcp_f32_e32 v136, v144
	s_nop 0
	v_mul_f32_e32 v133, v140, v136
	v_pk_fma_f32 v[140:141], v[142:143], v[188:189], v[190:191]
	v_mov_b32_e32 v136, v119
	v_pk_fma_f32 v[140:141], v[118:119], v[134:135], v[140:141]
	s_nop 0
	v_pk_fma_f32 v[140:141], v[136:137], v[186:187], v[140:141]
	s_nop 0
	v_mul_f32_e32 v136, 0xbfb8aa3b, v140
	v_mul_f32_e32 v137, 0xbfb8aa3b, v141
	v_exp_f32_e32 v136, v136
	v_exp_f32_e32 v137, v137
	s_nop 0
	v_pk_add_f32 v[142:143], v[136:137], 1.0 op_sel_hi:[1,0]
	s_nop 0
	v_rcp_f32_e32 v137, v143
	s_nop 0
	v_mul_f32_e32 v136, v141, v137
	v_rcp_f32_e32 v141, v142
	s_nop 0
	v_mul_f32_e32 v137, v140, v141
	v_cndmask_b32_e64 v140, 0, 1, s[26:27]
	v_cmp_ne_u32_e64 s[0:1], 1, v140
	s_andn2_b64 vcc, exec, s[26:27]
	s_cbranch_vccnz .LBB0_1175
	s_and_b64 s[26:27], s[24:25], exec
	v_readlane_b32 s26, v252, 45
	v_readlane_b32 s28, v252, 47
	v_readlane_b32 s27, v252, 46
	v_readlane_b32 s29, v252, 48
	v_lshlrev_b64 v[140:141], 11, v[182:183]
	s_cselect_b32 s27, s27, s29
	s_cselect_b32 s26, s26, s28
	v_readlane_b32 s36, v252, 26
	s_movk_i32 s28, 0xf000
	v_readlane_b32 s37, v252, 27
	v_lshl_add_u64 v[140:141], s[26:27], 0, v[140:141]
	s_mov_b32 s29, s37
	s_cselect_b32 s28, s28, 0xffffe800
	v_lshl_add_u64 v[140:141], v[128:129], 1, v[140:141]
	v_lshl_add_u64 v[140:141], v[140:141], 0, s[28:29]
	v_cvt_pk_bf16_f32 v142, v133, s0
	global_store_short v[140:141], v142, off
	v_cvt_pk_bf16_f32 v142, v131, s0
	s_mov_b32 s27, s37
	global_store_short v[140:141], v142, off offset:2048
	v_add_co_u32_e32 v140, vcc, 0x1000, v140
	v_writelane_b32 v252, s26, 26
	v_cvt_pk_bf16_f32 v142, v137, s0
	v_addc_co_u32_e32 v141, vcc, 0, v141, vcc
	v_writelane_b32 v252, s27, 27
	global_store_short v[140:141], v142, off
	v_cvt_pk_bf16_f32 v142, v136, s0
	s_mov_b64 s[28:29], 0
	global_store_short v[140:141], v142, off offset:2048

.LBB0_1177:
	v_mov_b32_e32 v131, v221
	v_mov_b32_e32 v133, v221
	v_mov_b32_e32 v142, v121
	v_lshlrev_b32_e32 v131, 2, v131
	v_lshlrev_b32_e32 v133, 2, v133
	v_xor_b32_e32 v131, 0x80, v131
	v_xor_b32_e32 v133, 0x80, v133
	ds_bpermute_b32 v131, v131, v123
	ds_bpermute_b32 v137, v133, v124
	v_mov_b32_e32 v143, v122
	v_or_b32_e32 v180, v239, v205
	v_ashrrev_i32_e32 v181, 31, v180
	s_waitcnt lgkmcnt(1)
	v_cndmask_b32_e64 v138, v131, v138, s[4:5]
	s_waitcnt lgkmcnt(0)
	v_cndmask_b32_e64 v141, v137, v139, s[4:5]
	v_mov_b32_e32 v139, v120
	v_pk_fma_f32 v[138:139], v[188:189], v[138:139], v[190:191]
	s_nop 0
	v_pk_fma_f32 v[138:139], v[120:121], v[134:135], v[138:139]
	s_nop 0
	v_pk_fma_f32 v[138:139], v[142:143], v[186:187], v[138:139]
	s_nop 0
	v_mul_f32_e32 v133, 0xbfb8aa3b, v138
	v_exp_f32_e32 v144, v133
	v_mul_f32_e32 v133, 0xbfb8aa3b, v139
	v_exp_f32_e32 v145, v133
	s_nop 0
	v_pk_add_f32 v[144:145], v[144:145], 1.0 op_sel_hi:[1,0]
	s_nop 0
	v_rcp_f32_e32 v136, v145
	s_nop 0
	v_mul_f32_e32 v133, v139, v136
	v_rcp_f32_e32 v139, v144
	s_nop 0
	v_mul_f32_e32 v136, v138, v139
	v_pk_fma_f32 v[138:139], v[142:143], v[188:189], v[190:191]
	v_mov_b32_e32 v140, v123
	v_pk_fma_f32 v[138:139], v[122:123], v[134:135], v[138:139]
	s_nop 0
	v_pk_fma_f32 v[140:141], v[140:141], v[186:187], v[138:139]
	s_nop 0
	v_mul_f32_e32 v138, 0xbfb8aa3b, v140
	v_mul_f32_e32 v139, 0xbfb8aa3b, v141
	v_exp_f32_e32 v138, v138
	v_exp_f32_e32 v139, v139
	s_nop 0
	v_pk_add_f32 v[142:143], v[138:139], 1.0 op_sel_hi:[1,0]
	s_nop 0
	v_rcp_f32_e32 v139, v143
	s_nop 0
	v_mul_f32_e32 v138, v141, v139
	v_rcp_f32_e32 v141, v142
	s_mov_b64 s[26:27], -1
	v_mul_f32_e32 v139, v140, v141
	s_and_b64 vcc, exec, s[0:1]
	s_cbranch_vccnz .LBB0_1179
	s_and_b64 s[26:27], s[24:25], exec
	v_readlane_b32 s26, v252, 45
	v_readlane_b32 s28, v252, 47
	v_readlane_b32 s27, v252, 46
	v_readlane_b32 s29, v252, 48
	v_lshlrev_b64 v[140:141], 11, v[180:181]
	s_cselect_b32 s27, s27, s29
	s_cselect_b32 s26, s26, s28
	v_readlane_b32 s36, v252, 26
	s_movk_i32 s28, 0xf000
	v_readlane_b32 s37, v252, 27
	v_lshl_add_u64 v[140:141], s[26:27], 0, v[140:141]
	s_mov_b32 s29, s37
	s_cselect_b32 s28, s28, 0xffffe800
	v_lshl_add_u64 v[140:141], v[128:129], 1, v[140:141]
	v_lshl_add_u64 v[140:141], v[140:141], 0, s[28:29]
	v_cvt_pk_bf16_f32 v142, v136, s0
	global_store_short v[140:141], v142, off
	v_cvt_pk_bf16_f32 v142, v133, s0
	s_mov_b32 s27, s37
	global_store_short v[140:141], v142, off offset:2048
	v_add_co_u32_e32 v140, vcc, 0x1000, v140
	v_writelane_b32 v252, s26, 26
	v_cvt_pk_bf16_f32 v142, v139, s0
	v_addc_co_u32_e32 v141, vcc, 0, v141, vcc
	v_writelane_b32 v252, s27, 27
	global_store_short v[140:141], v142, off
	v_cvt_pk_bf16_f32 v142, v138, s0
	s_mov_b64 s[26:27], 0
	global_store_short v[140:141], v142, off offset:2048

.LBB0_1181:
	v_mov_b32_e32 v133, v221
	v_mov_b32_e32 v141, v124
	v_lshlrev_b32_e32 v133, 2, v133
	v_xor_b32_e32 v133, 0x80, v133
	ds_bpermute_b32 v136, v133, v127
	v_mov_b32_e32 v144, v125
	v_mov_b32_e32 v145, v126
	v_mov_b32_e32 v133, v221
	s_waitcnt lgkmcnt(0)
	v_cndmask_b32_e64 v140, v136, v131, s[4:5]
	v_pk_fma_f32 v[140:141], v[188:189], v[140:141], v[190:191]
	v_lshlrev_b32_e32 v133, 2, v133
	v_pk_fma_f32 v[140:141], v[124:125], v[134:135], v[140:141]
	v_xor_b32_e32 v133, 0x80, v133
	v_pk_fma_f32 v[140:141], v[144:145], v[186:187], v[140:141]
	ds_bpermute_b32 v138, v133, v80
	v_mul_f32_e32 v131, 0xbfb8aa3b, v140
	v_exp_f32_e32 v146, v131
	v_mul_f32_e32 v131, 0xbfb8aa3b, v141
	v_exp_f32_e32 v147, v131
	s_waitcnt lgkmcnt(0)
	v_cndmask_b32_e64 v143, v138, v137, s[4:5]
	v_or_b32_e32 v176, v239, v206
	v_ashrrev_i32_e32 v177, 31, v176
	v_pk_add_f32 v[146:147], v[146:147], 1.0 op_sel_hi:[1,0]
	s_nop 0
	v_rcp_f32_e32 v133, v147
	s_nop 0
	v_mul_f32_e32 v131, v141, v133
	v_rcp_f32_e32 v137, v146
	s_nop 0
	v_mul_f32_e32 v133, v140, v137
	v_pk_fma_f32 v[140:141], v[144:145], v[188:189], v[190:191]
	v_mov_b32_e32 v142, v127
	v_pk_fma_f32 v[140:141], v[126:127], v[134:135], v[140:141]
	s_nop 0
	v_pk_fma_f32 v[140:141], v[142:143], v[186:187], v[140:141]
	s_nop 0
	v_mul_f32_e32 v137, 0xbfb8aa3b, v140
	v_exp_f32_e32 v142, v137
	v_mul_f32_e32 v137, 0xbfb8aa3b, v141
	v_exp_f32_e32 v143, v137
	s_nop 0
	v_pk_add_f32 v[142:143], v[142:143], 1.0 op_sel_hi:[1,0]
	s_nop 0
	v_rcp_f32_e32 v139, v143
	s_nop 0
	v_mul_f32_e32 v137, v141, v139
	v_rcp_f32_e32 v141, v142
	s_mov_b64 s[26:27], -1
	v_mul_f32_e32 v139, v140, v141
	s_and_b64 vcc, exec, s[0:1]
	s_cbranch_vccnz .LBB0_1183
	s_and_b64 s[26:27], s[24:25], exec
	v_readlane_b32 s26, v252, 45
	v_readlane_b32 s28, v252, 47
	v_readlane_b32 s27, v252, 46
	v_readlane_b32 s29, v252, 48
	v_lshlrev_b64 v[140:141], 11, v[176:177]
	s_cselect_b32 s27, s27, s29
	s_cselect_b32 s26, s26, s28
	v_readlane_b32 s36, v252, 26
	s_movk_i32 s28, 0xf000
	v_readlane_b32 s37, v252, 27
	v_lshl_add_u64 v[140:141], s[26:27], 0, v[140:141]
	s_mov_b32 s29, s37
	s_cselect_b32 s28, s28, 0xffffe800
	v_lshl_add_u64 v[140:141], v[128:129], 1, v[140:141]
	v_lshl_add_u64 v[140:141], v[140:141], 0, s[28:29]
	v_cvt_pk_bf16_f32 v142, v133, s0
	global_store_short v[140:141], v142, off
	v_cvt_pk_bf16_f32 v142, v131, s0
	s_mov_b32 s27, s37
	global_store_short v[140:141], v142, off offset:2048
	v_add_co_u32_e32 v140, vcc, 0x1000, v140
	v_writelane_b32 v252, s26, 26
	v_cvt_pk_bf16_f32 v142, v139, s0
	v_addc_co_u32_e32 v141, vcc, 0, v141, vcc
	v_writelane_b32 v252, s27, 27
	global_store_short v[140:141], v142, off
	v_cvt_pk_bf16_f32 v142, v137, s0
	s_mov_b64 s[26:27], 0
	global_store_short v[140:141], v142, off offset:2048

.LBB0_1185:
	v_mov_b32_e32 v131, v221
	v_mov_b32_e32 v141, v80
	v_lshlrev_b32_e32 v131, 2, v131
	v_xor_b32_e32 v131, 0x80, v131
	ds_bpermute_b32 v137, v131, v83
	v_mov_b32_e32 v131, v221
	v_mov_b32_e32 v144, v81
	v_lshlrev_b32_e32 v131, 2, v131
	s_waitcnt lgkmcnt(0)
	v_cndmask_b32_e64 v140, v137, v136, s[4:5]
	v_pk_fma_f32 v[140:141], v[188:189], v[140:141], v[190:191]
	v_mov_b32_e32 v145, v82
	v_pk_fma_f32 v[140:141], v[80:81], v[134:135], v[140:141]
	v_xor_b32_e32 v131, 0x80, v131
	v_pk_fma_f32 v[140:141], v[144:145], v[186:187], v[140:141]
	ds_bpermute_b32 v139, v131, v84
	v_mul_f32_e32 v131, 0xbfb8aa3b, v140
	v_exp_f32_e32 v146, v131
	v_mul_f32_e32 v131, 0xbfb8aa3b, v141
	v_exp_f32_e32 v147, v131
	s_waitcnt lgkmcnt(0)
	v_cndmask_b32_e64 v143, v139, v138, s[4:5]
	v_or_b32_e32 v174, v239, v207
	v_ashrrev_i32_e32 v175, 31, v174
	v_pk_add_f32 v[146:147], v[146:147], 1.0 op_sel_hi:[1,0]
	s_nop 0
	v_rcp_f32_e32 v133, v147
	s_nop 0
	v_mul_f32_e32 v131, v141, v133
	v_rcp_f32_e32 v136, v146
	s_nop 0
	v_mul_f32_e32 v133, v140, v136
	v_pk_fma_f32 v[140:141], v[144:145], v[188:189], v[190:191]
	v_mov_b32_e32 v142, v83
	v_pk_fma_f32 v[140:141], v[82:83], v[134:135], v[140:141]
	s_nop 0
	v_pk_fma_f32 v[140:141], v[142:143], v[186:187], v[140:141]
	s_nop 0
	v_mul_f32_e32 v136, 0xbfb8aa3b, v140
	v_exp_f32_e32 v142, v136
	v_mul_f32_e32 v136, 0xbfb8aa3b, v141
	v_exp_f32_e32 v143, v136
	s_nop 0
	v_pk_add_f32 v[142:143], v[142:143], 1.0 op_sel_hi:[1,0]
	s_nop 0
	v_rcp_f32_e32 v138, v143
	s_nop 0
	v_mul_f32_e32 v136, v141, v138
	v_rcp_f32_e32 v141, v142
	s_mov_b64 s[26:27], -1
	v_mul_f32_e32 v138, v140, v141
	s_and_b64 vcc, exec, s[0:1]
	s_cbranch_vccnz .LBB0_1187
	s_and_b64 s[26:27], s[24:25], exec
	v_readlane_b32 s26, v252, 45
	v_readlane_b32 s28, v252, 47
	v_readlane_b32 s27, v252, 46
	v_readlane_b32 s29, v252, 48
	v_lshlrev_b64 v[140:141], 11, v[174:175]
	s_cselect_b32 s27, s27, s29
	s_cselect_b32 s26, s26, s28
	v_readlane_b32 s36, v252, 26
	s_movk_i32 s28, 0xf000
	v_readlane_b32 s37, v252, 27
	v_lshl_add_u64 v[140:141], s[26:27], 0, v[140:141]
	s_mov_b32 s29, s37
	s_cselect_b32 s28, s28, 0xffffe800
	v_lshl_add_u64 v[140:141], v[128:129], 1, v[140:141]
	v_lshl_add_u64 v[140:141], v[140:141], 0, s[28:29]
	v_cvt_pk_bf16_f32 v142, v133, s0
	global_store_short v[140:141], v142, off
	v_cvt_pk_bf16_f32 v142, v131, s0
	s_mov_b32 s27, s37
	global_store_short v[140:141], v142, off offset:2048
	v_add_co_u32_e32 v140, vcc, 0x1000, v140
	v_writelane_b32 v252, s26, 26
	v_cvt_pk_bf16_f32 v142, v138, s0
	v_addc_co_u32_e32 v141, vcc, 0, v141, vcc
	v_writelane_b32 v252, s27, 27
	global_store_short v[140:141], v142, off
	v_cvt_pk_bf16_f32 v142, v136, s0
	s_mov_b64 s[26:27], 0
	global_store_short v[140:141], v142, off offset:2048

.LBB0_1189:
	v_mov_b32_e32 v131, v221
	v_mov_b32_e32 v133, v221
	v_lshlrev_b32_e32 v131, 2, v131
	v_xor_b32_e32 v131, 0x80, v131
	ds_bpermute_b32 v131, v131, v87
	v_mov_b32_e32 v142, v85
	v_lshlrev_b32_e32 v133, 2, v133
	v_mov_b32_e32 v143, v86
	s_waitcnt lgkmcnt(0)
	v_cndmask_b32_e64 v136, v131, v137, s[4:5]
	v_mov_b32_e32 v137, v84
	v_pk_fma_f32 v[136:137], v[188:189], v[136:137], v[190:191]
	v_xor_b32_e32 v133, 0x80, v133
	v_pk_fma_f32 v[136:137], v[84:85], v[134:135], v[136:137]
	ds_bpermute_b32 v138, v133, v88
	v_pk_fma_f32 v[136:137], v[142:143], v[186:187], v[136:137]
	v_pk_fma_f32 v[142:143], v[142:143], v[188:189], v[190:191]
	v_mul_f32_e32 v133, 0xbfb8aa3b, v136
	v_exp_f32_e32 v144, v133
	v_mul_f32_e32 v133, 0xbfb8aa3b, v137
	v_exp_f32_e32 v145, v133
	s_waitcnt lgkmcnt(0)
	v_cndmask_b32_e64 v141, v138, v139, s[4:5]
	v_pk_fma_f32 v[142:143], v[86:87], v[134:135], v[142:143]
	v_or_b32_e32 v172, v239, v208
	v_pk_add_f32 v[144:145], v[144:145], 1.0 op_sel_hi:[1,0]
	v_ashrrev_i32_e32 v173, 31, v172
	v_rcp_f32_e32 v139, v145
	s_nop 0
	v_mul_f32_e32 v133, v137, v139
	v_rcp_f32_e32 v139, v144
	s_nop 0
	v_mov_b32_e32 v140, v87
	v_mul_f32_e32 v137, v136, v139
	v_pk_fma_f32 v[140:141], v[140:141], v[186:187], v[142:143]
	v_mov_b32_e32 v136, v137
	v_mul_f32_e32 v137, 0xbfb8aa3b, v140
	v_exp_f32_e32 v142, v137
	v_mul_f32_e32 v137, 0xbfb8aa3b, v141
	v_exp_f32_e32 v143, v137
	s_nop 0
	v_pk_add_f32 v[142:143], v[142:143], 1.0 op_sel_hi:[1,0]
	s_nop 0
	v_rcp_f32_e32 v139, v143
	s_nop 0
	v_mul_f32_e32 v137, v141, v139
	v_rcp_f32_e32 v141, v142
	s_mov_b64 s[26:27], -1
	v_mul_f32_e32 v139, v140, v141
	s_and_b64 vcc, exec, s[0:1]
	s_cbranch_vccnz .LBB0_1191
	s_and_b64 s[26:27], s[24:25], exec
	v_readlane_b32 s26, v252, 45
	v_readlane_b32 s28, v252, 47
	v_readlane_b32 s27, v252, 46
	v_readlane_b32 s29, v252, 48
	v_lshlrev_b64 v[140:141], 11, v[172:173]
	s_cselect_b32 s27, s27, s29
	s_cselect_b32 s26, s26, s28
	v_readlane_b32 s36, v252, 26
	s_movk_i32 s28, 0xf000
	v_readlane_b32 s37, v252, 27
	v_lshl_add_u64 v[140:141], s[26:27], 0, v[140:141]
	s_mov_b32 s29, s37
	s_cselect_b32 s28, s28, 0xffffe800
	v_lshl_add_u64 v[140:141], v[128:129], 1, v[140:141]
	v_lshl_add_u64 v[140:141], v[140:141], 0, s[28:29]
	v_cvt_pk_bf16_f32 v142, v136, s0
	global_store_short v[140:141], v142, off
	v_cvt_pk_bf16_f32 v142, v133, s0
	s_mov_b32 s27, s37
	global_store_short v[140:141], v142, off offset:2048
	v_add_co_u32_e32 v140, vcc, 0x1000, v140
	v_writelane_b32 v252, s26, 26
	v_cvt_pk_bf16_f32 v142, v139, s0
	v_addc_co_u32_e32 v141, vcc, 0, v141, vcc
	v_writelane_b32 v252, s27, 27
	global_store_short v[140:141], v142, off
	v_cvt_pk_bf16_f32 v142, v137, s0
	s_mov_b64 s[26:27], 0
	global_store_short v[140:141], v142, off offset:2048

.LBB0_1193:
	v_mov_b32_e32 v133, v221
	v_mov_b32_e32 v141, v88
	v_lshlrev_b32_e32 v133, 2, v133
	v_xor_b32_e32 v133, 0x80, v133
	ds_bpermute_b32 v136, v133, v91
	v_mov_b32_e32 v142, v89
	v_mov_b32_e32 v143, v90
	v_mov_b32_e32 v133, v221
	s_waitcnt lgkmcnt(0)
	v_cndmask_b32_e64 v140, v136, v131, s[4:5]
	v_pk_fma_f32 v[140:141], v[188:189], v[140:141], v[190:191]
	v_lshlrev_b32_e32 v133, 2, v133
	v_pk_fma_f32 v[140:141], v[88:89], v[134:135], v[140:141]
	v_xor_b32_e32 v133, 0x80, v133
	v_pk_fma_f32 v[140:141], v[142:143], v[186:187], v[140:141]
	ds_bpermute_b32 v137, v133, v92
	v_mul_f32_e32 v131, 0xbfb8aa3b, v140
	v_exp_f32_e32 v144, v131
	v_mul_f32_e32 v131, 0xbfb8aa3b, v141
	v_exp_f32_e32 v145, v131
	s_waitcnt lgkmcnt(0)
	v_cndmask_b32_e64 v139, v137, v138, s[4:5]
	v_or_b32_e32 v152, v239, v209
	v_ashrrev_i32_e32 v153, 31, v152
	v_pk_add_f32 v[144:145], v[144:145], 1.0 op_sel_hi:[1,0]
	s_nop 0
	v_rcp_f32_e32 v133, v145
	s_nop 0
	v_mul_f32_e32 v131, v141, v133
	v_rcp_f32_e32 v138, v144
	s_nop 0
	v_mul_f32_e32 v133, v140, v138
	v_pk_fma_f32 v[140:141], v[142:143], v[188:189], v[190:191]
	v_mov_b32_e32 v138, v91
	v_pk_fma_f32 v[140:141], v[90:91], v[134:135], v[140:141]
	s_nop 0
	v_pk_fma_f32 v[140:141], v[138:139], v[186:187], v[140:141]
	s_nop 0
	v_mul_f32_e32 v138, 0xbfb8aa3b, v140
	v_mul_f32_e32 v139, 0xbfb8aa3b, v141
	v_exp_f32_e32 v138, v138
	v_exp_f32_e32 v139, v139
	s_nop 0
	v_pk_add_f32 v[142:143], v[138:139], 1.0 op_sel_hi:[1,0]
	s_nop 0
	v_rcp_f32_e32 v139, v143
	s_nop 0
	v_mul_f32_e32 v138, v141, v139
	v_rcp_f32_e32 v141, v142
	s_mov_b64 s[26:27], -1
	v_mul_f32_e32 v139, v140, v141
	s_and_b64 vcc, exec, s[0:1]
	s_cbranch_vccnz .LBB0_1195
	s_and_b64 s[26:27], s[24:25], exec
	v_readlane_b32 s26, v252, 45
	v_readlane_b32 s28, v252, 47
	v_readlane_b32 s27, v252, 46
	v_readlane_b32 s29, v252, 48
	v_lshlrev_b64 v[140:141], 11, v[152:153]
	s_cselect_b32 s27, s27, s29
	s_cselect_b32 s26, s26, s28
	v_readlane_b32 s36, v252, 26
	s_movk_i32 s28, 0xf000
	v_readlane_b32 s37, v252, 27
	v_lshl_add_u64 v[140:141], s[26:27], 0, v[140:141]
	s_mov_b32 s29, s37
	s_cselect_b32 s28, s28, 0xffffe800
	v_lshl_add_u64 v[140:141], v[128:129], 1, v[140:141]
	v_lshl_add_u64 v[140:141], v[140:141], 0, s[28:29]
	v_cvt_pk_bf16_f32 v142, v133, s0
	global_store_short v[140:141], v142, off
	v_cvt_pk_bf16_f32 v142, v131, s0
	s_mov_b32 s27, s37
	global_store_short v[140:141], v142, off offset:2048
	v_add_co_u32_e32 v140, vcc, 0x1000, v140
	v_writelane_b32 v252, s26, 26
	v_cvt_pk_bf16_f32 v142, v139, s0
	v_addc_co_u32_e32 v141, vcc, 0, v141, vcc
	v_writelane_b32 v252, s27, 27
	global_store_short v[140:141], v142, off
	v_cvt_pk_bf16_f32 v142, v138, s0
	s_mov_b64 s[26:27], 0
	global_store_short v[140:141], v142, off offset:2048

.LBB0_1197:
	v_mov_b32_e32 v131, v221
	v_mov_b32_e32 v133, v221
	v_mov_b32_e32 v142, v93
	v_lshlrev_b32_e32 v131, 2, v131
	v_lshlrev_b32_e32 v133, 2, v133
	v_xor_b32_e32 v131, 0x80, v131
	v_xor_b32_e32 v133, 0x80, v133
	ds_bpermute_b32 v131, v131, v95
	ds_bpermute_b32 v138, v133, v48
	v_mov_b32_e32 v143, v94
	v_or_b32_e32 v150, v239, v210
	v_ashrrev_i32_e32 v151, 31, v150
	s_waitcnt lgkmcnt(1)
	v_cndmask_b32_e64 v136, v131, v136, s[4:5]
	s_waitcnt lgkmcnt(0)
	v_cndmask_b32_e64 v141, v138, v137, s[4:5]
	v_mov_b32_e32 v137, v92
	v_pk_fma_f32 v[136:137], v[188:189], v[136:137], v[190:191]
	s_nop 0
	v_pk_fma_f32 v[136:137], v[92:93], v[134:135], v[136:137]
	s_nop 0
	v_pk_fma_f32 v[136:137], v[142:143], v[186:187], v[136:137]
	v_pk_fma_f32 v[142:143], v[142:143], v[188:189], v[190:191]
	v_mul_f32_e32 v133, 0xbfb8aa3b, v136
	v_exp_f32_e32 v144, v133
	v_mul_f32_e32 v133, 0xbfb8aa3b, v137
	v_exp_f32_e32 v145, v133
	v_pk_fma_f32 v[142:143], v[94:95], v[134:135], v[142:143]
	v_pk_add_f32 v[144:145], v[144:145], 1.0 op_sel_hi:[1,0]
	s_nop 0
	v_rcp_f32_e32 v139, v145
	s_nop 0
	v_mul_f32_e32 v133, v137, v139
	v_rcp_f32_e32 v139, v144
	s_nop 0
	v_mov_b32_e32 v140, v95
	v_mul_f32_e32 v137, v136, v139
	v_pk_fma_f32 v[140:141], v[140:141], v[186:187], v[142:143]
	v_mov_b32_e32 v136, v137
	v_mul_f32_e32 v137, 0xbfb8aa3b, v140
	v_exp_f32_e32 v142, v137
	v_mul_f32_e32 v137, 0xbfb8aa3b, v141
	v_exp_f32_e32 v143, v137
	s_nop 0
	v_pk_add_f32 v[142:143], v[142:143], 1.0 op_sel_hi:[1,0]
	s_nop 0
	v_rcp_f32_e32 v139, v143
	s_nop 0
	v_mul_f32_e32 v137, v141, v139
	v_rcp_f32_e32 v141, v142
	s_mov_b64 s[26:27], -1
	v_mul_f32_e32 v139, v140, v141
	s_and_b64 vcc, exec, s[0:1]
	s_cbranch_vccnz .LBB0_1199
	s_and_b64 s[26:27], s[24:25], exec
	v_readlane_b32 s26, v252, 45
	v_readlane_b32 s28, v252, 47
	v_readlane_b32 s27, v252, 46
	v_readlane_b32 s29, v252, 48
	v_lshlrev_b64 v[140:141], 11, v[150:151]
	s_cselect_b32 s27, s27, s29
	s_cselect_b32 s26, s26, s28
	v_readlane_b32 s36, v252, 26
	s_movk_i32 s28, 0xf000
	v_readlane_b32 s37, v252, 27
	v_lshl_add_u64 v[140:141], s[26:27], 0, v[140:141]
	s_mov_b32 s29, s37
	s_cselect_b32 s28, s28, 0xffffe800
	v_lshl_add_u64 v[140:141], v[128:129], 1, v[140:141]
	v_lshl_add_u64 v[140:141], v[140:141], 0, s[28:29]
	v_cvt_pk_bf16_f32 v142, v136, s0
	global_store_short v[140:141], v142, off
	v_cvt_pk_bf16_f32 v142, v133, s0
	s_mov_b32 s27, s37
	global_store_short v[140:141], v142, off offset:2048
	v_add_co_u32_e32 v140, vcc, 0x1000, v140
	v_writelane_b32 v252, s26, 26
	v_cvt_pk_bf16_f32 v142, v139, s0
	v_addc_co_u32_e32 v141, vcc, 0, v141, vcc
	v_writelane_b32 v252, s27, 27
	global_store_short v[140:141], v142, off
	v_cvt_pk_bf16_f32 v142, v137, s0
	s_mov_b64 s[26:27], 0
	global_store_short v[140:141], v142, off offset:2048

.LBB0_1201:
	v_mov_b32_e32 v133, v221
	v_mov_b32_e32 v141, v48
	v_lshlrev_b32_e32 v133, 2, v133
	v_xor_b32_e32 v133, 0x80, v133
	ds_bpermute_b32 v136, v133, v51
	v_mov_b32_e32 v144, v49
	v_mov_b32_e32 v145, v50
	v_mov_b32_e32 v133, v221
	s_waitcnt lgkmcnt(0)
	v_cndmask_b32_e64 v140, v136, v131, s[4:5]
	v_pk_fma_f32 v[140:141], v[188:189], v[140:141], v[190:191]
	v_lshlrev_b32_e32 v133, 2, v133
	v_pk_fma_f32 v[140:141], v[48:49], v[134:135], v[140:141]
	v_xor_b32_e32 v133, 0x80, v133
	v_pk_fma_f32 v[140:141], v[144:145], v[186:187], v[140:141]
	ds_bpermute_b32 v139, v133, v52
	v_mul_f32_e32 v131, 0xbfb8aa3b, v140
	v_exp_f32_e32 v146, v131
	v_mul_f32_e32 v131, 0xbfb8aa3b, v141
	v_exp_f32_e32 v147, v131
	s_waitcnt lgkmcnt(0)
	v_cndmask_b32_e64 v143, v139, v138, s[4:5]
	v_or_b32_e32 v148, v239, v211
	v_ashrrev_i32_e32 v149, 31, v148
	v_pk_add_f32 v[146:147], v[146:147], 1.0 op_sel_hi:[1,0]
	s_nop 0
	v_rcp_f32_e32 v133, v147
	s_nop 0
	v_mul_f32_e32 v131, v141, v133
	v_rcp_f32_e32 v137, v146
	s_nop 0
	v_mul_f32_e32 v133, v140, v137
	v_pk_fma_f32 v[140:141], v[144:145], v[188:189], v[190:191]
	v_mov_b32_e32 v142, v51
	v_pk_fma_f32 v[140:141], v[50:51], v[134:135], v[140:141]
	s_nop 0
	v_pk_fma_f32 v[140:141], v[142:143], v[186:187], v[140:141]
	s_nop 0
	v_mul_f32_e32 v137, 0xbfb8aa3b, v140
	v_exp_f32_e32 v142, v137
	v_mul_f32_e32 v137, 0xbfb8aa3b, v141
	v_exp_f32_e32 v143, v137
	s_nop 0
	v_pk_add_f32 v[142:143], v[142:143], 1.0 op_sel_hi:[1,0]
	s_nop 0
	v_rcp_f32_e32 v138, v143
	s_nop 0
	v_mul_f32_e32 v137, v141, v138
	v_rcp_f32_e32 v141, v142
	s_mov_b64 s[26:27], -1
	v_mul_f32_e32 v138, v140, v141
	s_and_b64 vcc, exec, s[0:1]
	s_cbranch_vccnz .LBB0_1203
	s_and_b64 s[26:27], s[24:25], exec
	v_readlane_b32 s26, v252, 45
	v_readlane_b32 s28, v252, 47
	v_readlane_b32 s27, v252, 46
	v_readlane_b32 s29, v252, 48
	v_lshlrev_b64 v[140:141], 11, v[148:149]
	s_cselect_b32 s27, s27, s29
	s_cselect_b32 s26, s26, s28
	v_readlane_b32 s36, v252, 26
	s_movk_i32 s28, 0xf000
	v_readlane_b32 s37, v252, 27
	v_lshl_add_u64 v[140:141], s[26:27], 0, v[140:141]
	s_mov_b32 s29, s37
	s_cselect_b32 s28, s28, 0xffffe800
	v_lshl_add_u64 v[140:141], v[128:129], 1, v[140:141]
	v_lshl_add_u64 v[140:141], v[140:141], 0, s[28:29]
	v_cvt_pk_bf16_f32 v142, v133, s0
	global_store_short v[140:141], v142, off
	v_cvt_pk_bf16_f32 v142, v131, s0
	s_mov_b32 s27, s37
	global_store_short v[140:141], v142, off offset:2048
	v_add_co_u32_e32 v140, vcc, 0x1000, v140
	v_writelane_b32 v252, s26, 26
	v_cvt_pk_bf16_f32 v142, v138, s0
	v_addc_co_u32_e32 v141, vcc, 0, v141, vcc
	v_writelane_b32 v252, s27, 27
	global_store_short v[140:141], v142, off
	v_cvt_pk_bf16_f32 v142, v137, s0
	s_mov_b64 s[26:27], 0
	global_store_short v[140:141], v142, off offset:2048

.LBB0_1205:
	v_mov_b32_e32 v131, v221
	v_mov_b32_e32 v133, v221
	v_mov_b32_e32 v142, v53
	v_lshlrev_b32_e32 v131, 2, v131
	v_lshlrev_b32_e32 v133, 2, v133
	v_xor_b32_e32 v131, 0x80, v131
	v_xor_b32_e32 v133, 0x80, v133
	ds_bpermute_b32 v131, v131, v55
	ds_bpermute_b32 v137, v133, v56
	v_mov_b32_e32 v143, v54
	s_waitcnt lgkmcnt(1)
	v_cndmask_b32_e64 v138, v131, v136, s[4:5]
	s_waitcnt lgkmcnt(0)
	v_cndmask_b32_e64 v141, v137, v139, s[4:5]
	v_mov_b32_e32 v139, v52
	v_pk_fma_f32 v[138:139], v[188:189], v[138:139], v[190:191]
	s_nop 0
	v_pk_fma_f32 v[138:139], v[52:53], v[134:135], v[138:139]
	s_nop 0
	v_pk_fma_f32 v[138:139], v[142:143], v[186:187], v[138:139]
	s_nop 0
	v_mul_f32_e32 v133, 0xbfb8aa3b, v138
	v_exp_f32_e32 v144, v133
	v_mul_f32_e32 v133, 0xbfb8aa3b, v139
	v_exp_f32_e32 v145, v133
	s_nop 0
	v_pk_add_f32 v[144:145], v[144:145], 1.0 op_sel_hi:[1,0]
	s_nop 0
	v_rcp_f32_e32 v136, v145
	s_nop 0
	v_mul_f32_e32 v133, v139, v136
	v_rcp_f32_e32 v139, v144
	s_nop 0
	v_mul_f32_e32 v136, v138, v139
	v_pk_fma_f32 v[138:139], v[142:143], v[188:189], v[190:191]
	v_mov_b32_e32 v140, v55
	v_pk_fma_f32 v[138:139], v[54:55], v[134:135], v[138:139]
	s_nop 0
	v_pk_fma_f32 v[140:141], v[140:141], v[186:187], v[138:139]
	s_nop 0
	v_mul_f32_e32 v138, 0xbfb8aa3b, v140
	v_mul_f32_e32 v139, 0xbfb8aa3b, v141
	v_exp_f32_e32 v138, v138
	v_exp_f32_e32 v139, v139
	s_nop 0
	v_pk_add_f32 v[142:143], v[138:139], 1.0 op_sel_hi:[1,0]
	s_nop 0
	v_rcp_f32_e32 v139, v143
	s_nop 0
	v_mul_f32_e32 v138, v141, v139
	v_rcp_f32_e32 v141, v142
	v_or_b32_e32 v146, v239, v212
	s_mov_b64 s[26:27], -1
	v_ashrrev_i32_e32 v147, 31, v146
	v_mul_f32_e32 v139, v140, v141
	s_and_b64 vcc, exec, s[0:1]
	s_cbranch_vccnz .LBB0_1207
	s_and_b64 s[26:27], s[24:25], exec
	v_readlane_b32 s26, v252, 45
	v_readlane_b32 s28, v252, 47
	v_readlane_b32 s27, v252, 46
	v_readlane_b32 s29, v252, 48
	v_lshlrev_b64 v[140:141], 11, v[146:147]
	s_cselect_b32 s27, s27, s29
	s_cselect_b32 s26, s26, s28
	v_readlane_b32 s36, v252, 26
	s_movk_i32 s28, 0xf000
	v_readlane_b32 s37, v252, 27
	v_lshl_add_u64 v[140:141], s[26:27], 0, v[140:141]
	s_mov_b32 s29, s37
	s_cselect_b32 s28, s28, 0xffffe800
	v_lshl_add_u64 v[140:141], v[128:129], 1, v[140:141]
	v_lshl_add_u64 v[140:141], v[140:141], 0, s[28:29]
	v_cvt_pk_bf16_f32 v142, v136, s0
	global_store_short v[140:141], v142, off
	v_cvt_pk_bf16_f32 v142, v133, s0
	s_mov_b32 s27, s37
	global_store_short v[140:141], v142, off offset:2048
	v_add_co_u32_e32 v140, vcc, 0x1000, v140
	v_writelane_b32 v252, s26, 26
	v_cvt_pk_bf16_f32 v142, v139, s0
	v_addc_co_u32_e32 v141, vcc, 0, v141, vcc
	v_writelane_b32 v252, s27, 27
	global_store_short v[140:141], v142, off
	v_cvt_pk_bf16_f32 v142, v138, s0
	s_mov_b64 s[26:27], 0
	global_store_short v[140:141], v142, off offset:2048

.LBB0_1209:
	v_mov_b32_e32 v133, v221
	v_mov_b32_e32 v141, v56
	v_lshlrev_b32_e32 v133, 2, v133
	v_xor_b32_e32 v133, 0x80, v133
	ds_bpermute_b32 v136, v133, v59
	v_mov_b32_e32 v144, v57
	v_mov_b32_e32 v145, v58
	v_mov_b32_e32 v133, v221
	s_waitcnt lgkmcnt(0)
	v_cndmask_b32_e64 v140, v136, v131, s[4:5]
	v_pk_fma_f32 v[140:141], v[188:189], v[140:141], v[190:191]
	v_lshlrev_b32_e32 v133, 2, v133
	v_pk_fma_f32 v[140:141], v[56:57], v[134:135], v[140:141]
	v_xor_b32_e32 v133, 0x80, v133
	v_pk_fma_f32 v[140:141], v[144:145], v[186:187], v[140:141]
	ds_bpermute_b32 v138, v133, v60
	v_mul_f32_e32 v131, 0xbfb8aa3b, v140
	v_exp_f32_e32 v194, v131
	v_mul_f32_e32 v131, 0xbfb8aa3b, v141
	v_exp_f32_e32 v195, v131
	s_waitcnt lgkmcnt(0)
	v_cndmask_b32_e64 v143, v138, v137, s[4:5]
	v_pk_add_f32 v[194:195], v[194:195], 1.0 op_sel_hi:[1,0]
	s_nop 0
	v_rcp_f32_e32 v133, v195
	s_nop 0
	v_mul_f32_e32 v131, v141, v133
	v_rcp_f32_e32 v137, v194
	s_nop 0
	v_mul_f32_e32 v133, v140, v137
	v_pk_fma_f32 v[140:141], v[144:145], v[188:189], v[190:191]
	v_mov_b32_e32 v142, v59
	v_pk_fma_f32 v[140:141], v[58:59], v[134:135], v[140:141]
	s_nop 0
	v_pk_fma_f32 v[140:141], v[142:143], v[186:187], v[140:141]
	s_nop 0
	v_mul_f32_e32 v137, 0xbfb8aa3b, v140
	v_exp_f32_e32 v142, v137
	v_mul_f32_e32 v137, 0xbfb8aa3b, v141
	v_exp_f32_e32 v143, v137
	s_nop 0
	v_pk_add_f32 v[142:143], v[142:143], 1.0 op_sel_hi:[1,0]
	s_nop 0
	v_rcp_f32_e32 v139, v143
	s_nop 0
	v_mul_f32_e32 v137, v141, v139
	v_rcp_f32_e32 v141, v142
	s_mov_b64 s[26:27], -1
	v_mul_f32_e32 v139, v140, v141
	v_or_b32_e32 v144, v239, v213
	s_and_b64 vcc, exec, s[0:1]
	v_ashrrev_i32_e32 v145, 31, v144
	s_cbranch_vccnz .LBB0_1211
	s_and_b64 s[26:27], s[24:25], exec
	v_readlane_b32 s26, v252, 45
	v_readlane_b32 s28, v252, 47
	v_readlane_b32 s27, v252, 46
	v_readlane_b32 s29, v252, 48
	v_lshlrev_b64 v[140:141], 11, v[144:145]
	s_cselect_b32 s27, s27, s29
	s_cselect_b32 s26, s26, s28
	v_readlane_b32 s36, v252, 26
	s_movk_i32 s28, 0xf000
	v_readlane_b32 s37, v252, 27
	v_lshl_add_u64 v[140:141], s[26:27], 0, v[140:141]
	s_mov_b32 s29, s37
	s_cselect_b32 s28, s28, 0xffffe800
	v_lshl_add_u64 v[140:141], v[128:129], 1, v[140:141]
	v_lshl_add_u64 v[140:141], v[140:141], 0, s[28:29]
	v_cvt_pk_bf16_f32 v142, v133, s0
	global_store_short v[140:141], v142, off
	v_cvt_pk_bf16_f32 v142, v131, s0
	s_mov_b32 s27, s37
	global_store_short v[140:141], v142, off offset:2048
	v_add_co_u32_e32 v140, vcc, 0x1000, v140
	v_writelane_b32 v252, s26, 26
	v_cvt_pk_bf16_f32 v142, v139, s0
	v_addc_co_u32_e32 v141, vcc, 0, v141, vcc
	v_writelane_b32 v252, s27, 27
	global_store_short v[140:141], v142, off
	v_cvt_pk_bf16_f32 v142, v137, s0
	s_mov_b64 s[26:27], 0
	global_store_short v[140:141], v142, off offset:2048

.LBB0_1213:
	v_mov_b32_e32 v131, v221
	v_mov_b32_e32 v133, v221
	v_lshlrev_b32_e32 v131, 2, v131
	v_xor_b32_e32 v131, 0x80, v131
	ds_bpermute_b32 v131, v131, v63
	v_mov_b32_e32 v141, v60
	v_mov_b32_e32 v142, v61
	v_lshlrev_b32_e32 v133, 2, v133
	s_waitcnt lgkmcnt(0)
	v_cndmask_b32_e64 v140, v131, v136, s[4:5]
	v_pk_fma_f32 v[140:141], v[188:189], v[140:141], v[190:191]
	v_mov_b32_e32 v143, v62
	v_pk_fma_f32 v[140:141], v[60:61], v[134:135], v[140:141]
	v_xor_b32_e32 v133, 0x80, v133
	v_pk_fma_f32 v[140:141], v[142:143], v[186:187], v[140:141]
	ds_bpermute_b32 v137, v133, v16
	v_mul_f32_e32 v133, 0xbfb8aa3b, v140
	v_exp_f32_e32 v194, v133
	v_mul_f32_e32 v133, 0xbfb8aa3b, v141
	v_exp_f32_e32 v195, v133
	s_waitcnt lgkmcnt(0)
	v_cndmask_b32_e64 v139, v137, v138, s[4:5]
	v_pk_add_f32 v[194:195], v[194:195], 1.0 op_sel_hi:[1,0]
	s_nop 0
	v_rcp_f32_e32 v136, v195
	s_nop 0
	v_mul_f32_e32 v133, v141, v136
	v_rcp_f32_e32 v138, v194
	s_nop 0
	v_mul_f32_e32 v136, v140, v138
	v_pk_fma_f32 v[140:141], v[142:143], v[188:189], v[190:191]
	v_mov_b32_e32 v138, v63
	v_pk_fma_f32 v[140:141], v[62:63], v[134:135], v[140:141]
	s_nop 0
	v_pk_fma_f32 v[140:141], v[138:139], v[186:187], v[140:141]
	s_nop 0
	v_mul_f32_e32 v138, 0xbfb8aa3b, v140
	v_mul_f32_e32 v139, 0xbfb8aa3b, v141
	v_exp_f32_e32 v138, v138
	v_exp_f32_e32 v139, v139
	s_nop 0
	v_pk_add_f32 v[142:143], v[138:139], 1.0 op_sel_hi:[1,0]
	s_nop 0
	v_rcp_f32_e32 v139, v143
	s_nop 0
	v_mul_f32_e32 v138, v141, v139
	v_rcp_f32_e32 v141, v142
	s_mov_b64 s[26:27], -1
	v_mul_f32_e32 v139, v140, v141
	v_or_b32_e32 v142, v239, v214
	s_and_b64 vcc, exec, s[0:1]
	v_ashrrev_i32_e32 v143, 31, v142
	s_cbranch_vccnz .LBB0_1215
	s_and_b64 s[26:27], s[24:25], exec
	v_readlane_b32 s26, v252, 45
	v_readlane_b32 s28, v252, 47
	v_readlane_b32 s27, v252, 46
	v_readlane_b32 s29, v252, 48
	v_lshlrev_b64 v[140:141], 11, v[142:143]
	s_cselect_b32 s27, s27, s29
	s_cselect_b32 s26, s26, s28
	v_readlane_b32 s36, v252, 26
	s_movk_i32 s28, 0xf000
	v_readlane_b32 s37, v252, 27
	v_lshl_add_u64 v[140:141], s[26:27], 0, v[140:141]
	s_mov_b32 s29, s37
	s_cselect_b32 s28, s28, 0xffffe800
	v_lshl_add_u64 v[140:141], v[128:129], 1, v[140:141]
	v_lshl_add_u64 v[140:141], v[140:141], 0, s[28:29]
	v_cvt_pk_bf16_f32 v194, v136, s0
	global_store_short v[140:141], v194, off
	v_cvt_pk_bf16_f32 v194, v133, s0
	s_mov_b32 s27, s37
	global_store_short v[140:141], v194, off offset:2048
	v_add_co_u32_e32 v140, vcc, 0x1000, v140
	v_writelane_b32 v252, s26, 26
	v_cvt_pk_bf16_f32 v194, v139, s0
	v_addc_co_u32_e32 v141, vcc, 0, v141, vcc
	v_writelane_b32 v252, s27, 27
	global_store_short v[140:141], v194, off
	v_cvt_pk_bf16_f32 v194, v138, s0
	s_mov_b64 s[26:27], 0
	global_store_short v[140:141], v194, off offset:2048

.LBB0_1217:
	v_mov_b32_e32 v133, v221
	v_mov_b32_e32 v141, v16
	v_lshlrev_b32_e32 v133, 2, v133
	v_xor_b32_e32 v133, 0x80, v133
	ds_bpermute_b32 v136, v133, v19
	v_mov_b32_e32 v224, v17
	v_mov_b32_e32 v225, v18
	v_mov_b32_e32 v133, v221
	s_waitcnt lgkmcnt(0)
	v_cndmask_b32_e64 v140, v136, v131, s[4:5]
	v_pk_fma_f32 v[140:141], v[188:189], v[140:141], v[190:191]
	v_lshlrev_b32_e32 v133, 2, v133
	v_pk_fma_f32 v[140:141], v[16:17], v[134:135], v[140:141]
	v_xor_b32_e32 v133, 0x80, v133
	v_pk_fma_f32 v[140:141], v[224:225], v[186:187], v[140:141]
	ds_bpermute_b32 v138, v133, v20
	v_mul_f32_e32 v131, 0xbfb8aa3b, v140
	v_exp_f32_e32 v226, v131
	v_mul_f32_e32 v131, 0xbfb8aa3b, v141
	v_exp_f32_e32 v227, v131
	s_waitcnt lgkmcnt(0)
	v_cndmask_b32_e64 v195, v138, v137, s[4:5]
	v_pk_add_f32 v[226:227], v[226:227], 1.0 op_sel_hi:[1,0]
	s_nop 0
	v_rcp_f32_e32 v133, v227
	s_nop 0
	v_mul_f32_e32 v131, v141, v133
	v_rcp_f32_e32 v137, v226
	s_nop 0
	v_mul_f32_e32 v133, v140, v137
	v_pk_fma_f32 v[140:141], v[224:225], v[188:189], v[190:191]
	v_mov_b32_e32 v194, v19
	v_pk_fma_f32 v[140:141], v[18:19], v[134:135], v[140:141]
	s_nop 0
	v_pk_fma_f32 v[140:141], v[194:195], v[186:187], v[140:141]
	s_nop 0
	v_mul_f32_e32 v137, 0xbfb8aa3b, v140
	v_exp_f32_e32 v194, v137
	v_mul_f32_e32 v137, 0xbfb8aa3b, v141
	v_exp_f32_e32 v195, v137
	s_nop 0
	v_pk_add_f32 v[194:195], v[194:195], 1.0 op_sel_hi:[1,0]
	s_nop 0
	v_rcp_f32_e32 v139, v195
	s_nop 0
	v_mul_f32_e32 v137, v141, v139
	v_rcp_f32_e32 v141, v194
	s_mov_b64 s[26:27], -1
	v_mul_f32_e32 v139, v140, v141
	v_or_b32_e32 v140, v239, v215
	s_and_b64 vcc, exec, s[0:1]
	v_ashrrev_i32_e32 v141, 31, v140
	s_cbranch_vccnz .LBB0_1219
	s_and_b64 s[26:27], s[24:25], exec
	v_readlane_b32 s26, v252, 45
	v_readlane_b32 s28, v252, 47
	v_readlane_b32 s27, v252, 46
	v_readlane_b32 s29, v252, 48
	v_lshlrev_b64 v[194:195], 11, v[140:141]
	s_cselect_b32 s27, s27, s29
	s_cselect_b32 s26, s26, s28
	v_readlane_b32 s36, v252, 26
	s_movk_i32 s28, 0xf000
	v_readlane_b32 s37, v252, 27
	v_lshl_add_u64 v[194:195], s[26:27], 0, v[194:195]
	s_mov_b32 s29, s37
	s_cselect_b32 s28, s28, 0xffffe800
	v_lshl_add_u64 v[194:195], v[128:129], 1, v[194:195]
	v_lshl_add_u64 v[194:195], v[194:195], 0, s[28:29]
	v_cvt_pk_bf16_f32 v222, v133, s0
	global_store_short v[194:195], v222, off
	v_cvt_pk_bf16_f32 v222, v131, s0
	s_mov_b32 s27, s37
	global_store_short v[194:195], v222, off offset:2048
	v_add_co_u32_e32 v194, vcc, 0x1000, v194
	v_writelane_b32 v252, s26, 26
	v_cvt_pk_bf16_f32 v222, v139, s0
	v_addc_co_u32_e32 v195, vcc, 0, v195, vcc
	v_writelane_b32 v252, s27, 27
	global_store_short v[194:195], v222, off
	v_cvt_pk_bf16_f32 v222, v137, s0
	s_mov_b64 s[26:27], 0
	global_store_short v[194:195], v222, off offset:2048

.LBB0_1221:
	v_mov_b32_e32 v131, v221
	v_mov_b32_e32 v133, v221
	v_lshlrev_b32_e32 v131, 2, v131
	v_xor_b32_e32 v131, 0x80, v131
	ds_bpermute_b32 v131, v131, v23
	v_mov_b32_e32 v195, v20
	v_mov_b32_e32 v224, v21
	v_lshlrev_b32_e32 v133, 2, v133
	s_waitcnt lgkmcnt(0)
	v_cndmask_b32_e64 v194, v131, v136, s[4:5]
	v_pk_fma_f32 v[194:195], v[188:189], v[194:195], v[190:191]
	v_mov_b32_e32 v225, v22
	v_pk_fma_f32 v[194:195], v[20:21], v[134:135], v[194:195]
	v_xor_b32_e32 v133, 0x80, v133
	v_pk_fma_f32 v[194:195], v[224:225], v[186:187], v[194:195]
	ds_bpermute_b32 v137, v133, v24
	v_mul_f32_e32 v133, 0xbfb8aa3b, v194
	v_exp_f32_e32 v226, v133
	v_mul_f32_e32 v133, 0xbfb8aa3b, v195
	v_exp_f32_e32 v227, v133
	s_waitcnt lgkmcnt(0)
	v_cndmask_b32_e64 v139, v137, v138, s[4:5]
	v_pk_add_f32 v[226:227], v[226:227], 1.0 op_sel_hi:[1,0]
	s_nop 0
	v_rcp_f32_e32 v136, v227
	s_nop 0
	v_mul_f32_e32 v133, v195, v136
	v_rcp_f32_e32 v138, v226
	s_nop 0
	v_mul_f32_e32 v136, v194, v138
	v_pk_fma_f32 v[194:195], v[224:225], v[188:189], v[190:191]
	v_mov_b32_e32 v138, v23
	v_pk_fma_f32 v[194:195], v[22:23], v[134:135], v[194:195]
	s_nop 0
	v_pk_fma_f32 v[138:139], v[138:139], v[186:187], v[194:195]
	s_nop 0
	v_mul_f32_e32 v194, 0xbfb8aa3b, v138
	v_mul_f32_e32 v195, 0xbfb8aa3b, v139
	v_exp_f32_e32 v194, v194
	v_exp_f32_e32 v195, v195
	s_nop 0
	v_pk_add_f32 v[224:225], v[194:195], 1.0 op_sel_hi:[1,0]
	s_nop 0
	v_rcp_f32_e32 v195, v225
	s_nop 0
	v_mul_f32_e32 v194, v139, v195
	v_rcp_f32_e32 v195, v224
	s_mov_b64 s[26:27], -1
	v_mul_f32_e32 v139, v138, v195
	v_mov_b32_e32 v195, v139
	v_or_b32_e32 v138, v239, v216
	s_and_b64 vcc, exec, s[0:1]
	v_ashrrev_i32_e32 v139, 31, v138
	s_cbranch_vccnz .LBB0_1223
	s_and_b64 s[26:27], s[24:25], exec
	v_readlane_b32 s26, v252, 45
	v_readlane_b32 s28, v252, 47
	v_readlane_b32 s27, v252, 46
	v_readlane_b32 s29, v252, 48
	v_lshlrev_b64 v[224:225], 11, v[138:139]
	s_cselect_b32 s27, s27, s29
	s_cselect_b32 s26, s26, s28
	v_readlane_b32 s36, v252, 26
	s_movk_i32 s28, 0xf000
	v_readlane_b32 s37, v252, 27
	v_lshl_add_u64 v[224:225], s[26:27], 0, v[224:225]
	s_mov_b32 s29, s37
	s_cselect_b32 s28, s28, 0xffffe800
	v_lshl_add_u64 v[224:225], v[128:129], 1, v[224:225]
	v_lshl_add_u64 v[224:225], v[224:225], 0, s[28:29]
	v_cvt_pk_bf16_f32 v222, v136, s0
	global_store_short v[224:225], v222, off
	v_cvt_pk_bf16_f32 v222, v133, s0
	s_mov_b32 s27, s37
	global_store_short v[224:225], v222, off offset:2048
	v_add_co_u32_e32 v224, vcc, 0x1000, v224
	v_writelane_b32 v252, s26, 26
	v_cvt_pk_bf16_f32 v222, v195, s0
	v_addc_co_u32_e32 v225, vcc, 0, v225, vcc
	v_writelane_b32 v252, s27, 27
	global_store_short v[224:225], v222, off
	v_cvt_pk_bf16_f32 v222, v194, s0
	s_mov_b64 s[26:27], 0
	global_store_short v[224:225], v222, off offset:2048

.LBB0_1225:
	v_mov_b32_e32 v133, v221
	v_mov_b32_e32 v226, v25
	v_lshlrev_b32_e32 v133, 2, v133
	v_xor_b32_e32 v133, 0x80, v133
	ds_bpermute_b32 v194, v133, v27
	v_mov_b32_e32 v133, v221
	v_mov_b32_e32 v227, v26
	v_lshlrev_b32_e32 v133, 2, v133
	v_xor_b32_e32 v133, 0x80, v133
	ds_bpermute_b32 v195, v133, v28
	s_waitcnt lgkmcnt(1)
	v_cndmask_b32_e64 v136, v194, v131, s[4:5]
	s_waitcnt lgkmcnt(0)
	v_cndmask_b32_e64 v225, v195, v137, s[4:5]
	v_mov_b32_e32 v137, v24
	v_pk_fma_f32 v[136:137], v[188:189], v[136:137], v[190:191]
	s_nop 0
	v_pk_fma_f32 v[136:137], v[24:25], v[134:135], v[136:137]
	s_nop 0
	v_pk_fma_f32 v[136:137], v[226:227], v[186:187], v[136:137]
	s_nop 0
	v_mul_f32_e32 v131, 0xbfb8aa3b, v136
	v_exp_f32_e32 v240, v131
	v_mul_f32_e32 v131, 0xbfb8aa3b, v137
	v_exp_f32_e32 v241, v131
	s_nop 0
	v_pk_add_f32 v[240:241], v[240:241], 1.0 op_sel_hi:[1,0]
	s_nop 0
	v_rcp_f32_e32 v133, v241
	s_nop 0
	v_mul_f32_e32 v131, v137, v133
	v_rcp_f32_e32 v137, v240
	s_nop 0
	v_mul_f32_e32 v133, v136, v137
	v_pk_fma_f32 v[136:137], v[226:227], v[188:189], v[190:191]
	v_mov_b32_e32 v224, v27
	v_pk_fma_f32 v[136:137], v[26:27], v[134:135], v[136:137]
	s_nop 0
	v_pk_fma_f32 v[136:137], v[224:225], v[186:187], v[136:137]
	s_nop 0
	v_mul_f32_e32 v222, 0xbfb8aa3b, v136
	v_exp_f32_e32 v224, v222
	v_mul_f32_e32 v222, 0xbfb8aa3b, v137
	v_exp_f32_e32 v225, v222
	s_nop 0
	v_pk_add_f32 v[224:225], v[224:225], 1.0 op_sel_hi:[1,0]
	s_nop 0
	v_rcp_f32_e32 v223, v225
	s_nop 0
	v_mul_f32_e32 v222, v137, v223
	v_mov_b32_e32 v240, v222
	v_rcp_f32_e32 v222, v224
	s_mov_b64 s[26:27], -1
	v_mul_f32_e32 v137, v136, v222
	v_mov_b32_e32 v241, v137
	v_or_b32_e32 v136, v239, v217
	s_and_b64 vcc, exec, s[0:1]
	v_ashrrev_i32_e32 v137, 31, v136
	s_cbranch_vccnz .LBB0_1227
	s_and_b64 s[26:27], s[24:25], exec
	v_readlane_b32 s26, v252, 45
	v_readlane_b32 s28, v252, 47
	v_readlane_b32 s27, v252, 46
	v_readlane_b32 s29, v252, 48
	v_lshlrev_b64 v[224:225], 11, v[136:137]
	s_cselect_b32 s27, s27, s29
	s_cselect_b32 s26, s26, s28
	v_readlane_b32 s36, v252, 26
	s_movk_i32 s28, 0xf000
	v_readlane_b32 s37, v252, 27
	v_lshl_add_u64 v[224:225], s[26:27], 0, v[224:225]
	s_mov_b32 s29, s37
	s_cselect_b32 s28, s28, 0xffffe800
	v_lshl_add_u64 v[224:225], v[128:129], 1, v[224:225]
	v_lshl_add_u64 v[224:225], v[224:225], 0, s[28:29]
	v_cvt_pk_bf16_f32 v222, v133, s0
	global_store_short v[224:225], v222, off
	v_cvt_pk_bf16_f32 v222, v131, s0
	s_mov_b32 s27, s37
	global_store_short v[224:225], v222, off offset:2048
	v_add_co_u32_e32 v224, vcc, 0x1000, v224
	v_writelane_b32 v252, s26, 26
	v_cvt_pk_bf16_f32 v222, v241, s0
	v_addc_co_u32_e32 v225, vcc, 0, v225, vcc
	v_writelane_b32 v252, s27, 27
	global_store_short v[224:225], v222, off
	v_cvt_pk_bf16_f32 v222, v240, s0
	s_mov_b64 s[26:27], 0
	global_store_short v[224:225], v222, off offset:2048

.LBB0_1229:
	v_mov_b32_e32 v131, v221
	v_cndmask_b32_e64 v225, 0, v195, s[4:5]
	v_lshlrev_b32_e32 v131, 2, v131
	v_xor_b32_e32 v131, 0x80, v131
	ds_bpermute_b32 v131, v131, v31
	v_mov_b32_e32 v195, v28
	v_mov_b32_e32 v226, v29
	v_mov_b32_e32 v227, v30
	s_waitcnt lgkmcnt(0)
	v_cndmask_b32_e64 v194, v131, v194, s[4:5]
	v_pk_fma_f32 v[194:195], v[188:189], v[194:195], v[190:191]
	v_pk_fma_f32 v[188:189], v[226:227], v[188:189], v[190:191]
	v_pk_fma_f32 v[194:195], v[28:29], v[134:135], v[194:195]
	v_pk_fma_f32 v[134:135], v[30:31], v[134:135], v[188:189]
	v_pk_fma_f32 v[194:195], v[226:227], v[186:187], v[194:195]
	s_nop 0
	v_mul_f32_e32 v131, 0xbfb8aa3b, v194
	v_exp_f32_e32 v240, v131
	v_mul_f32_e32 v131, 0xbfb8aa3b, v195
	v_exp_f32_e32 v241, v131
	s_nop 0
	v_pk_add_f32 v[240:241], v[240:241], 1.0 op_sel_hi:[1,0]
	s_nop 0
	v_rcp_f32_e32 v133, v241
	s_nop 0
	v_mul_f32_e32 v131, v195, v133
	v_rcp_f32_e32 v195, v240
	s_nop 0
	v_mov_b32_e32 v224, v31
	v_pk_fma_f32 v[134:135], v[224:225], v[186:187], v[134:135]
	v_mul_f32_e32 v186, 0xbfb8aa3b, v134
	v_mul_f32_e32 v187, 0xbfb8aa3b, v135
	v_exp_f32_e32 v186, v186
	v_exp_f32_e32 v187, v187
	v_mul_f32_e32 v133, v194, v195
	v_pk_add_f32 v[188:189], v[186:187], 1.0 op_sel_hi:[1,0]
	s_nop 0
	v_rcp_f32_e32 v187, v189
	s_nop 0
	v_mul_f32_e32 v186, v135, v187
	v_rcp_f32_e32 v187, v188
	s_mov_b64 s[26:27], -1
	v_mul_f32_e32 v135, v134, v187
	v_mov_b32_e32 v187, v135
	v_or_b32_e32 v134, v239, v233
	s_and_b64 vcc, exec, s[0:1]
	v_ashrrev_i32_e32 v135, 31, v134
	s_cbranch_vccnz .LBB0_1231
	s_and_b64 s[26:27], s[24:25], exec
	v_readlane_b32 s26, v252, 45
	v_readlane_b32 s28, v252, 47
	v_readlane_b32 s27, v252, 46
	v_readlane_b32 s29, v252, 48
	v_lshlrev_b64 v[188:189], 11, v[134:135]
	s_cselect_b32 s27, s27, s29
	s_cselect_b32 s26, s26, s28
	v_readlane_b32 s36, v252, 26
	s_movk_i32 s28, 0xf000
	v_readlane_b32 s37, v252, 27
	v_lshl_add_u64 v[188:189], s[26:27], 0, v[188:189]
	s_mov_b32 s29, s37
	s_cselect_b32 s28, s28, 0xffffe800
	v_lshl_add_u64 v[188:189], v[128:129], 1, v[188:189]
	v_lshl_add_u64 v[188:189], v[188:189], 0, s[28:29]
	v_cvt_pk_bf16_f32 v128, v133, s0
	global_store_short v[188:189], v128, off
	v_cvt_pk_bf16_f32 v128, v131, s0
	s_mov_b32 s27, s37
	global_store_short v[188:189], v128, off offset:2048
	v_add_co_u32_e32 v188, vcc, 0x1000, v188
	v_writelane_b32 v252, s26, 26
	v_cvt_pk_bf16_f32 v128, v187, s0
	v_addc_co_u32_e32 v189, vcc, 0, v189, vcc
	v_writelane_b32 v252, s27, 27
	global_store_short v[188:189], v128, off
	v_cvt_pk_bf16_f32 v128, v186, s0
	s_mov_b64 s[26:27], 0
	global_store_short v[188:189], v128, off offset:2048

.LBB0_1237:
	s_or_b64 exec, exec, s[26:27]
	v_cvt_pk_bf16_f32 v131, v131, s0
	v_lshl_add_u64 v[178:179], v[178:179], 0, v[194:195]
	global_store_short v[178:179], v131, off
	v_mov_b32_e32 v131, v221
	v_mov_b32_e32 v178, v221
	v_lshlrev_b32_e32 v131, 2, v131
	v_xor_b32_e32 v131, 0x80, v131
	ds_bpermute_b32 v133, v131, v96
	v_mov_b32_e32 v131, v221
	v_mov_b32_e32 v179, v96
	v_lshlrev_b32_e32 v131, 2, v131
	v_xor_b32_e32 v131, 0x80, v131
	v_lshlrev_b32_e32 v178, 2, v178
	ds_bpermute_b32 v131, v131, v99
	v_xor_b32_e32 v178, 0x80, v178
	ds_bpermute_b32 v194, v178, v100
	v_pk_mov_b32 v[224:225], v[98:99], v[98:99] op_sel:[1,0]
	v_mov_b32_e32 v226, v97
	s_waitcnt lgkmcnt(1)
	v_cndmask_b32_e64 v178, v131, 0, s[4:5]
	s_waitcnt vmcnt(1)
	v_pk_fma_f32 v[178:179], v[186:187], v[178:179], v[192:193] op_sel_hi:[0,1,0]
	s_waitcnt lgkmcnt(0)
	v_cndmask_b32_e64 v189, v194, v133, s[4:5]
	v_pk_fma_f32 v[178:179], v[188:189], v[96:97], v[178:179] op_sel_hi:[0,1,1]
	v_mov_b32_e32 v227, v225
	v_pk_fma_f32 v[178:179], v[190:191], v[226:227], v[178:179] op_sel_hi:[0,1,1]
	v_mul_f32_e32 v133, 0xbfb8aa3b, v178
	v_exp_f32_e32 v240, v133
	v_mul_f32_e32 v133, 0xbfb8aa3b, v179
	v_exp_f32_e32 v241, v133
	v_mov_b32_e32 v225, v189
	v_pk_add_f32 v[240:241], v[240:241], 1.0 op_sel_hi:[1,0]
	s_nop 0
	v_rcp_f32_e32 v187, v241
	s_nop 0
	v_mul_f32_e32 v133, v179, v187
	v_rcp_f32_e32 v187, v240
	s_nop 0
	v_mul_f32_e32 v179, v178, v187
	v_mov_b32_e32 v187, v179
	v_pk_fma_f32 v[178:179], v[186:187], v[226:227], v[192:193] op_sel_hi:[0,1,0]
	v_pk_fma_f32 v[178:179], v[98:99], v[188:189], v[178:179] op_sel_hi:[1,0,1]
	s_nop 0
	v_pk_fma_f32 v[178:179], v[224:225], v[190:191], v[178:179] op_sel_hi:[1,0,1]
	s_nop 0
	v_mul_f32_e32 v189, 0xbfb8aa3b, v178
	v_exp_f32_e32 v224, v189
	v_mul_f32_e32 v189, 0xbfb8aa3b, v179
	v_exp_f32_e32 v225, v189
	s_nop 0
	v_pk_add_f32 v[224:225], v[224:225], 1.0 op_sel_hi:[1,0]
	s_nop 0
	v_rcp_f32_e32 v191, v225
	s_nop 0
	v_mul_f32_e32 v189, v179, v191
	v_rcp_f32_e32 v191, v224
	s_mov_b64 s[26:27], -1
	v_mul_f32_e32 v179, v178, v191
	v_mov_b32_e32 v191, v179
	s_and_b64 vcc, exec, s[0:1]
	s_cbranch_vccnz .LBB0_1239
	s_and_b64 s[26:27], s[24:25], exec
	v_or_b32_e32 v178, v239, v158
	v_readlane_b32 s26, v252, 45
	v_readlane_b32 s28, v252, 47
	v_ashrrev_i32_e32 v179, 31, v178
	v_readlane_b32 s27, v252, 46
	v_readlane_b32 s29, v252, 48
	v_lshlrev_b64 v[178:179], 11, v[178:179]
	s_cselect_b32 s27, s27, s29
	s_cselect_b32 s26, s26, s28
	v_readlane_b32 s36, v252, 26
	s_movk_i32 s28, 0xf000
	v_readlane_b32 s37, v252, 27
	v_lshl_add_u64 v[178:179], s[26:27], 0, v[178:179]
	s_mov_b32 s29, s37
	s_cselect_b32 s28, s28, 0xffffe800
	v_lshl_add_u64 v[178:179], v[128:129], 1, v[178:179]
	v_lshl_add_u64 v[178:179], v[178:179], 0, s[28:29]
	v_cvt_pk_bf16_f32 v193, v187, s0
	global_store_short v[178:179], v193, off
	v_cvt_pk_bf16_f32 v193, v133, s0
	s_mov_b32 s27, s37
	global_store_short v[178:179], v193, off offset:2048
	v_add_co_u32_e32 v178, vcc, 0x1000, v178
	v_writelane_b32 v252, s26, 26
	v_cvt_pk_bf16_f32 v193, v191, s0
	v_addc_co_u32_e32 v179, vcc, 0, v179, vcc
	v_writelane_b32 v252, s27, 27
	global_store_short v[178:179], v193, off
	v_cvt_pk_bf16_f32 v193, v189, s0
	s_mov_b64 s[26:27], 0
	global_store_short v[178:179], v193, off offset:2048

.LBB0_1241:
	v_mov_b32_e32 v133, v221
	v_mov_b32_e32 v187, v186
	v_lshlrev_b32_e32 v133, 2, v133
	v_xor_b32_e32 v133, 0x80, v133
	ds_bpermute_b32 v184, v133, v103
	v_mov_b32_e32 v193, v192
	v_mov_b32_e32 v225, v100
	v_mov_b32_e32 v189, v188
	v_mov_b32_e32 v191, v190
	s_waitcnt lgkmcnt(0)
	v_cndmask_b32_e64 v224, v184, v131, s[4:5]
	v_pk_fma_f32 v[224:225], v[186:187], v[224:225], v[192:193]
	v_mov_b32_e32 v226, v101
	v_pk_fma_f32 v[224:225], v[100:101], v[188:189], v[224:225]
	v_mov_b32_e32 v227, v102
	v_pk_fma_f32 v[224:225], v[226:227], v[190:191], v[224:225]
	v_mov_b32_e32 v133, v221
	v_mul_f32_e32 v131, 0xbfb8aa3b, v224
	v_exp_f32_e32 v240, v131
	v_mul_f32_e32 v131, 0xbfb8aa3b, v225
	v_exp_f32_e32 v241, v131
	s_nop 0
	v_lshlrev_b32_e32 v133, 2, v133
	v_xor_b32_e32 v133, 0x80, v133
	v_pk_add_f32 v[240:241], v[240:241], 1.0 op_sel_hi:[1,0]
	ds_bpermute_b32 v185, v133, v104
	v_rcp_f32_e32 v133, v241
	s_waitcnt lgkmcnt(0)
	v_cndmask_b32_e64 v195, v185, v194, s[4:5]
	v_mul_f32_e32 v131, v225, v133
	v_rcp_f32_e32 v194, v240
	s_nop 0
	v_mul_f32_e32 v133, v224, v194
	v_pk_fma_f32 v[224:225], v[226:227], v[186:187], v[192:193]
	v_mov_b32_e32 v194, v103
	v_pk_fma_f32 v[224:225], v[102:103], v[188:189], v[224:225]
	s_nop 0
	v_pk_fma_f32 v[224:225], v[194:195], v[190:191], v[224:225]
	s_nop 0
	v_mul_f32_e32 v194, 0xbfb8aa3b, v224
	v_mul_f32_e32 v195, 0xbfb8aa3b, v225
	v_exp_f32_e32 v194, v194
	v_exp_f32_e32 v195, v195
	s_nop 0
	v_pk_add_f32 v[226:227], v[194:195], 1.0 op_sel_hi:[1,0]
	s_nop 0
	v_rcp_f32_e32 v195, v227
	s_nop 0
	v_mul_f32_e32 v194, v225, v195
	v_rcp_f32_e32 v222, v226
	s_mov_b64 s[26:27], -1
	v_mul_f32_e32 v195, v224, v222
	s_and_b64 vcc, exec, s[0:1]
	s_cbranch_vccnz .LBB0_1243
	s_and_b64 s[26:27], s[24:25], exec
	v_readlane_b32 s26, v252, 45
	v_readlane_b32 s28, v252, 47
	v_readlane_b32 s27, v252, 46
	v_readlane_b32 s29, v252, 48
	v_lshlrev_b64 v[182:183], 11, v[182:183]
	s_cselect_b32 s27, s27, s29
	s_cselect_b32 s26, s26, s28
	v_readlane_b32 s36, v252, 26
	s_movk_i32 s28, 0xf000
	v_readlane_b32 s37, v252, 27
	v_lshl_add_u64 v[182:183], s[26:27], 0, v[182:183]
	s_mov_b32 s29, s37
	s_cselect_b32 s28, s28, 0xffffe800
	v_lshl_add_u64 v[182:183], v[128:129], 1, v[182:183]
	v_lshl_add_u64 v[182:183], v[182:183], 0, s[28:29]
	v_cvt_pk_bf16_f32 v222, v133, s0
	global_store_short v[182:183], v222, off
	v_cvt_pk_bf16_f32 v222, v131, s0
	s_mov_b32 s27, s37
	global_store_short v[182:183], v222, off offset:2048
	v_add_co_u32_e32 v182, vcc, 0x1000, v182
	v_writelane_b32 v252, s26, 26
	v_cvt_pk_bf16_f32 v222, v195, s0
	v_addc_co_u32_e32 v183, vcc, 0, v183, vcc
	v_writelane_b32 v252, s27, 27
	global_store_short v[182:183], v222, off
	v_cvt_pk_bf16_f32 v222, v194, s0
	s_mov_b64 s[26:27], 0
	global_store_short v[182:183], v222, off offset:2048

.LBB0_1245:
	v_mov_b32_e32 v131, v221
	v_mov_b32_e32 v133, v221
	v_mov_b32_e32 v224, v105
	v_lshlrev_b32_e32 v131, 2, v131
	v_lshlrev_b32_e32 v133, 2, v133
	v_xor_b32_e32 v131, 0x80, v131
	v_xor_b32_e32 v133, 0x80, v133
	ds_bpermute_b32 v131, v131, v107
	ds_bpermute_b32 v182, v133, v108
	v_mov_b32_e32 v225, v106
	s_waitcnt lgkmcnt(1)
	v_cndmask_b32_e64 v184, v131, v184, s[4:5]
	s_waitcnt lgkmcnt(0)
	v_cndmask_b32_e64 v195, v182, v185, s[4:5]
	v_mov_b32_e32 v185, v104
	v_pk_fma_f32 v[184:185], v[186:187], v[184:185], v[192:193]
	s_nop 0
	v_pk_fma_f32 v[184:185], v[104:105], v[188:189], v[184:185]
	s_nop 0
	v_pk_fma_f32 v[184:185], v[224:225], v[190:191], v[184:185]
	s_nop 0
	v_mul_f32_e32 v133, 0xbfb8aa3b, v184
	v_exp_f32_e32 v226, v133
	v_mul_f32_e32 v133, 0xbfb8aa3b, v185
	v_exp_f32_e32 v227, v133
	s_nop 0
	v_pk_add_f32 v[226:227], v[226:227], 1.0 op_sel_hi:[1,0]
	s_nop 0
	v_rcp_f32_e32 v183, v227
	s_nop 0
	v_mul_f32_e32 v133, v185, v183
	v_rcp_f32_e32 v185, v226
	s_nop 0
	v_mul_f32_e32 v183, v184, v185
	v_pk_fma_f32 v[184:185], v[224:225], v[186:187], v[192:193]
	v_mov_b32_e32 v194, v107
	v_pk_fma_f32 v[184:185], v[106:107], v[188:189], v[184:185]
	s_nop 0
	v_pk_fma_f32 v[194:195], v[194:195], v[190:191], v[184:185]
	s_nop 0
	v_mul_f32_e32 v184, 0xbfb8aa3b, v194
	v_mul_f32_e32 v185, 0xbfb8aa3b, v195
	v_exp_f32_e32 v184, v184
	v_exp_f32_e32 v185, v185
	s_nop 0
	v_pk_add_f32 v[224:225], v[184:185], 1.0 op_sel_hi:[1,0]
	s_nop 0
	v_rcp_f32_e32 v185, v225
	s_nop 0
	v_mul_f32_e32 v184, v195, v185
	v_rcp_f32_e32 v195, v224
	s_mov_b64 s[26:27], -1
	v_mul_f32_e32 v185, v194, v195
	s_and_b64 vcc, exec, s[0:1]
	s_cbranch_vccnz .LBB0_1247
	s_and_b64 s[26:27], s[24:25], exec
	v_readlane_b32 s26, v252, 45
	v_readlane_b32 s28, v252, 47
	v_readlane_b32 s27, v252, 46
	v_readlane_b32 s29, v252, 48
	v_lshlrev_b64 v[180:181], 11, v[180:181]
	s_cselect_b32 s27, s27, s29
	s_cselect_b32 s26, s26, s28
	v_readlane_b32 s36, v252, 26
	s_movk_i32 s28, 0xf000
	v_readlane_b32 s37, v252, 27
	v_lshl_add_u64 v[180:181], s[26:27], 0, v[180:181]
	s_mov_b32 s29, s37
	s_cselect_b32 s28, s28, 0xffffe800
	v_lshl_add_u64 v[180:181], v[128:129], 1, v[180:181]
	v_lshl_add_u64 v[180:181], v[180:181], 0, s[28:29]
	v_cvt_pk_bf16_f32 v194, v183, s0
	global_store_short v[180:181], v194, off
	v_cvt_pk_bf16_f32 v194, v133, s0
	s_mov_b32 s27, s37
	global_store_short v[180:181], v194, off offset:2048
	v_add_co_u32_e32 v180, vcc, 0x1000, v180
	v_writelane_b32 v252, s26, 26
	v_cvt_pk_bf16_f32 v194, v185, s0
	v_addc_co_u32_e32 v181, vcc, 0, v181, vcc
	v_writelane_b32 v252, s27, 27
	global_store_short v[180:181], v194, off
	v_cvt_pk_bf16_f32 v194, v184, s0
	s_mov_b64 s[26:27], 0
	global_store_short v[180:181], v194, off offset:2048

.LBB0_1249:
	v_mov_b32_e32 v133, v221
	v_mov_b32_e32 v185, v108
	v_lshlrev_b32_e32 v133, 2, v133
	v_xor_b32_e32 v133, 0x80, v133
	ds_bpermute_b32 v180, v133, v111
	v_mov_b32_e32 v194, v109
	v_mov_b32_e32 v195, v110
	v_mov_b32_e32 v133, v221
	s_waitcnt lgkmcnt(0)
	v_cndmask_b32_e64 v184, v180, v131, s[4:5]
	v_pk_fma_f32 v[184:185], v[186:187], v[184:185], v[192:193]
	v_lshlrev_b32_e32 v133, 2, v133
	v_pk_fma_f32 v[184:185], v[108:109], v[188:189], v[184:185]
	v_xor_b32_e32 v133, 0x80, v133
	v_pk_fma_f32 v[184:185], v[194:195], v[190:191], v[184:185]
	ds_bpermute_b32 v181, v133, v64
	v_mul_f32_e32 v131, 0xbfb8aa3b, v184
	v_exp_f32_e32 v224, v131
	v_mul_f32_e32 v131, 0xbfb8aa3b, v185
	v_exp_f32_e32 v225, v131
	s_waitcnt lgkmcnt(0)
	v_cndmask_b32_e64 v183, v181, v182, s[4:5]
	v_pk_add_f32 v[224:225], v[224:225], 1.0 op_sel_hi:[1,0]
	s_nop 0
	v_rcp_f32_e32 v133, v225
	s_nop 0
	v_mul_f32_e32 v131, v185, v133
	v_rcp_f32_e32 v182, v224
	s_nop 0
	v_mul_f32_e32 v133, v184, v182
	v_pk_fma_f32 v[184:185], v[194:195], v[186:187], v[192:193]
	v_mov_b32_e32 v182, v111
	v_pk_fma_f32 v[184:185], v[110:111], v[188:189], v[184:185]
	s_nop 0
	v_pk_fma_f32 v[184:185], v[182:183], v[190:191], v[184:185]
	s_nop 0
	v_mul_f32_e32 v182, 0xbfb8aa3b, v184
	v_mul_f32_e32 v183, 0xbfb8aa3b, v185
	v_exp_f32_e32 v182, v182
	v_exp_f32_e32 v183, v183
	s_nop 0
	v_pk_add_f32 v[194:195], v[182:183], 1.0 op_sel_hi:[1,0]
	s_nop 0
	v_rcp_f32_e32 v183, v195
	s_nop 0
	v_mul_f32_e32 v182, v185, v183
	v_rcp_f32_e32 v185, v194
	s_mov_b64 s[26:27], -1
	v_mul_f32_e32 v183, v184, v185
	s_and_b64 vcc, exec, s[0:1]
	s_cbranch_vccnz .LBB0_1251
	s_and_b64 s[26:27], s[24:25], exec
	v_readlane_b32 s26, v252, 45
	v_readlane_b32 s28, v252, 47
	v_readlane_b32 s27, v252, 46
	v_readlane_b32 s29, v252, 48
	v_lshlrev_b64 v[176:177], 11, v[176:177]
	s_cselect_b32 s27, s27, s29
	s_cselect_b32 s26, s26, s28
	v_readlane_b32 s36, v252, 26
	s_movk_i32 s28, 0xf000
	v_readlane_b32 s37, v252, 27
	v_lshl_add_u64 v[176:177], s[26:27], 0, v[176:177]
	s_mov_b32 s29, s37
	s_cselect_b32 s28, s28, 0xffffe800
	v_lshl_add_u64 v[176:177], v[128:129], 1, v[176:177]
	v_lshl_add_u64 v[176:177], v[176:177], 0, s[28:29]
	v_cvt_pk_bf16_f32 v184, v133, s0
	global_store_short v[176:177], v184, off
	v_cvt_pk_bf16_f32 v184, v131, s0
	s_mov_b32 s27, s37
	global_store_short v[176:177], v184, off offset:2048
	v_add_co_u32_e32 v176, vcc, 0x1000, v176
	v_writelane_b32 v252, s26, 26
	v_cvt_pk_bf16_f32 v184, v183, s0
	v_addc_co_u32_e32 v177, vcc, 0, v177, vcc
	v_writelane_b32 v252, s27, 27
	global_store_short v[176:177], v184, off
	v_cvt_pk_bf16_f32 v184, v182, s0
	s_mov_b64 s[26:27], 0
	global_store_short v[176:177], v184, off offset:2048

.LBB0_1253:
	v_mov_b32_e32 v131, v221
	v_mov_b32_e32 v184, v65
	v_lshlrev_b32_e32 v131, 2, v131
	v_xor_b32_e32 v131, 0x80, v131
	ds_bpermute_b32 v176, v131, v67
	v_mov_b32_e32 v131, v221
	v_mov_b32_e32 v185, v66
	v_lshlrev_b32_e32 v131, 2, v131
	v_xor_b32_e32 v131, 0x80, v131
	ds_bpermute_b32 v177, v131, v68
	s_waitcnt lgkmcnt(1)
	v_cndmask_b32_e64 v180, v176, v180, s[4:5]
	s_waitcnt lgkmcnt(0)
	v_cndmask_b32_e64 v183, v177, v181, s[4:5]
	v_mov_b32_e32 v181, v64
	v_pk_fma_f32 v[180:181], v[186:187], v[180:181], v[192:193]
	s_nop 0
	v_pk_fma_f32 v[180:181], v[64:65], v[188:189], v[180:181]
	s_nop 0
	v_pk_fma_f32 v[180:181], v[184:185], v[190:191], v[180:181]
	s_nop 0
	v_mul_f32_e32 v131, 0xbfb8aa3b, v180
	v_exp_f32_e32 v194, v131
	v_mul_f32_e32 v131, 0xbfb8aa3b, v181
	v_exp_f32_e32 v195, v131
	s_nop 0
	v_pk_add_f32 v[194:195], v[194:195], 1.0 op_sel_hi:[1,0]
	s_nop 0
	v_rcp_f32_e32 v133, v195
	s_nop 0
	v_mul_f32_e32 v131, v181, v133
	v_rcp_f32_e32 v181, v194
	s_nop 0
	v_mul_f32_e32 v133, v180, v181
	v_pk_fma_f32 v[180:181], v[184:185], v[186:187], v[192:193]
	v_mov_b32_e32 v182, v67
	v_pk_fma_f32 v[180:181], v[66:67], v[188:189], v[180:181]
	s_nop 0
	v_pk_fma_f32 v[182:183], v[182:183], v[190:191], v[180:181]
	s_nop 0
	v_mul_f32_e32 v180, 0xbfb8aa3b, v182
	v_mul_f32_e32 v181, 0xbfb8aa3b, v183
	v_exp_f32_e32 v180, v180
	v_exp_f32_e32 v181, v181
	s_nop 0
	v_pk_add_f32 v[184:185], v[180:181], 1.0 op_sel_hi:[1,0]
	s_nop 0
	v_rcp_f32_e32 v181, v185
	s_nop 0
	v_mul_f32_e32 v180, v183, v181
	v_rcp_f32_e32 v183, v184
	s_mov_b64 s[26:27], -1
	v_mul_f32_e32 v181, v182, v183
	s_and_b64 vcc, exec, s[0:1]
	s_cbranch_vccnz .LBB0_1255
	s_and_b64 s[26:27], s[24:25], exec
	v_readlane_b32 s26, v252, 45
	v_readlane_b32 s28, v252, 47
	v_readlane_b32 s27, v252, 46
	v_readlane_b32 s29, v252, 48
	v_lshlrev_b64 v[174:175], 11, v[174:175]
	s_cselect_b32 s27, s27, s29
	s_cselect_b32 s26, s26, s28
	v_readlane_b32 s36, v252, 26
	s_movk_i32 s28, 0xf000
	v_readlane_b32 s37, v252, 27
	v_lshl_add_u64 v[174:175], s[26:27], 0, v[174:175]
	s_mov_b32 s29, s37
	s_cselect_b32 s28, s28, 0xffffe800
	v_lshl_add_u64 v[174:175], v[128:129], 1, v[174:175]
	v_lshl_add_u64 v[174:175], v[174:175], 0, s[28:29]
	v_cvt_pk_bf16_f32 v182, v133, s0
	global_store_short v[174:175], v182, off
	v_cvt_pk_bf16_f32 v182, v131, s0
	s_mov_b32 s27, s37
	global_store_short v[174:175], v182, off offset:2048
	v_add_co_u32_e32 v174, vcc, 0x1000, v174
	v_writelane_b32 v252, s26, 26
	v_cvt_pk_bf16_f32 v182, v181, s0
	v_addc_co_u32_e32 v175, vcc, 0, v175, vcc
	v_writelane_b32 v252, s27, 27
	global_store_short v[174:175], v182, off
	v_cvt_pk_bf16_f32 v182, v180, s0
	s_mov_b64 s[26:27], 0
	global_store_short v[174:175], v182, off offset:2048

.LBB0_1257:
	v_mov_b32_e32 v131, v221
	v_mov_b32_e32 v133, v221
	v_mov_b32_e32 v182, v69
	v_lshlrev_b32_e32 v131, 2, v131
	v_lshlrev_b32_e32 v133, 2, v133
	v_xor_b32_e32 v131, 0x80, v131
	v_xor_b32_e32 v133, 0x80, v133
	ds_bpermute_b32 v131, v131, v71
	ds_bpermute_b32 v174, v133, v72
	v_mov_b32_e32 v183, v70
	s_waitcnt lgkmcnt(1)
	v_cndmask_b32_e64 v176, v131, v176, s[4:5]
	s_waitcnt lgkmcnt(0)
	v_cndmask_b32_e64 v181, v174, v177, s[4:5]
	v_mov_b32_e32 v177, v68
	v_pk_fma_f32 v[176:177], v[186:187], v[176:177], v[192:193]
	s_nop 0
	v_pk_fma_f32 v[176:177], v[68:69], v[188:189], v[176:177]
	s_nop 0
	v_pk_fma_f32 v[176:177], v[182:183], v[190:191], v[176:177]
	s_nop 0
	v_mul_f32_e32 v133, 0xbfb8aa3b, v176
	v_exp_f32_e32 v184, v133
	v_mul_f32_e32 v133, 0xbfb8aa3b, v177
	v_exp_f32_e32 v185, v133
	s_nop 0
	v_pk_add_f32 v[184:185], v[184:185], 1.0 op_sel_hi:[1,0]
	s_nop 0
	v_rcp_f32_e32 v175, v185
	s_nop 0
	v_mul_f32_e32 v133, v177, v175
	v_rcp_f32_e32 v177, v184
	s_nop 0
	v_mul_f32_e32 v175, v176, v177
	v_pk_fma_f32 v[176:177], v[182:183], v[186:187], v[192:193]
	v_mov_b32_e32 v180, v71
	v_pk_fma_f32 v[176:177], v[70:71], v[188:189], v[176:177]
	s_nop 0
	v_pk_fma_f32 v[180:181], v[180:181], v[190:191], v[176:177]
	s_nop 0
	v_mul_f32_e32 v176, 0xbfb8aa3b, v180
	v_mul_f32_e32 v177, 0xbfb8aa3b, v181
	v_exp_f32_e32 v176, v176
	v_exp_f32_e32 v177, v177
	s_nop 0
	v_pk_add_f32 v[182:183], v[176:177], 1.0 op_sel_hi:[1,0]
	s_nop 0
	v_rcp_f32_e32 v177, v183
	s_nop 0
	v_mul_f32_e32 v176, v181, v177
	v_rcp_f32_e32 v181, v182
	s_mov_b64 s[26:27], -1
	v_mul_f32_e32 v177, v180, v181
	s_and_b64 vcc, exec, s[0:1]
	s_cbranch_vccnz .LBB0_1259
	s_and_b64 s[26:27], s[24:25], exec
	v_readlane_b32 s26, v252, 45
	v_readlane_b32 s28, v252, 47
	v_readlane_b32 s27, v252, 46
	v_readlane_b32 s29, v252, 48
	v_lshlrev_b64 v[172:173], 11, v[172:173]
	s_cselect_b32 s27, s27, s29
	s_cselect_b32 s26, s26, s28
	v_readlane_b32 s36, v252, 26
	s_movk_i32 s28, 0xf000
	v_readlane_b32 s37, v252, 27
	v_lshl_add_u64 v[172:173], s[26:27], 0, v[172:173]
	s_mov_b32 s29, s37
	s_cselect_b32 s28, s28, 0xffffe800
	v_lshl_add_u64 v[172:173], v[128:129], 1, v[172:173]
	v_lshl_add_u64 v[172:173], v[172:173], 0, s[28:29]
	v_cvt_pk_bf16_f32 v180, v175, s0
	global_store_short v[172:173], v180, off
	v_cvt_pk_bf16_f32 v180, v133, s0
	s_mov_b32 s27, s37
	global_store_short v[172:173], v180, off offset:2048
	v_add_co_u32_e32 v172, vcc, 0x1000, v172
	v_writelane_b32 v252, s26, 26
	v_cvt_pk_bf16_f32 v180, v177, s0
	v_addc_co_u32_e32 v173, vcc, 0, v173, vcc
	v_writelane_b32 v252, s27, 27
	global_store_short v[172:173], v180, off
	v_cvt_pk_bf16_f32 v180, v176, s0
	s_mov_b64 s[26:27], 0
	global_store_short v[172:173], v180, off offset:2048

.LBB0_1261:
	v_mov_b32_e32 v133, v221
	v_mov_b32_e32 v177, v72
	v_lshlrev_b32_e32 v133, 2, v133
	v_xor_b32_e32 v133, 0x80, v133
	ds_bpermute_b32 v172, v133, v75
	v_mov_b32_e32 v180, v73
	v_mov_b32_e32 v181, v74
	v_mov_b32_e32 v133, v221
	s_waitcnt lgkmcnt(0)
	v_cndmask_b32_e64 v176, v172, v131, s[4:5]
	v_pk_fma_f32 v[176:177], v[186:187], v[176:177], v[192:193]
	v_lshlrev_b32_e32 v133, 2, v133
	v_pk_fma_f32 v[176:177], v[72:73], v[188:189], v[176:177]
	v_xor_b32_e32 v133, 0x80, v133
	v_pk_fma_f32 v[176:177], v[180:181], v[190:191], v[176:177]
	ds_bpermute_b32 v173, v133, v76
	v_mul_f32_e32 v131, 0xbfb8aa3b, v176
	v_exp_f32_e32 v182, v131
	v_mul_f32_e32 v131, 0xbfb8aa3b, v177
	v_exp_f32_e32 v183, v131
	s_waitcnt lgkmcnt(0)
	v_cndmask_b32_e64 v175, v173, v174, s[4:5]
	v_pk_add_f32 v[182:183], v[182:183], 1.0 op_sel_hi:[1,0]
	s_nop 0
	v_rcp_f32_e32 v133, v183
	s_nop 0
	v_mul_f32_e32 v131, v177, v133
	v_rcp_f32_e32 v174, v182
	s_nop 0
	v_mul_f32_e32 v133, v176, v174
	v_pk_fma_f32 v[176:177], v[180:181], v[186:187], v[192:193]
	v_mov_b32_e32 v174, v75
	v_pk_fma_f32 v[176:177], v[74:75], v[188:189], v[176:177]
	s_nop 0
	v_pk_fma_f32 v[176:177], v[174:175], v[190:191], v[176:177]
	s_nop 0
	v_mul_f32_e32 v174, 0xbfb8aa3b, v176
	v_mul_f32_e32 v175, 0xbfb8aa3b, v177
	v_exp_f32_e32 v174, v174
	v_exp_f32_e32 v175, v175
	s_nop 0
	v_pk_add_f32 v[180:181], v[174:175], 1.0 op_sel_hi:[1,0]
	s_nop 0
	v_rcp_f32_e32 v175, v181
	s_nop 0
	v_mul_f32_e32 v174, v177, v175
	v_rcp_f32_e32 v177, v180
	s_mov_b64 s[26:27], -1
	v_mul_f32_e32 v175, v176, v177
	s_and_b64 vcc, exec, s[0:1]
	s_cbranch_vccnz .LBB0_1263
	s_and_b64 s[26:27], s[24:25], exec
	v_readlane_b32 s26, v252, 45
	v_readlane_b32 s28, v252, 47
	v_readlane_b32 s27, v252, 46
	v_readlane_b32 s29, v252, 48
	v_lshlrev_b64 v[152:153], 11, v[152:153]
	s_cselect_b32 s27, s27, s29
	s_cselect_b32 s26, s26, s28
	v_readlane_b32 s36, v252, 26
	s_movk_i32 s28, 0xf000
	v_readlane_b32 s37, v252, 27
	v_lshl_add_u64 v[152:153], s[26:27], 0, v[152:153]
	s_mov_b32 s29, s37
	s_cselect_b32 s28, s28, 0xffffe800
	v_lshl_add_u64 v[152:153], v[128:129], 1, v[152:153]
	v_lshl_add_u64 v[152:153], v[152:153], 0, s[28:29]
	v_cvt_pk_bf16_f32 v176, v133, s0
	global_store_short v[152:153], v176, off
	v_cvt_pk_bf16_f32 v176, v131, s0
	s_mov_b32 s27, s37
	global_store_short v[152:153], v176, off offset:2048
	v_add_co_u32_e32 v152, vcc, 0x1000, v152
	v_writelane_b32 v252, s26, 26
	v_cvt_pk_bf16_f32 v176, v175, s0
	v_addc_co_u32_e32 v153, vcc, 0, v153, vcc
	v_writelane_b32 v252, s27, 27
	global_store_short v[152:153], v176, off
	v_cvt_pk_bf16_f32 v176, v174, s0
	s_mov_b64 s[26:27], 0
	global_store_short v[152:153], v176, off offset:2048

.LBB0_1265:
	v_mov_b32_e32 v131, v221
	v_mov_b32_e32 v133, v221
	v_mov_b32_e32 v176, v77
	v_lshlrev_b32_e32 v131, 2, v131
	v_lshlrev_b32_e32 v133, 2, v133
	v_xor_b32_e32 v131, 0x80, v131
	v_xor_b32_e32 v133, 0x80, v133
	ds_bpermute_b32 v131, v131, v79
	ds_bpermute_b32 v152, v133, v32
	v_mov_b32_e32 v177, v78
	s_waitcnt lgkmcnt(1)
	v_cndmask_b32_e64 v172, v131, v172, s[4:5]
	s_waitcnt lgkmcnt(0)
	v_cndmask_b32_e64 v175, v152, v173, s[4:5]
	v_mov_b32_e32 v173, v76
	v_pk_fma_f32 v[172:173], v[186:187], v[172:173], v[192:193]
	s_nop 0
	v_pk_fma_f32 v[172:173], v[76:77], v[188:189], v[172:173]
	s_nop 0
	v_pk_fma_f32 v[172:173], v[176:177], v[190:191], v[172:173]
	s_nop 0
	v_mul_f32_e32 v133, 0xbfb8aa3b, v172
	v_exp_f32_e32 v180, v133
	v_mul_f32_e32 v133, 0xbfb8aa3b, v173
	v_exp_f32_e32 v181, v133
	s_nop 0
	v_pk_add_f32 v[180:181], v[180:181], 1.0 op_sel_hi:[1,0]
	s_nop 0
	v_rcp_f32_e32 v153, v181
	s_nop 0
	v_mul_f32_e32 v133, v173, v153
	v_rcp_f32_e32 v173, v180
	s_nop 0
	v_mul_f32_e32 v153, v172, v173
	v_pk_fma_f32 v[172:173], v[176:177], v[186:187], v[192:193]
	v_mov_b32_e32 v174, v79
	v_pk_fma_f32 v[172:173], v[78:79], v[188:189], v[172:173]
	s_nop 0
	v_pk_fma_f32 v[174:175], v[174:175], v[190:191], v[172:173]
	s_nop 0
	v_mul_f32_e32 v172, 0xbfb8aa3b, v174
	v_mul_f32_e32 v173, 0xbfb8aa3b, v175
	v_exp_f32_e32 v172, v172
	v_exp_f32_e32 v173, v173
	s_nop 0
	v_pk_add_f32 v[176:177], v[172:173], 1.0 op_sel_hi:[1,0]
	s_nop 0
	v_rcp_f32_e32 v173, v177
	s_nop 0
	v_mul_f32_e32 v172, v175, v173
	v_rcp_f32_e32 v175, v176
	s_mov_b64 s[26:27], -1
	v_mul_f32_e32 v173, v174, v175
	s_and_b64 vcc, exec, s[0:1]
	s_cbranch_vccnz .LBB0_1267
	s_and_b64 s[26:27], s[24:25], exec
	v_readlane_b32 s26, v252, 45
	v_readlane_b32 s28, v252, 47
	v_readlane_b32 s27, v252, 46
	v_readlane_b32 s29, v252, 48
	v_lshlrev_b64 v[150:151], 11, v[150:151]
	s_cselect_b32 s27, s27, s29
	s_cselect_b32 s26, s26, s28
	v_readlane_b32 s36, v252, 26
	s_movk_i32 s28, 0xf000
	v_readlane_b32 s37, v252, 27
	v_lshl_add_u64 v[150:151], s[26:27], 0, v[150:151]
	s_mov_b32 s29, s37
	s_cselect_b32 s28, s28, 0xffffe800
	v_lshl_add_u64 v[150:151], v[128:129], 1, v[150:151]
	v_lshl_add_u64 v[150:151], v[150:151], 0, s[28:29]
	v_cvt_pk_bf16_f32 v174, v153, s0
	global_store_short v[150:151], v174, off
	v_cvt_pk_bf16_f32 v174, v133, s0
	s_mov_b32 s27, s37
	global_store_short v[150:151], v174, off offset:2048
	v_add_co_u32_e32 v150, vcc, 0x1000, v150
	v_writelane_b32 v252, s26, 26
	v_cvt_pk_bf16_f32 v174, v173, s0
	v_addc_co_u32_e32 v151, vcc, 0, v151, vcc
	v_writelane_b32 v252, s27, 27
	global_store_short v[150:151], v174, off
	v_cvt_pk_bf16_f32 v174, v172, s0
	s_mov_b64 s[26:27], 0
	global_store_short v[150:151], v174, off offset:2048

.LBB0_1269:
	v_mov_b32_e32 v133, v221
	v_mov_b32_e32 v173, v32
	v_lshlrev_b32_e32 v133, 2, v133
	v_xor_b32_e32 v133, 0x80, v133
	ds_bpermute_b32 v150, v133, v35
	v_mov_b32_e32 v174, v33
	v_mov_b32_e32 v175, v34
	v_mov_b32_e32 v133, v221
	s_waitcnt lgkmcnt(0)
	v_cndmask_b32_e64 v172, v150, v131, s[4:5]
	v_pk_fma_f32 v[172:173], v[186:187], v[172:173], v[192:193]
	v_lshlrev_b32_e32 v133, 2, v133
	v_pk_fma_f32 v[172:173], v[32:33], v[188:189], v[172:173]
	v_xor_b32_e32 v133, 0x80, v133
	v_pk_fma_f32 v[172:173], v[174:175], v[190:191], v[172:173]
	ds_bpermute_b32 v151, v133, v36
	v_mul_f32_e32 v131, 0xbfb8aa3b, v172
	v_exp_f32_e32 v176, v131
	v_mul_f32_e32 v131, 0xbfb8aa3b, v173
	v_exp_f32_e32 v177, v131
	s_waitcnt lgkmcnt(0)
	v_cndmask_b32_e64 v153, v151, v152, s[4:5]
	v_pk_add_f32 v[176:177], v[176:177], 1.0 op_sel_hi:[1,0]
	s_nop 0
	v_rcp_f32_e32 v133, v177
	s_nop 0
	v_mul_f32_e32 v131, v173, v133
	v_rcp_f32_e32 v152, v176
	s_nop 0
	v_mul_f32_e32 v133, v172, v152
	v_pk_fma_f32 v[172:173], v[174:175], v[186:187], v[192:193]
	v_mov_b32_e32 v152, v35
	v_pk_fma_f32 v[172:173], v[34:35], v[188:189], v[172:173]
	s_nop 0
	v_pk_fma_f32 v[172:173], v[152:153], v[190:191], v[172:173]
	s_nop 0
	v_mul_f32_e32 v152, 0xbfb8aa3b, v172
	v_mul_f32_e32 v153, 0xbfb8aa3b, v173
	v_exp_f32_e32 v152, v152
	v_exp_f32_e32 v153, v153
	s_nop 0
	v_pk_add_f32 v[174:175], v[152:153], 1.0 op_sel_hi:[1,0]
	s_nop 0
	v_rcp_f32_e32 v153, v175
	s_nop 0
	v_mul_f32_e32 v152, v173, v153
	v_rcp_f32_e32 v173, v174
	s_mov_b64 s[26:27], -1
	v_mul_f32_e32 v153, v172, v173
	s_and_b64 vcc, exec, s[0:1]
	s_cbranch_vccnz .LBB0_1271
	s_and_b64 s[26:27], s[24:25], exec
	v_readlane_b32 s26, v252, 45
	v_readlane_b32 s28, v252, 47
	v_readlane_b32 s27, v252, 46
	v_readlane_b32 s29, v252, 48
	v_lshlrev_b64 v[148:149], 11, v[148:149]
	s_cselect_b32 s27, s27, s29
	s_cselect_b32 s26, s26, s28
	v_readlane_b32 s36, v252, 26
	s_movk_i32 s28, 0xf000
	v_readlane_b32 s37, v252, 27
	v_lshl_add_u64 v[148:149], s[26:27], 0, v[148:149]
	s_mov_b32 s29, s37
	s_cselect_b32 s28, s28, 0xffffe800
	v_lshl_add_u64 v[148:149], v[128:129], 1, v[148:149]
	v_lshl_add_u64 v[148:149], v[148:149], 0, s[28:29]
	v_cvt_pk_bf16_f32 v172, v133, s0
	global_store_short v[148:149], v172, off
	v_cvt_pk_bf16_f32 v172, v131, s0
	s_mov_b32 s27, s37
	global_store_short v[148:149], v172, off offset:2048
	v_add_co_u32_e32 v148, vcc, 0x1000, v148
	v_writelane_b32 v252, s26, 26
	v_cvt_pk_bf16_f32 v172, v153, s0
	v_addc_co_u32_e32 v149, vcc, 0, v149, vcc
	v_writelane_b32 v252, s27, 27
	global_store_short v[148:149], v172, off
	v_cvt_pk_bf16_f32 v172, v152, s0
	s_mov_b64 s[26:27], 0
	global_store_short v[148:149], v172, off offset:2048

.LBB0_1273:
	v_mov_b32_e32 v131, v221
	v_mov_b32_e32 v133, v221
	v_mov_b32_e32 v172, v37
	v_lshlrev_b32_e32 v131, 2, v131
	v_lshlrev_b32_e32 v133, 2, v133
	v_xor_b32_e32 v131, 0x80, v131
	v_xor_b32_e32 v133, 0x80, v133
	ds_bpermute_b32 v131, v131, v39
	ds_bpermute_b32 v148, v133, v40
	v_mov_b32_e32 v173, v38
	s_waitcnt lgkmcnt(1)
	v_cndmask_b32_e64 v150, v131, v150, s[4:5]
	s_waitcnt lgkmcnt(0)
	v_cndmask_b32_e64 v153, v148, v151, s[4:5]
	v_mov_b32_e32 v151, v36
	v_pk_fma_f32 v[150:151], v[186:187], v[150:151], v[192:193]
	s_nop 0
	v_pk_fma_f32 v[150:151], v[36:37], v[188:189], v[150:151]
	s_nop 0
	v_pk_fma_f32 v[150:151], v[172:173], v[190:191], v[150:151]
	s_nop 0
	v_mul_f32_e32 v133, 0xbfb8aa3b, v150
	v_exp_f32_e32 v174, v133
	v_mul_f32_e32 v133, 0xbfb8aa3b, v151
	v_exp_f32_e32 v175, v133
	s_nop 0
	v_pk_add_f32 v[174:175], v[174:175], 1.0 op_sel_hi:[1,0]
	s_nop 0
	v_rcp_f32_e32 v149, v175
	s_nop 0
	v_mul_f32_e32 v133, v151, v149
	v_rcp_f32_e32 v151, v174
	s_nop 0
	v_mul_f32_e32 v149, v150, v151
	v_pk_fma_f32 v[150:151], v[172:173], v[186:187], v[192:193]
	v_mov_b32_e32 v152, v39
	v_pk_fma_f32 v[150:151], v[38:39], v[188:189], v[150:151]
	s_nop 0
	v_pk_fma_f32 v[152:153], v[152:153], v[190:191], v[150:151]
	s_nop 0
	v_mul_f32_e32 v150, 0xbfb8aa3b, v152
	v_mul_f32_e32 v151, 0xbfb8aa3b, v153
	v_exp_f32_e32 v150, v150
	v_exp_f32_e32 v151, v151
	s_nop 0
	v_pk_add_f32 v[172:173], v[150:151], 1.0 op_sel_hi:[1,0]
	s_nop 0
	v_rcp_f32_e32 v151, v173
	s_nop 0
	v_mul_f32_e32 v150, v153, v151
	v_rcp_f32_e32 v153, v172
	s_mov_b64 s[26:27], -1
	v_mul_f32_e32 v151, v152, v153
	s_and_b64 vcc, exec, s[0:1]
	s_cbranch_vccnz .LBB0_1275
	s_and_b64 s[26:27], s[24:25], exec
	v_readlane_b32 s26, v252, 45
	v_readlane_b32 s28, v252, 47
	v_readlane_b32 s27, v252, 46
	v_readlane_b32 s29, v252, 48
	v_lshlrev_b64 v[146:147], 11, v[146:147]
	s_cselect_b32 s27, s27, s29
	s_cselect_b32 s26, s26, s28
	v_readlane_b32 s36, v252, 26
	s_movk_i32 s28, 0xf000
	v_readlane_b32 s37, v252, 27
	v_lshl_add_u64 v[146:147], s[26:27], 0, v[146:147]
	s_mov_b32 s29, s37
	s_cselect_b32 s28, s28, 0xffffe800
	v_lshl_add_u64 v[146:147], v[128:129], 1, v[146:147]
	v_lshl_add_u64 v[146:147], v[146:147], 0, s[28:29]
	v_cvt_pk_bf16_f32 v152, v149, s0
	global_store_short v[146:147], v152, off
	v_cvt_pk_bf16_f32 v152, v133, s0
	s_mov_b32 s27, s37
	global_store_short v[146:147], v152, off offset:2048
	v_add_co_u32_e32 v146, vcc, 0x1000, v146
	v_writelane_b32 v252, s26, 26
	v_cvt_pk_bf16_f32 v152, v151, s0
	v_addc_co_u32_e32 v147, vcc, 0, v147, vcc
	v_writelane_b32 v252, s27, 27
	global_store_short v[146:147], v152, off
	v_cvt_pk_bf16_f32 v152, v150, s0
	s_mov_b64 s[26:27], 0
	global_store_short v[146:147], v152, off offset:2048

.LBB0_1277:
	v_mov_b32_e32 v133, v221
	v_mov_b32_e32 v151, v40
	v_lshlrev_b32_e32 v133, 2, v133
	v_xor_b32_e32 v133, 0x80, v133
	ds_bpermute_b32 v146, v133, v43
	v_mov_b32_e32 v152, v41
	v_mov_b32_e32 v153, v42
	v_mov_b32_e32 v133, v221
	s_waitcnt lgkmcnt(0)
	v_cndmask_b32_e64 v150, v146, v131, s[4:5]
	v_pk_fma_f32 v[150:151], v[186:187], v[150:151], v[192:193]
	v_lshlrev_b32_e32 v133, 2, v133
	v_pk_fma_f32 v[150:151], v[40:41], v[188:189], v[150:151]
	v_xor_b32_e32 v133, 0x80, v133
	v_pk_fma_f32 v[150:151], v[152:153], v[190:191], v[150:151]
	ds_bpermute_b32 v147, v133, v44
	v_mul_f32_e32 v131, 0xbfb8aa3b, v150
	v_exp_f32_e32 v172, v131
	v_mul_f32_e32 v131, 0xbfb8aa3b, v151
	v_exp_f32_e32 v173, v131
	s_waitcnt lgkmcnt(0)
	v_cndmask_b32_e64 v149, v147, v148, s[4:5]
	v_pk_add_f32 v[172:173], v[172:173], 1.0 op_sel_hi:[1,0]
	s_nop 0
	v_rcp_f32_e32 v133, v173
	s_nop 0
	v_mul_f32_e32 v131, v151, v133
	v_rcp_f32_e32 v148, v172
	s_nop 0
	v_mul_f32_e32 v133, v150, v148
	v_pk_fma_f32 v[150:151], v[152:153], v[186:187], v[192:193]
	v_mov_b32_e32 v148, v43
	v_pk_fma_f32 v[150:151], v[42:43], v[188:189], v[150:151]
	s_nop 0
	v_pk_fma_f32 v[150:151], v[148:149], v[190:191], v[150:151]
	s_nop 0
	v_mul_f32_e32 v148, 0xbfb8aa3b, v150
	v_mul_f32_e32 v149, 0xbfb8aa3b, v151
	v_exp_f32_e32 v148, v148
	v_exp_f32_e32 v149, v149
	s_nop 0
	v_pk_add_f32 v[152:153], v[148:149], 1.0 op_sel_hi:[1,0]
	s_nop 0
	v_rcp_f32_e32 v149, v153
	s_nop 0
	v_mul_f32_e32 v148, v151, v149
	v_rcp_f32_e32 v151, v152
	s_mov_b64 s[26:27], -1
	v_mul_f32_e32 v149, v150, v151
	s_and_b64 vcc, exec, s[0:1]
	s_cbranch_vccnz .LBB0_1279
	s_and_b64 s[26:27], s[24:25], exec
	v_readlane_b32 s26, v252, 45
	v_readlane_b32 s28, v252, 47
	v_readlane_b32 s27, v252, 46
	v_readlane_b32 s29, v252, 48
	v_lshlrev_b64 v[144:145], 11, v[144:145]
	s_cselect_b32 s27, s27, s29
	s_cselect_b32 s26, s26, s28
	v_readlane_b32 s36, v252, 26
	s_movk_i32 s28, 0xf000
	v_readlane_b32 s37, v252, 27
	v_lshl_add_u64 v[144:145], s[26:27], 0, v[144:145]
	s_mov_b32 s29, s37
	s_cselect_b32 s28, s28, 0xffffe800
	v_lshl_add_u64 v[144:145], v[128:129], 1, v[144:145]
	v_lshl_add_u64 v[144:145], v[144:145], 0, s[28:29]
	v_cvt_pk_bf16_f32 v150, v133, s0
	global_store_short v[144:145], v150, off
	v_cvt_pk_bf16_f32 v150, v131, s0
	s_mov_b32 s27, s37
	global_store_short v[144:145], v150, off offset:2048
	v_add_co_u32_e32 v144, vcc, 0x1000, v144
	v_writelane_b32 v252, s26, 26
	v_cvt_pk_bf16_f32 v150, v149, s0
	v_addc_co_u32_e32 v145, vcc, 0, v145, vcc
	v_writelane_b32 v252, s27, 27
	global_store_short v[144:145], v150, off
	v_cvt_pk_bf16_f32 v150, v148, s0
	s_mov_b64 s[26:27], 0
	global_store_short v[144:145], v150, off offset:2048

.LBB0_1281:
	v_mov_b32_e32 v131, v221
	v_mov_b32_e32 v133, v221
	v_mov_b32_e32 v150, v45
	v_lshlrev_b32_e32 v131, 2, v131
	v_lshlrev_b32_e32 v133, 2, v133
	v_xor_b32_e32 v131, 0x80, v131
	v_xor_b32_e32 v133, 0x80, v133
	ds_bpermute_b32 v131, v131, v47
	ds_bpermute_b32 v144, v133, v0
	v_mov_b32_e32 v151, v46
	s_waitcnt lgkmcnt(1)
	v_cndmask_b32_e64 v146, v131, v146, s[4:5]
	s_waitcnt lgkmcnt(0)
	v_cndmask_b32_e64 v149, v144, v147, s[4:5]
	v_mov_b32_e32 v147, v44
	v_pk_fma_f32 v[146:147], v[186:187], v[146:147], v[192:193]
	s_nop 0
	v_pk_fma_f32 v[146:147], v[44:45], v[188:189], v[146:147]
	s_nop 0
	v_pk_fma_f32 v[146:147], v[150:151], v[190:191], v[146:147]
	s_nop 0
	v_mul_f32_e32 v133, 0xbfb8aa3b, v146
	v_exp_f32_e32 v152, v133
	v_mul_f32_e32 v133, 0xbfb8aa3b, v147
	v_exp_f32_e32 v153, v133
	s_nop 0
	v_pk_add_f32 v[152:153], v[152:153], 1.0 op_sel_hi:[1,0]
	s_nop 0
	v_rcp_f32_e32 v145, v153
	s_nop 0
	v_mul_f32_e32 v133, v147, v145
	v_rcp_f32_e32 v147, v152
	s_nop 0
	v_mul_f32_e32 v145, v146, v147
	v_pk_fma_f32 v[146:147], v[150:151], v[186:187], v[192:193]
	v_mov_b32_e32 v148, v47
	v_pk_fma_f32 v[146:147], v[46:47], v[188:189], v[146:147]
	s_nop 0
	v_pk_fma_f32 v[148:149], v[148:149], v[190:191], v[146:147]
	s_nop 0
	v_mul_f32_e32 v146, 0xbfb8aa3b, v148
	v_mul_f32_e32 v147, 0xbfb8aa3b, v149
	v_exp_f32_e32 v146, v146
	v_exp_f32_e32 v147, v147
	s_nop 0
	v_pk_add_f32 v[150:151], v[146:147], 1.0 op_sel_hi:[1,0]
	s_nop 0
	v_rcp_f32_e32 v147, v151
	s_nop 0
	v_mul_f32_e32 v146, v149, v147
	v_rcp_f32_e32 v149, v150
	s_mov_b64 s[26:27], -1
	v_mul_f32_e32 v147, v148, v149
	s_and_b64 vcc, exec, s[0:1]
	s_cbranch_vccnz .LBB0_1283
	s_and_b64 s[26:27], s[24:25], exec
	v_readlane_b32 s26, v252, 45
	v_readlane_b32 s28, v252, 47
	v_readlane_b32 s27, v252, 46
	v_readlane_b32 s29, v252, 48
	v_lshlrev_b64 v[142:143], 11, v[142:143]
	s_cselect_b32 s27, s27, s29
	s_cselect_b32 s26, s26, s28
	v_readlane_b32 s36, v252, 26
	s_movk_i32 s28, 0xf000
	v_readlane_b32 s37, v252, 27
	v_lshl_add_u64 v[142:143], s[26:27], 0, v[142:143]
	s_mov_b32 s29, s37
	s_cselect_b32 s28, s28, 0xffffe800
	v_lshl_add_u64 v[142:143], v[128:129], 1, v[142:143]
	v_lshl_add_u64 v[142:143], v[142:143], 0, s[28:29]
	v_cvt_pk_bf16_f32 v148, v145, s0
	global_store_short v[142:143], v148, off
	v_cvt_pk_bf16_f32 v148, v133, s0
	s_mov_b32 s27, s37
	global_store_short v[142:143], v148, off offset:2048
	v_add_co_u32_e32 v142, vcc, 0x1000, v142
	v_writelane_b32 v252, s26, 26
	v_cvt_pk_bf16_f32 v148, v147, s0
	v_addc_co_u32_e32 v143, vcc, 0, v143, vcc
	v_writelane_b32 v252, s27, 27
	global_store_short v[142:143], v148, off
	v_cvt_pk_bf16_f32 v148, v146, s0
	s_mov_b64 s[26:27], 0
	global_store_short v[142:143], v148, off offset:2048

.LBB0_1285:
	v_mov_b32_e32 v133, v221
	v_mov_b32_e32 v147, v0
	v_lshlrev_b32_e32 v133, 2, v133
	v_xor_b32_e32 v133, 0x80, v133
	ds_bpermute_b32 v142, v133, v3
	v_mov_b32_e32 v148, v1
	v_mov_b32_e32 v149, v2
	v_mov_b32_e32 v133, v221
	s_waitcnt lgkmcnt(0)
	v_cndmask_b32_e64 v146, v142, v131, s[4:5]
	v_pk_fma_f32 v[146:147], v[186:187], v[146:147], v[192:193]
	v_lshlrev_b32_e32 v133, 2, v133
	v_pk_fma_f32 v[146:147], v[0:1], v[188:189], v[146:147]
	v_xor_b32_e32 v133, 0x80, v133
	v_pk_fma_f32 v[146:147], v[148:149], v[190:191], v[146:147]
	ds_bpermute_b32 v143, v133, v4
	v_mul_f32_e32 v131, 0xbfb8aa3b, v146
	v_exp_f32_e32 v150, v131
	v_mul_f32_e32 v131, 0xbfb8aa3b, v147
	v_exp_f32_e32 v151, v131
	s_waitcnt lgkmcnt(0)
	v_cndmask_b32_e64 v145, v143, v144, s[4:5]
	v_pk_add_f32 v[150:151], v[150:151], 1.0 op_sel_hi:[1,0]
	s_nop 0
	v_rcp_f32_e32 v133, v151
	s_nop 0
	v_mul_f32_e32 v131, v147, v133
	v_rcp_f32_e32 v144, v150
	s_nop 0
	v_mul_f32_e32 v133, v146, v144
	v_pk_fma_f32 v[146:147], v[148:149], v[186:187], v[192:193]
	v_mov_b32_e32 v144, v3
	v_pk_fma_f32 v[146:147], v[2:3], v[188:189], v[146:147]
	s_nop 0
	v_pk_fma_f32 v[146:147], v[144:145], v[190:191], v[146:147]
	s_nop 0
	v_mul_f32_e32 v144, 0xbfb8aa3b, v146
	v_mul_f32_e32 v145, 0xbfb8aa3b, v147
	v_exp_f32_e32 v144, v144
	v_exp_f32_e32 v145, v145
	s_nop 0
	v_pk_add_f32 v[148:149], v[144:145], 1.0 op_sel_hi:[1,0]
	s_nop 0
	v_rcp_f32_e32 v145, v149
	s_nop 0
	v_mul_f32_e32 v144, v147, v145
	v_rcp_f32_e32 v147, v148
	s_mov_b64 s[26:27], -1
	v_mul_f32_e32 v145, v146, v147
	s_and_b64 vcc, exec, s[0:1]
	s_cbranch_vccnz .LBB0_1287
	s_and_b64 s[26:27], s[24:25], exec
	v_readlane_b32 s26, v252, 45
	v_readlane_b32 s28, v252, 47
	v_readlane_b32 s27, v252, 46
	v_readlane_b32 s29, v252, 48
	v_lshlrev_b64 v[140:141], 11, v[140:141]
	s_cselect_b32 s27, s27, s29
	s_cselect_b32 s26, s26, s28
	v_readlane_b32 s36, v252, 26
	s_movk_i32 s28, 0xf000
	v_readlane_b32 s37, v252, 27
	v_lshl_add_u64 v[140:141], s[26:27], 0, v[140:141]
	s_mov_b32 s29, s37
	s_cselect_b32 s28, s28, 0xffffe800
	v_lshl_add_u64 v[140:141], v[128:129], 1, v[140:141]
	v_lshl_add_u64 v[140:141], v[140:141], 0, s[28:29]
	v_cvt_pk_bf16_f32 v146, v133, s0
	global_store_short v[140:141], v146, off
	v_cvt_pk_bf16_f32 v146, v131, s0
	s_mov_b32 s27, s37
	global_store_short v[140:141], v146, off offset:2048
	v_add_co_u32_e32 v140, vcc, 0x1000, v140
	v_writelane_b32 v252, s26, 26
	v_cvt_pk_bf16_f32 v146, v145, s0
	v_addc_co_u32_e32 v141, vcc, 0, v141, vcc
	v_writelane_b32 v252, s27, 27
	global_store_short v[140:141], v146, off
	v_cvt_pk_bf16_f32 v146, v144, s0
	s_mov_b64 s[26:27], 0
	global_store_short v[140:141], v146, off offset:2048

.LBB0_1289:
	v_mov_b32_e32 v131, v221
	v_mov_b32_e32 v133, v221
	v_mov_b32_e32 v146, v5
	v_lshlrev_b32_e32 v131, 2, v131
	v_lshlrev_b32_e32 v133, 2, v133
	v_xor_b32_e32 v131, 0x80, v131
	v_xor_b32_e32 v133, 0x80, v133
	ds_bpermute_b32 v131, v131, v7
	ds_bpermute_b32 v140, v133, v8
	v_mov_b32_e32 v147, v6
	s_waitcnt lgkmcnt(1)
	v_cndmask_b32_e64 v142, v131, v142, s[4:5]
	s_waitcnt lgkmcnt(0)
	v_cndmask_b32_e64 v145, v140, v143, s[4:5]
	v_mov_b32_e32 v143, v4
	v_pk_fma_f32 v[142:143], v[186:187], v[142:143], v[192:193]
	s_nop 0
	v_pk_fma_f32 v[142:143], v[4:5], v[188:189], v[142:143]
	s_nop 0
	v_pk_fma_f32 v[142:143], v[146:147], v[190:191], v[142:143]
	s_nop 0
	v_mul_f32_e32 v133, 0xbfb8aa3b, v142
	v_exp_f32_e32 v148, v133
	v_mul_f32_e32 v133, 0xbfb8aa3b, v143
	v_exp_f32_e32 v149, v133
	s_nop 0
	v_pk_add_f32 v[148:149], v[148:149], 1.0 op_sel_hi:[1,0]
	s_nop 0
	v_rcp_f32_e32 v141, v149
	s_nop 0
	v_mul_f32_e32 v133, v143, v141
	v_rcp_f32_e32 v143, v148
	s_nop 0
	v_mul_f32_e32 v141, v142, v143
	v_pk_fma_f32 v[142:143], v[146:147], v[186:187], v[192:193]
	v_mov_b32_e32 v144, v7
	v_pk_fma_f32 v[142:143], v[6:7], v[188:189], v[142:143]
	s_nop 0
	v_pk_fma_f32 v[144:145], v[144:145], v[190:191], v[142:143]
	s_nop 0
	v_mul_f32_e32 v142, 0xbfb8aa3b, v144
	v_mul_f32_e32 v143, 0xbfb8aa3b, v145
	v_exp_f32_e32 v142, v142
	v_exp_f32_e32 v143, v143
	s_nop 0
	v_pk_add_f32 v[146:147], v[142:143], 1.0 op_sel_hi:[1,0]
	s_nop 0
	v_rcp_f32_e32 v143, v147
	s_nop 0
	v_mul_f32_e32 v142, v145, v143
	v_rcp_f32_e32 v145, v146
	s_mov_b64 s[26:27], -1
	v_mul_f32_e32 v143, v144, v145
	s_and_b64 vcc, exec, s[0:1]
	s_cbranch_vccnz .LBB0_1291
	s_and_b64 s[26:27], s[24:25], exec
	v_readlane_b32 s26, v252, 45
	v_readlane_b32 s28, v252, 47
	v_readlane_b32 s27, v252, 46
	v_readlane_b32 s29, v252, 48
	v_lshlrev_b64 v[138:139], 11, v[138:139]
	s_cselect_b32 s27, s27, s29
	s_cselect_b32 s26, s26, s28
	v_readlane_b32 s36, v252, 26
	s_movk_i32 s28, 0xf000
	v_readlane_b32 s37, v252, 27
	v_lshl_add_u64 v[138:139], s[26:27], 0, v[138:139]
	s_mov_b32 s29, s37
	s_cselect_b32 s28, s28, 0xffffe800
	v_lshl_add_u64 v[138:139], v[128:129], 1, v[138:139]
	v_lshl_add_u64 v[138:139], v[138:139], 0, s[28:29]
	v_cvt_pk_bf16_f32 v144, v141, s0
	global_store_short v[138:139], v144, off
	v_cvt_pk_bf16_f32 v144, v133, s0
	s_mov_b32 s27, s37
	global_store_short v[138:139], v144, off offset:2048
	v_add_co_u32_e32 v138, vcc, 0x1000, v138
	v_writelane_b32 v252, s26, 26
	v_cvt_pk_bf16_f32 v144, v143, s0
	v_addc_co_u32_e32 v139, vcc, 0, v139, vcc
	v_writelane_b32 v252, s27, 27
	global_store_short v[138:139], v144, off
	v_cvt_pk_bf16_f32 v144, v142, s0
	s_mov_b64 s[26:27], 0
	global_store_short v[138:139], v144, off offset:2048

.LBB0_1293:
	v_mov_b32_e32 v133, v221
	v_mov_b32_e32 v143, v8
	v_lshlrev_b32_e32 v133, 2, v133
	v_xor_b32_e32 v133, 0x80, v133
	ds_bpermute_b32 v138, v133, v11
	v_mov_b32_e32 v144, v9
	v_mov_b32_e32 v145, v10
	v_mov_b32_e32 v133, v221
	s_waitcnt lgkmcnt(0)
	v_cndmask_b32_e64 v142, v138, v131, s[4:5]
	v_pk_fma_f32 v[142:143], v[186:187], v[142:143], v[192:193]
	v_lshlrev_b32_e32 v133, 2, v133
	v_pk_fma_f32 v[142:143], v[8:9], v[188:189], v[142:143]
	v_xor_b32_e32 v133, 0x80, v133
	v_pk_fma_f32 v[142:143], v[144:145], v[190:191], v[142:143]
	ds_bpermute_b32 v139, v133, v12
	v_mul_f32_e32 v131, 0xbfb8aa3b, v142
	v_exp_f32_e32 v146, v131
	v_mul_f32_e32 v131, 0xbfb8aa3b, v143
	v_exp_f32_e32 v147, v131
	s_waitcnt lgkmcnt(0)
	v_cndmask_b32_e64 v141, v139, v140, s[4:5]
	v_pk_add_f32 v[146:147], v[146:147], 1.0 op_sel_hi:[1,0]
	s_nop 0
	v_rcp_f32_e32 v133, v147
	s_nop 0
	v_mul_f32_e32 v131, v143, v133
	v_rcp_f32_e32 v140, v146
	s_nop 0
	v_mul_f32_e32 v133, v142, v140
	v_pk_fma_f32 v[142:143], v[144:145], v[186:187], v[192:193]
	v_mov_b32_e32 v140, v11
	v_pk_fma_f32 v[142:143], v[10:11], v[188:189], v[142:143]
	s_nop 0
	v_pk_fma_f32 v[142:143], v[140:141], v[190:191], v[142:143]
	s_nop 0
	v_mul_f32_e32 v140, 0xbfb8aa3b, v142
	v_mul_f32_e32 v141, 0xbfb8aa3b, v143
	v_exp_f32_e32 v140, v140
	v_exp_f32_e32 v141, v141
	s_nop 0
	v_pk_add_f32 v[144:145], v[140:141], 1.0 op_sel_hi:[1,0]
	s_nop 0
	v_rcp_f32_e32 v141, v145
	s_nop 0
	v_mul_f32_e32 v140, v143, v141
	v_rcp_f32_e32 v143, v144
	s_mov_b64 s[26:27], -1
	v_mul_f32_e32 v141, v142, v143
	s_and_b64 vcc, exec, s[0:1]
	s_cbranch_vccnz .LBB0_1295
	s_and_b64 s[26:27], s[24:25], exec
	v_readlane_b32 s26, v252, 45
	v_readlane_b32 s28, v252, 47
	v_readlane_b32 s27, v252, 46
	v_readlane_b32 s29, v252, 48
	v_lshlrev_b64 v[136:137], 11, v[136:137]
	s_cselect_b32 s27, s27, s29
	s_cselect_b32 s26, s26, s28
	v_readlane_b32 s36, v252, 26
	s_movk_i32 s28, 0xf000
	v_readlane_b32 s37, v252, 27
	v_lshl_add_u64 v[136:137], s[26:27], 0, v[136:137]
	s_mov_b32 s29, s37
	s_cselect_b32 s28, s28, 0xffffe800
	v_lshl_add_u64 v[136:137], v[128:129], 1, v[136:137]
	v_lshl_add_u64 v[136:137], v[136:137], 0, s[28:29]
	v_cvt_pk_bf16_f32 v142, v133, s0
	global_store_short v[136:137], v142, off
	v_cvt_pk_bf16_f32 v142, v131, s0
	s_mov_b32 s27, s37
	global_store_short v[136:137], v142, off offset:2048
	v_add_co_u32_e32 v136, vcc, 0x1000, v136
	v_writelane_b32 v252, s26, 26
	v_cvt_pk_bf16_f32 v142, v141, s0
	v_addc_co_u32_e32 v137, vcc, 0, v137, vcc
	v_writelane_b32 v252, s27, 27
	global_store_short v[136:137], v142, off
	v_cvt_pk_bf16_f32 v142, v140, s0
	s_mov_b64 s[26:27], 0
	global_store_short v[136:137], v142, off offset:2048

.LBB0_1297:
	v_mov_b32_e32 v131, v221
	v_mov_b32_e32 v137, v12
	v_lshlrev_b32_e32 v131, 2, v131
	v_xor_b32_e32 v131, 0x80, v131
	ds_bpermute_b32 v131, v131, v15
	v_mov_b32_e32 v140, v13
	v_mov_b32_e32 v141, v14
	v_cndmask_b32_e64 v139, 0, v139, s[4:5]
	s_waitcnt lgkmcnt(0)
	v_cndmask_b32_e64 v136, v131, v138, s[4:5]
	v_pk_fma_f32 v[136:137], v[186:187], v[136:137], v[192:193]
	s_nop 0
	v_pk_fma_f32 v[136:137], v[12:13], v[188:189], v[136:137]
	s_nop 0
	v_pk_fma_f32 v[136:137], v[140:141], v[190:191], v[136:137]
	s_nop 0
	v_mul_f32_e32 v131, 0xbfb8aa3b, v136
	v_exp_f32_e32 v142, v131
	v_mul_f32_e32 v131, 0xbfb8aa3b, v137
	v_exp_f32_e32 v143, v131
	s_nop 0
	v_pk_add_f32 v[142:143], v[142:143], 1.0 op_sel_hi:[1,0]
	s_nop 0
	v_rcp_f32_e32 v133, v143
	s_nop 0
	v_mul_f32_e32 v131, v137, v133
	v_rcp_f32_e32 v137, v142
	s_nop 0
	v_mul_f32_e32 v133, v136, v137
	v_pk_fma_f32 v[136:137], v[140:141], v[186:187], v[192:193]
	v_mov_b32_e32 v138, v15
	v_pk_fma_f32 v[136:137], v[14:15], v[188:189], v[136:137]
	s_nop 0
	v_pk_fma_f32 v[138:139], v[138:139], v[190:191], v[136:137]
	s_nop 0
	v_mul_f32_e32 v136, 0xbfb8aa3b, v138
	v_mul_f32_e32 v137, 0xbfb8aa3b, v139
	v_exp_f32_e32 v136, v136
	v_exp_f32_e32 v137, v137
	s_nop 0
	v_pk_add_f32 v[140:141], v[136:137], 1.0 op_sel_hi:[1,0]
	s_nop 0
	v_rcp_f32_e32 v137, v141
	s_nop 0
	v_mul_f32_e32 v136, v139, v137
	v_rcp_f32_e32 v139, v140
	s_mov_b64 s[26:27], -1
	v_mul_f32_e32 v137, v138, v139
	s_and_b64 vcc, exec, s[0:1]
	s_cbranch_vccnz .LBB0_1299
	s_and_b64 s[0:1], s[24:25], exec
	v_readlane_b32 s0, v252, 45
	v_readlane_b32 s24, v252, 47
	v_readlane_b32 s1, v252, 46
	v_readlane_b32 s25, v252, 48
	v_lshlrev_b64 v[134:135], 11, v[134:135]
	s_cselect_b32 s1, s1, s25
	s_cselect_b32 s0, s0, s24
	v_readlane_b32 s26, v252, 26
	s_movk_i32 s24, 0xf000
	v_readlane_b32 s27, v252, 27
	v_lshl_add_u64 v[134:135], s[0:1], 0, v[134:135]
	s_mov_b32 s25, s27
	s_cselect_b32 s24, s24, 0xffffe800
	v_lshl_add_u64 v[134:135], v[128:129], 1, v[134:135]
	s_mov_b32 s1, s27
	v_writelane_b32 v252, s0, 26
	v_lshl_add_u64 v[134:135], v[134:135], 0, s[24:25]
	s_mov_b64 s[26:27], 0
	v_cvt_pk_bf16_f32 v128, v133, s0
	global_store_short v[134:135], v128, off
	v_cvt_pk_bf16_f32 v128, v131, s0
	global_store_short v[134:135], v128, off offset:2048
	v_add_co_u32_e32 v134, vcc, 0x1000, v134
	v_cvt_pk_bf16_f32 v128, v137, s0
	s_nop 0
	v_addc_co_u32_e32 v135, vcc, 0, v135, vcc
	v_writelane_b32 v252, s1, 27
	global_store_short v[134:135], v128, off
	v_cvt_pk_bf16_f32 v128, v136, s0
	global_store_short v[134:135], v128, off offset:2048

.LBB0_2338:
	s_or_b64 exec, exec, s[12:13]
	v_cvt_pk_bf16_f32 v143, v143, s0
	v_lshl_add_u64 v[132:133], v[132:133], 0, v[134:135]
	global_store_short v[132:133], v143, off
	v_or_b32_e32 v134, v142, v181
	v_mov_b64_e32 v[132:133], s[6:7]
	s_movk_i32 s12, 0x1600
	v_mad_i64_i32 v[132:133], s[12:13], v134, s12, v[132:133]
	v_lshl_add_u64 v[130:131], v[130:131], 1, v[132:133]
	v_mov_b32_e32 v132, v221
	v_mov_b32_e32 v133, v221
	v_mov_b32_e32 v134, v221
	v_mov_b32_e32 v135, v221
	v_lshlrev_b32_e32 v134, 2, v134
	v_xor_b32_e32 v134, 0x80, v134
	ds_bpermute_b32 v134, v134, v115
	v_lshlrev_b32_e32 v132, 2, v132
	v_lshlrev_b32_e32 v135, 2, v135
	v_xor_b32_e32 v135, 0x80, v135
	s_waitcnt lgkmcnt(0)
	v_cndmask_b32_e64 v144, v134, 0, s[0:1]
	s_waitcnt vmcnt(5)
	v_mul_f32_e32 v144, v136, v144
	v_fmac_f32_e32 v144, v137, v112
	s_waitcnt vmcnt(4)
	v_fmac_f32_e32 v144, v139, v113
	v_mul_f32_e32 v145, 0xbfb8aa3b, v144
	v_exp_f32_e32 v145, v145
	ds_bpermute_b32 v135, v135, v99
	v_xor_b32_e32 v132, 0x80, v132
	ds_bpermute_b32 v132, v132, v112
	v_add_f32_e32 v145, 1.0, v145
	v_rcp_f32_e32 v148, v145
	s_waitcnt lgkmcnt(1)
	v_cndmask_b32_e64 v146, v135, 0, s[0:1]
	s_waitcnt vmcnt(3)
	v_mul_f32_e32 v146, v138, v146
	s_waitcnt vmcnt(2)
	v_fmac_f32_e32 v146, v140, v96
	v_mul_f32_e32 v147, v144, v148
	v_mov_b32_e32 v144, v147
	v_mul_f32_e32 v145, v137, v113
	v_fmac_f32_e32 v145, v136, v112
	v_fmac_f32_e32 v145, v114, v139
	v_mul_f32_e32 v112, 0xbfb8aa3b, v145
	v_exp_f32_e32 v112, v112
	s_waitcnt vmcnt(1)
	v_fmac_f32_e32 v146, v141, v97
	v_mul_f32_e32 v144, v146, v144
	v_mov_b32_e32 v142, v221
	v_mov_b32_e32 v143, v221
	v_cvt_pk_bf16_f32 v144, v144, s0
	v_add_f32_e32 v112, 1.0, v112
	global_store_short v[130:131], v144, off
	v_rcp_f32_e32 v146, v112
	v_lshlrev_b32_e32 v133, 2, v133
	v_xor_b32_e32 v133, 0x80, v133
	v_mul_f32_e32 v147, v140, v97
	ds_bpermute_b32 v133, v133, v96
	v_fmac_f32_e32 v147, v138, v96
	v_mul_f32_e32 v144, v136, v113
	v_fmac_f32_e32 v144, v114, v137
	v_mul_f32_e32 v96, v145, v146
	v_fmac_f32_e32 v144, v115, v139
	v_mul_f32_e32 v112, 0xbfb8aa3b, v144
	v_exp_f32_e32 v145, v112
	v_fmac_f32_e32 v147, v98, v141
	s_movk_i32 s12, 0x1000
	v_mul_f32_e32 v96, v147, v96
	v_add_co_u32_e32 v112, vcc, s12, v130
	v_cvt_pk_bf16_f32 v96, v96, s0
	s_nop 0
	v_addc_co_u32_e32 v113, vcc, 0, v131, vcc
	global_store_short v[112:113], v96, off offset:1536
	v_add_f32_e32 v96, 1.0, v145
	v_rcp_f32_e32 v113, v96
	v_lshlrev_b32_e32 v142, 2, v142
	v_xor_b32_e32 v142, 0x80, v142
	ds_bpermute_b32 v142, v142, v116
	v_mul_f32_e32 v97, v138, v97
	v_fmac_f32_e32 v97, v98, v140
	v_mul_f32_e32 v112, v144, v113
	v_mul_f32_e32 v113, v115, v137
	s_waitcnt lgkmcnt(0)
	v_cndmask_b32_e64 v132, v142, v132, s[0:1]
	v_fmac_f32_e32 v97, v99, v141
	v_mov_b32_e32 v96, v112
	v_fmac_f32_e32 v113, v114, v136
	v_mul_f32_e32 v96, v97, v96
	v_fmac_f32_e32 v113, v139, v132
	v_cvt_pk_bf16_f32 v112, v96, s0
	v_mul_f32_e32 v96, 0xbfb8aa3b, v113
	v_exp_f32_e32 v114, v96
	v_add_co_u32_e32 v96, vcc, s47, v130
	v_lshlrev_b32_e32 v143, 2, v143
	s_nop 0
	v_addc_co_u32_e32 v97, vcc, 0, v131, vcc
	global_store_short v[96:97], v112, off offset:3072
	v_add_f32_e32 v96, 1.0, v114
	v_rcp_f32_e32 v112, v96
	v_mul_f32_e32 v99, v99, v140
	v_xor_b32_e32 v143, 0x80, v143
	v_fmac_f32_e32 v99, v98, v138
	ds_bpermute_b32 v143, v143, v100
	s_waitcnt lgkmcnt(0)
	v_cndmask_b32_e64 v133, v143, v133, s[0:1]
	v_mul_f32_e32 v97, v113, v112
	v_fmac_f32_e32 v99, v141, v133
	v_mov_b32_e32 v96, v97
	v_mul_f32_e32 v96, v99, v96
	s_movk_i32 s12, 0x4000
	v_cvt_pk_bf16_f32 v98, v96, s0
	v_add_co_u32_e32 v96, vcc, s12, v130
	s_nop 1
	v_addc_co_u32_e32 v97, vcc, 0, v131, vcc
	global_store_short v[96:97], v98, off offset:512
	v_mov_b32_e32 v96, v221
	s_nop 0
	v_lshlrev_b32_e32 v96, 2, v96
	v_xor_b32_e32 v96, 0x80, v96
	ds_bpermute_b32 v98, v96, v119
	v_mov_b32_e32 v96, v221
	s_nop 0
	v_lshlrev_b32_e32 v96, 2, v96
	v_xor_b32_e32 v96, 0x80, v96
	ds_bpermute_b32 v99, v96, v103
	v_mov_b32_e32 v96, v221
	s_waitcnt lgkmcnt(0)
	v_cndmask_b32_e64 v114, v99, v135, s[0:1]
	v_lshlrev_b32_e32 v96, 2, v96
	v_xor_b32_e32 v96, 0x80, v96
	ds_bpermute_b32 v112, v96, v120
	v_mov_b32_e32 v96, v221
	v_mul_f32_e32 v114, v138, v114
	v_lshlrev_b32_e32 v96, 2, v96
	v_xor_b32_e32 v96, 0x80, v96
	ds_bpermute_b32 v113, v96, v104
	v_cndmask_b32_e64 v96, v98, v134, s[0:1]
	v_mul_f32_e32 v96, v136, v96
	v_fmac_f32_e32 v96, v116, v137
	v_fmac_f32_e32 v96, v117, v139
	v_mul_f32_e32 v97, 0xbfb8aa3b, v96
	v_exp_f32_e32 v97, v97
	s_waitcnt lgkmcnt(1)
	v_cndmask_b32_e64 v115, v112, v142, s[0:1]
	s_waitcnt lgkmcnt(0)
	v_cndmask_b32_e64 v132, v113, v143, s[0:1]
	v_fmac_f32_e32 v114, v100, v140
	v_add_f32_e32 v97, 1.0, v97
	v_rcp_f32_e32 v134, v97
	v_fmac_f32_e32 v114, v101, v141
	s_mov_b32 s12, 0xb000
	v_mul_f32_e32 v133, v96, v134
	v_mov_b32_e32 v96, v133
	v_mul_f32_e32 v133, v117, v137
	v_fmac_f32_e32 v133, v116, v136
	v_mul_f32_e32 v96, v114, v96
	v_fmac_f32_e32 v133, v118, v139
	v_cvt_pk_bf16_f32 v114, v96, s0
	v_mul_f32_e32 v96, 0xbfb8aa3b, v133
	v_exp_f32_e32 v116, v96
	v_add_co_u32_e32 v96, vcc, s12, v130
	s_nop 1
	v_addc_co_u32_e32 v97, vcc, 0, v131, vcc
	global_store_short v[96:97], v114, off
	v_add_f32_e32 v96, 1.0, v116
	v_rcp_f32_e32 v114, v96
	v_mul_f32_e32 v116, v101, v140
	v_fmac_f32_e32 v116, v100, v138
	v_fmac_f32_e32 v116, v102, v141
	v_mul_f32_e32 v97, v133, v114
	v_mul_f32_e32 v114, v118, v137
	v_mov_b32_e32 v96, v97
	v_fmac_f32_e32 v114, v117, v136
	v_mul_f32_e32 v96, v116, v96
	v_fmac_f32_e32 v114, v119, v139
	v_cvt_pk_bf16_f32 v100, v96, s0
	v_mul_f32_e32 v96, 0xbfb8aa3b, v114
	v_exp_f32_e32 v116, v96
	s_mov_b32 s12, 0xc000
	v_add_co_u32_e32 v96, vcc, s12, v130
	s_nop 1
	v_addc_co_u32_e32 v97, vcc, 0, v131, vcc
	global_store_short v[96:97], v100, off offset:1536
	v_add_f32_e32 v96, 1.0, v116
	v_rcp_f32_e32 v100, v96
	v_mul_f32_e32 v116, v102, v140
	v_fmac_f32_e32 v116, v101, v138
	v_fmac_f32_e32 v116, v103, v141
	v_mul_f32_e32 v97, v114, v100
	v_mul_f32_e32 v101, v119, v137
	v_mov_b32_e32 v96, v97
	v_fmac_f32_e32 v101, v118, v136
	v_mul_f32_e32 v96, v116, v96
	v_fmac_f32_e32 v101, v139, v115
	v_cvt_pk_bf16_f32 v100, v96, s0
	v_mul_f32_e32 v96, 0xbfb8aa3b, v101
	v_exp_f32_e32 v114, v96
	s_mov_b32 s12, 0xd000
	v_add_co_u32_e32 v96, vcc, s12, v130
	v_mul_f32_e32 v103, v103, v140
	s_nop 0
	v_addc_co_u32_e32 v97, vcc, 0, v131, vcc
	global_store_short v[96:97], v100, off offset:3072
	v_add_f32_e32 v96, 1.0, v114
	v_rcp_f32_e32 v100, v96
	v_fmac_f32_e32 v103, v102, v138
	v_fmac_f32_e32 v103, v141, v132
	s_mov_b32 s12, 0xf000
	v_mul_f32_e32 v97, v101, v100
	v_mov_b32_e32 v96, v97
	v_mul_f32_e32 v96, v103, v96
	v_cvt_pk_bf16_f32 v100, v96, s0
	v_add_co_u32_e32 v96, vcc, s12, v130
	s_nop 1
	v_addc_co_u32_e32 v97, vcc, 0, v131, vcc
	global_store_short v[96:97], v100, off offset:512
	v_mov_b32_e32 v96, v221
	s_nop 0
	v_lshlrev_b32_e32 v96, 2, v96
	v_xor_b32_e32 v96, 0x80, v96
	ds_bpermute_b32 v100, v96, v123
	v_mov_b32_e32 v96, v221
	s_nop 0
	v_lshlrev_b32_e32 v96, 2, v96
	v_xor_b32_e32 v96, 0x80, v96
	ds_bpermute_b32 v101, v96, v107
	v_mov_b32_e32 v96, v221
	s_nop 0
	v_lshlrev_b32_e32 v96, 2, v96
	v_xor_b32_e32 v96, 0x80, v96
	ds_bpermute_b32 v102, v96, v124
	v_mov_b32_e32 v96, v221
	s_nop 0
	v_lshlrev_b32_e32 v96, 2, v96
	v_xor_b32_e32 v96, 0x80, v96
	ds_bpermute_b32 v103, v96, v108
	s_waitcnt lgkmcnt(3)
	v_cndmask_b32_e64 v96, v100, v98, s[0:1]
	v_mul_f32_e32 v96, v136, v96
	v_fmac_f32_e32 v96, v120, v137
	v_fmac_f32_e32 v96, v121, v139
	v_mul_f32_e32 v97, 0xbfb8aa3b, v96
	v_exp_f32_e32 v97, v97
	s_waitcnt lgkmcnt(2)
	v_cndmask_b32_e64 v98, v101, v99, s[0:1]
	s_waitcnt lgkmcnt(1)
	v_cndmask_b32_e64 v99, v102, v112, s[0:1]
	s_waitcnt lgkmcnt(0)
	v_cndmask_b32_e64 v112, v103, v113, s[0:1]
	v_add_f32_e32 v97, 1.0, v97
	v_rcp_f32_e32 v114, v97
	v_mul_f32_e32 v98, v138, v98
	v_fmac_f32_e32 v98, v104, v140
	v_fmac_f32_e32 v98, v105, v141
	v_mul_f32_e32 v113, v96, v114
	v_mov_b32_e32 v96, v113
	v_mul_f32_e32 v113, v121, v137
	v_fmac_f32_e32 v113, v120, v136
	v_mul_f32_e32 v96, v98, v96
	v_fmac_f32_e32 v113, v122, v139
	v_cvt_pk_bf16_f32 v98, v96, s0
	v_mul_f32_e32 v96, 0xbfb8aa3b, v113
	v_exp_f32_e32 v114, v96
	s_mov_b32 s12, 0x16000
	v_add_co_u32_e32 v96, vcc, s12, v130
	s_nop 1
	v_addc_co_u32_e32 v97, vcc, 0, v131, vcc
	global_store_short v[96:97], v98, off
	v_add_f32_e32 v96, 1.0, v114
	v_rcp_f32_e32 v98, v96
	v_mul_f32_e32 v114, v105, v140
	v_fmac_f32_e32 v114, v104, v138
	v_fmac_f32_e32 v114, v106, v141
	v_mul_f32_e32 v97, v113, v98
	v_mul_f32_e32 v104, v122, v137
	v_mov_b32_e32 v96, v97
	v_fmac_f32_e32 v104, v121, v136
	v_mul_f32_e32 v96, v114, v96
	v_fmac_f32_e32 v104, v123, v139
	v_cvt_pk_bf16_f32 v98, v96, s0
	v_mul_f32_e32 v96, 0xbfb8aa3b, v104
	v_exp_f32_e32 v113, v96
	s_mov_b32 s12, 0x17000
	v_add_co_u32_e32 v96, vcc, s12, v130
	s_nop 1
	v_addc_co_u32_e32 v97, vcc, 0, v131, vcc
	global_store_short v[96:97], v98, off offset:1536
	v_add_f32_e32 v96, 1.0, v113
	v_rcp_f32_e32 v98, v96
	v_mul_f32_e32 v113, v106, v140
	v_fmac_f32_e32 v113, v105, v138
	v_fmac_f32_e32 v113, v107, v141
	v_mul_f32_e32 v97, v104, v98
	v_mov_b32_e32 v96, v97
	v_mul_f32_e32 v104, v123, v137
	v_fmac_f32_e32 v104, v122, v136
	v_mul_f32_e32 v96, v113, v96
	v_fmac_f32_e32 v104, v139, v99
	v_cvt_pk_bf16_f32 v98, v96, s0
	v_mul_f32_e32 v96, 0xbfb8aa3b, v104
	v_exp_f32_e32 v99, v96
	s_mov_b32 s12, 0x18000
	v_add_co_u32_e32 v96, vcc, s12, v130
	s_nop 1
	v_addc_co_u32_e32 v97, vcc, 0, v131, vcc
	global_store_short v[96:97], v98, off offset:3072
	v_add_f32_e32 v96, 1.0, v99
	v_rcp_f32_e32 v98, v96
	v_mul_f32_e32 v99, v107, v140
	v_fmac_f32_e32 v99, v106, v138
	v_fmac_f32_e32 v99, v141, v112
	v_mul_f32_e32 v97, v104, v98
	v_mov_b32_e32 v96, v97
	v_mul_f32_e32 v96, v99, v96
	s_mov_b32 s12, 0x1a000
	v_cvt_pk_bf16_f32 v98, v96, s0
	v_add_co_u32_e32 v96, vcc, s12, v130
	s_nop 1
	v_addc_co_u32_e32 v97, vcc, 0, v131, vcc
	global_store_short v[96:97], v98, off offset:512
	v_mov_b32_e32 v96, v221
	s_nop 0
	v_lshlrev_b32_e32 v96, 2, v96
	v_xor_b32_e32 v96, 0x80, v96
	ds_bpermute_b32 v98, v96, v127
	v_mov_b32_e32 v96, v221
	s_nop 0
	v_lshlrev_b32_e32 v96, 2, v96
	v_xor_b32_e32 v96, 0x80, v96
	ds_bpermute_b32 v99, v96, v111
	v_mov_b32_e32 v96, v221
	s_nop 0
	v_lshlrev_b32_e32 v96, 2, v96
	v_xor_b32_e32 v96, 0x80, v96
	ds_bpermute_b32 v104, v96, v80
	v_mov_b32_e32 v96, v221
	s_nop 0
	v_lshlrev_b32_e32 v96, 2, v96
	v_xor_b32_e32 v96, 0x80, v96
	ds_bpermute_b32 v105, v96, v64
	s_waitcnt lgkmcnt(3)
	v_cndmask_b32_e64 v96, v98, v100, s[0:1]
	v_mul_f32_e32 v96, v136, v96
	v_fmac_f32_e32 v96, v124, v137
	v_fmac_f32_e32 v96, v125, v139
	v_mul_f32_e32 v97, 0xbfb8aa3b, v96
	v_exp_f32_e32 v97, v97
	s_waitcnt lgkmcnt(2)
	v_cndmask_b32_e64 v100, v99, v101, s[0:1]
	s_waitcnt lgkmcnt(1)
	v_cndmask_b32_e64 v101, v104, v102, s[0:1]
	s_waitcnt lgkmcnt(0)
	v_cndmask_b32_e64 v102, v105, v103, s[0:1]
	v_add_f32_e32 v97, 1.0, v97
	v_rcp_f32_e32 v106, v97
	v_mul_f32_e32 v100, v138, v100
	v_fmac_f32_e32 v100, v108, v140
	v_fmac_f32_e32 v100, v109, v141
	v_mul_f32_e32 v103, v96, v106
	v_mov_b32_e32 v96, v103
	v_mul_f32_e32 v103, v125, v137
	v_fmac_f32_e32 v103, v124, v136
	v_mul_f32_e32 v96, v100, v96
	v_fmac_f32_e32 v103, v126, v139
	v_cvt_pk_bf16_f32 v100, v96, s0
	v_mul_f32_e32 v96, 0xbfb8aa3b, v103
	v_exp_f32_e32 v106, v96
	s_mov_b32 s12, 0x21000
	v_add_co_u32_e32 v96, vcc, s12, v130
	s_nop 1
	v_addc_co_u32_e32 v97, vcc, 0, v131, vcc
	global_store_short v[96:97], v100, off
	v_add_f32_e32 v96, 1.0, v106
	v_rcp_f32_e32 v100, v96
	v_mul_f32_e32 v106, v109, v140
	v_fmac_f32_e32 v106, v108, v138
	v_fmac_f32_e32 v106, v110, v141
	v_mul_f32_e32 v97, v103, v100
	v_mov_b32_e32 v96, v97
	v_mul_f32_e32 v103, v126, v137
	v_fmac_f32_e32 v103, v125, v136
	v_mul_f32_e32 v96, v106, v96
	v_fmac_f32_e32 v103, v127, v139
	v_cvt_pk_bf16_f32 v100, v96, s0
	v_mul_f32_e32 v96, 0xbfb8aa3b, v103
	v_exp_f32_e32 v106, v96
	s_mov_b32 s12, 0x22000
	v_add_co_u32_e32 v96, vcc, s12, v130
	s_nop 1
	v_addc_co_u32_e32 v97, vcc, 0, v131, vcc
	global_store_short v[96:97], v100, off offset:1536
	v_add_f32_e32 v96, 1.0, v106
	v_rcp_f32_e32 v100, v96
	v_mul_f32_e32 v106, v110, v140
	v_fmac_f32_e32 v106, v109, v138
	v_fmac_f32_e32 v106, v111, v141
	v_mul_f32_e32 v97, v103, v100
	v_mov_b32_e32 v96, v97
	v_mul_f32_e32 v103, v127, v137
	v_fmac_f32_e32 v103, v126, v136
	v_mul_f32_e32 v96, v106, v96
	v_fmac_f32_e32 v103, v139, v101
	v_cvt_pk_bf16_f32 v100, v96, s0
	v_mul_f32_e32 v96, 0xbfb8aa3b, v103
	v_exp_f32_e32 v101, v96
	s_mov_b32 s12, 0x23000
	v_add_co_u32_e32 v96, vcc, s12, v130
	s_nop 1
	v_addc_co_u32_e32 v97, vcc, 0, v131, vcc
	global_store_short v[96:97], v100, off offset:3072
	v_add_f32_e32 v96, 1.0, v101
	v_rcp_f32_e32 v100, v96
	v_mul_f32_e32 v101, v111, v140
	v_fmac_f32_e32 v101, v110, v138
	v_fmac_f32_e32 v101, v141, v102
	v_mul_f32_e32 v97, v103, v100
	v_mov_b32_e32 v96, v97
	v_mul_f32_e32 v96, v101, v96
	s_mov_b32 s12, 0x25000
	v_cvt_pk_bf16_f32 v100, v96, s0
	v_add_co_u32_e32 v96, vcc, s12, v130
	s_nop 1
	v_addc_co_u32_e32 v97, vcc, 0, v131, vcc
	global_store_short v[96:97], v100, off offset:512
	v_mov_b32_e32 v96, v221
	s_nop 0
	v_lshlrev_b32_e32 v96, 2, v96
	v_xor_b32_e32 v96, 0x80, v96
	ds_bpermute_b32 v100, v96, v83
	v_mov_b32_e32 v96, v221
	s_nop 0
	v_lshlrev_b32_e32 v96, 2, v96
	v_xor_b32_e32 v96, 0x80, v96
	ds_bpermute_b32 v101, v96, v67
	v_mov_b32_e32 v96, v221
	s_nop 0
	v_lshlrev_b32_e32 v96, 2, v96
	v_xor_b32_e32 v96, 0x80, v96
	ds_bpermute_b32 v102, v96, v84
	v_mov_b32_e32 v96, v221
	s_nop 0
	v_lshlrev_b32_e32 v96, 2, v96
	v_xor_b32_e32 v96, 0x80, v96
	ds_bpermute_b32 v103, v96, v68
	s_waitcnt lgkmcnt(3)
	v_cndmask_b32_e64 v96, v100, v98, s[0:1]
	v_mul_f32_e32 v96, v136, v96
	v_fmac_f32_e32 v96, v80, v137
	v_fmac_f32_e32 v96, v81, v139
	v_mul_f32_e32 v97, 0xbfb8aa3b, v96
	v_exp_f32_e32 v97, v97
	s_waitcnt lgkmcnt(2)
	v_cndmask_b32_e64 v98, v101, v99, s[0:1]
	s_waitcnt lgkmcnt(1)
	v_cndmask_b32_e64 v99, v102, v104, s[0:1]
	s_waitcnt lgkmcnt(0)
	v_cndmask_b32_e64 v104, v103, v105, s[0:1]
	v_add_f32_e32 v97, 1.0, v97
	v_rcp_f32_e32 v106, v97
	v_mul_f32_e32 v98, v138, v98
	v_fmac_f32_e32 v98, v64, v140
	v_fmac_f32_e32 v98, v65, v141
	v_mul_f32_e32 v105, v96, v106
	v_mov_b32_e32 v96, v105
	v_mul_f32_e32 v105, v81, v137
	v_fmac_f32_e32 v105, v80, v136
	v_fmac_f32_e32 v105, v82, v139
	v_mul_f32_e32 v80, 0xbfb8aa3b, v105
	v_exp_f32_e32 v80, v80
	v_mul_f32_e32 v96, v98, v96
	s_mov_b32 s12, 0x2c000
	v_cvt_pk_bf16_f32 v98, v96, s0
	v_add_co_u32_e32 v96, vcc, s12, v130
	v_add_f32_e32 v80, 1.0, v80
	s_nop 0
	v_addc_co_u32_e32 v97, vcc, 0, v131, vcc
	global_store_short v[96:97], v98, off
	v_rcp_f32_e32 v97, v80
	v_mul_f32_e32 v98, v65, v140
	v_fmac_f32_e32 v98, v64, v138
	v_fmac_f32_e32 v98, v66, v141
	v_mul_f32_e32 v96, v82, v137
	v_fmac_f32_e32 v96, v81, v136
	v_mul_f32_e32 v64, v105, v97
	v_fmac_f32_e32 v96, v83, v139
	v_mul_f32_e32 v80, 0xbfb8aa3b, v96
	v_exp_f32_e32 v97, v80
	s_mov_b32 s12, 0x2d000
	v_mul_f32_e32 v64, v98, v64
	v_add_co_u32_e32 v80, vcc, s12, v130
	v_cvt_pk_bf16_f32 v64, v64, s0
	s_nop 0
	v_addc_co_u32_e32 v81, vcc, 0, v131, vcc
	global_store_short v[80:81], v64, off offset:1536
	v_add_f32_e32 v64, 1.0, v97
	v_rcp_f32_e32 v81, v64
	v_mul_f32_e32 v97, v66, v140
	v_fmac_f32_e32 v97, v65, v138
	v_fmac_f32_e32 v97, v67, v141
	v_mul_f32_e32 v65, v96, v81
	v_mul_f32_e32 v81, v83, v137
	v_mov_b32_e32 v64, v65
	v_fmac_f32_e32 v81, v82, v136
	v_mul_f32_e32 v64, v97, v64
	v_fmac_f32_e32 v81, v139, v99
	v_cvt_pk_bf16_f32 v80, v64, s0
	v_mul_f32_e32 v64, 0xbfb8aa3b, v81
	v_exp_f32_e32 v82, v64
	s_mov_b32 s12, 0x2e000
	v_add_co_u32_e32 v64, vcc, s12, v130
	v_mul_f32_e32 v67, v67, v140
	s_nop 0
	v_addc_co_u32_e32 v65, vcc, 0, v131, vcc
	global_store_short v[64:65], v80, off offset:3072
	v_add_f32_e32 v64, 1.0, v82
	v_rcp_f32_e32 v80, v64
	v_fmac_f32_e32 v67, v66, v138
	v_fmac_f32_e32 v67, v141, v104
	s_mov_b32 s12, 0x30000
	v_mul_f32_e32 v65, v81, v80
	v_mov_b32_e32 v64, v65
	v_mul_f32_e32 v64, v67, v64
	v_cvt_pk_bf16_f32 v66, v64, s0
	v_add_co_u32_e32 v64, vcc, s12, v130
	s_nop 1
	v_addc_co_u32_e32 v65, vcc, 0, v131, vcc
	global_store_short v[64:65], v66, off offset:512
	v_mov_b32_e32 v64, v221
	s_nop 0
	v_lshlrev_b32_e32 v64, 2, v64
	v_xor_b32_e32 v64, 0x80, v64
	ds_bpermute_b32 v66, v64, v87
	v_mov_b32_e32 v64, v221
	s_nop 0
	v_lshlrev_b32_e32 v64, 2, v64
	v_xor_b32_e32 v64, 0x80, v64
	ds_bpermute_b32 v67, v64, v71
	v_mov_b32_e32 v64, v221
	s_waitcnt lgkmcnt(0)
	v_cndmask_b32_e64 v82, v67, v101, s[0:1]
	v_lshlrev_b32_e32 v64, 2, v64
	v_xor_b32_e32 v64, 0x80, v64
	ds_bpermute_b32 v80, v64, v88
	v_mov_b32_e32 v64, v221
	v_mul_f32_e32 v82, v138, v82
	v_lshlrev_b32_e32 v64, 2, v64
	v_xor_b32_e32 v64, 0x80, v64
	ds_bpermute_b32 v81, v64, v72
	v_cndmask_b32_e64 v64, v66, v100, s[0:1]
	v_mul_f32_e32 v64, v136, v64
	v_fmac_f32_e32 v64, v84, v137
	v_fmac_f32_e32 v64, v85, v139
	v_mul_f32_e32 v65, 0xbfb8aa3b, v64
	v_exp_f32_e32 v65, v65
	v_fmac_f32_e32 v82, v68, v140
	v_fmac_f32_e32 v82, v69, v141
	s_waitcnt lgkmcnt(1)
	v_cndmask_b32_e64 v83, v80, v102, s[0:1]
	v_add_f32_e32 v65, 1.0, v65
	v_rcp_f32_e32 v98, v65
	s_mov_b32 s12, 0x37000
	s_waitcnt lgkmcnt(0)
	v_cndmask_b32_e64 v96, v81, v103, s[0:1]
	v_mul_f32_e32 v97, v64, v98
	v_mov_b32_e32 v64, v97
	v_mul_f32_e32 v97, v85, v137
	v_fmac_f32_e32 v97, v84, v136
	v_mul_f32_e32 v64, v82, v64
	v_fmac_f32_e32 v97, v86, v139
	v_cvt_pk_bf16_f32 v82, v64, s0
	v_mul_f32_e32 v64, 0xbfb8aa3b, v97
	v_exp_f32_e32 v84, v64
	v_add_co_u32_e32 v64, vcc, s12, v130
	s_nop 1
	v_addc_co_u32_e32 v65, vcc, 0, v131, vcc
	global_store_short v[64:65], v82, off
	v_add_f32_e32 v64, 1.0, v84
	v_rcp_f32_e32 v82, v64
	v_mul_f32_e32 v84, v69, v140
	v_fmac_f32_e32 v84, v68, v138
	v_fmac_f32_e32 v84, v70, v141
	v_mul_f32_e32 v65, v97, v82
	v_mul_f32_e32 v82, v86, v137
	v_mov_b32_e32 v64, v65
	v_fmac_f32_e32 v82, v85, v136
	v_mul_f32_e32 v64, v84, v64
	v_fmac_f32_e32 v82, v87, v139
	v_cvt_pk_bf16_f32 v68, v64, s0
	v_mul_f32_e32 v64, 0xbfb8aa3b, v82
	v_exp_f32_e32 v84, v64
	s_mov_b32 s12, 0x38000
	v_add_co_u32_e32 v64, vcc, s12, v130
	s_nop 1
	v_addc_co_u32_e32 v65, vcc, 0, v131, vcc
	global_store_short v[64:65], v68, off offset:1536
	v_add_f32_e32 v64, 1.0, v84
	v_rcp_f32_e32 v68, v64
	v_mul_f32_e32 v84, v70, v140
	v_fmac_f32_e32 v84, v69, v138
	v_fmac_f32_e32 v84, v71, v141
	v_mul_f32_e32 v65, v82, v68
	v_mul_f32_e32 v69, v87, v137
	v_mov_b32_e32 v64, v65
	v_fmac_f32_e32 v69, v86, v136
	v_mul_f32_e32 v64, v84, v64
	v_fmac_f32_e32 v69, v139, v83
	v_cvt_pk_bf16_f32 v68, v64, s0
	v_mul_f32_e32 v64, 0xbfb8aa3b, v69
	v_exp_f32_e32 v82, v64
	s_mov_b32 s12, 0x39000
	v_add_co_u32_e32 v64, vcc, s12, v130
	v_mul_f32_e32 v71, v71, v140
	s_nop 0
	v_addc_co_u32_e32 v65, vcc, 0, v131, vcc
	global_store_short v[64:65], v68, off offset:3072
	v_add_f32_e32 v64, 1.0, v82
	v_rcp_f32_e32 v68, v64
	v_fmac_f32_e32 v71, v70, v138
	v_fmac_f32_e32 v71, v141, v96
	s_mov_b32 s12, 0x3b000
	v_mul_f32_e32 v65, v69, v68
	v_mov_b32_e32 v64, v65
	v_mul_f32_e32 v64, v71, v64
	v_cvt_pk_bf16_f32 v68, v64, s0
	v_add_co_u32_e32 v64, vcc, s12, v130
	s_nop 1
	v_addc_co_u32_e32 v65, vcc, 0, v131, vcc
	global_store_short v[64:65], v68, off offset:512
	v_mov_b32_e32 v64, v221
	s_nop 0
	v_lshlrev_b32_e32 v64, 2, v64
	v_xor_b32_e32 v64, 0x80, v64
	ds_bpermute_b32 v68, v64, v91
	v_mov_b32_e32 v64, v221
	s_nop 0
	v_lshlrev_b32_e32 v64, 2, v64
	v_xor_b32_e32 v64, 0x80, v64
	ds_bpermute_b32 v69, v64, v75
	v_mov_b32_e32 v64, v221
	s_nop 0
	v_lshlrev_b32_e32 v64, 2, v64
	v_xor_b32_e32 v64, 0x80, v64
	ds_bpermute_b32 v70, v64, v92
	v_mov_b32_e32 v64, v221
	s_nop 0
	v_lshlrev_b32_e32 v64, 2, v64
	v_xor_b32_e32 v64, 0x80, v64
	ds_bpermute_b32 v71, v64, v76
	s_waitcnt lgkmcnt(3)
	v_cndmask_b32_e64 v64, v68, v66, s[0:1]
	v_mul_f32_e32 v64, v136, v64
	v_fmac_f32_e32 v64, v88, v137
	v_fmac_f32_e32 v64, v89, v139
	v_mul_f32_e32 v65, 0xbfb8aa3b, v64
	v_exp_f32_e32 v65, v65
	s_waitcnt lgkmcnt(2)
	v_cndmask_b32_e64 v66, v69, v67, s[0:1]
	s_waitcnt lgkmcnt(1)
	v_cndmask_b32_e64 v67, v70, v80, s[0:1]
	s_waitcnt lgkmcnt(0)
	v_cndmask_b32_e64 v80, v71, v81, s[0:1]
	v_add_f32_e32 v65, 1.0, v65
	v_rcp_f32_e32 v82, v65
	v_mul_f32_e32 v66, v138, v66
	v_fmac_f32_e32 v66, v72, v140
	v_fmac_f32_e32 v66, v73, v141
	v_mul_f32_e32 v81, v64, v82
	v_mov_b32_e32 v64, v81
	v_mul_f32_e32 v81, v89, v137
	v_fmac_f32_e32 v81, v88, v136
	v_mul_f32_e32 v64, v66, v64
	v_fmac_f32_e32 v81, v90, v139
	v_cvt_pk_bf16_f32 v66, v64, s0
	v_mul_f32_e32 v64, 0xbfb8aa3b, v81
	v_exp_f32_e32 v82, v64
	s_mov_b32 s12, 0x42000
	v_add_co_u32_e32 v64, vcc, s12, v130
	s_nop 1
	v_addc_co_u32_e32 v65, vcc, 0, v131, vcc
	global_store_short v[64:65], v66, off
	v_add_f32_e32 v64, 1.0, v82
	v_rcp_f32_e32 v66, v64
	v_mul_f32_e32 v82, v73, v140
	v_fmac_f32_e32 v82, v72, v138
	v_fmac_f32_e32 v82, v74, v141
	v_mul_f32_e32 v65, v81, v66
	v_mul_f32_e32 v72, v90, v137
	v_mov_b32_e32 v64, v65
	v_fmac_f32_e32 v72, v89, v136
	v_mul_f32_e32 v64, v82, v64
	v_fmac_f32_e32 v72, v91, v139
	v_cvt_pk_bf16_f32 v66, v64, s0
	v_mul_f32_e32 v64, 0xbfb8aa3b, v72
	v_exp_f32_e32 v81, v64
	s_mov_b32 s12, 0x43000
	v_add_co_u32_e32 v64, vcc, s12, v130
	s_nop 1
	v_addc_co_u32_e32 v65, vcc, 0, v131, vcc
	global_store_short v[64:65], v66, off offset:1536
	v_add_f32_e32 v64, 1.0, v81
	v_rcp_f32_e32 v66, v64
	v_mul_f32_e32 v81, v74, v140
	v_fmac_f32_e32 v81, v73, v138
	v_fmac_f32_e32 v81, v75, v141
	v_mul_f32_e32 v65, v72, v66
	v_mov_b32_e32 v64, v65
	v_mul_f32_e32 v72, v91, v137
	v_fmac_f32_e32 v72, v90, v136
	v_mul_f32_e32 v64, v81, v64
	v_fmac_f32_e32 v72, v139, v67
	v_cvt_pk_bf16_f32 v66, v64, s0
	v_mul_f32_e32 v64, 0xbfb8aa3b, v72
	v_exp_f32_e32 v67, v64
	s_mov_b32 s12, 0x44000
	v_add_co_u32_e32 v64, vcc, s12, v130
	s_nop 1
	v_addc_co_u32_e32 v65, vcc, 0, v131, vcc
	global_store_short v[64:65], v66, off offset:3072
	v_add_f32_e32 v64, 1.0, v67
	v_rcp_f32_e32 v66, v64
	v_mul_f32_e32 v67, v75, v140
	v_fmac_f32_e32 v67, v74, v138
	v_fmac_f32_e32 v67, v141, v80
	v_mul_f32_e32 v65, v72, v66
	v_mov_b32_e32 v64, v65
	v_mul_f32_e32 v64, v67, v64
	s_mov_b32 s12, 0x46000
	v_cvt_pk_bf16_f32 v66, v64, s0
	v_add_co_u32_e32 v64, vcc, s12, v130
	s_nop 1
	v_addc_co_u32_e32 v65, vcc, 0, v131, vcc
	global_store_short v[64:65], v66, off offset:512
	v_mov_b32_e32 v64, v221
	s_nop 0
	v_lshlrev_b32_e32 v64, 2, v64
	v_xor_b32_e32 v64, 0x80, v64
	ds_bpermute_b32 v66, v64, v95
	v_mov_b32_e32 v64, v221
	s_nop 0
	v_lshlrev_b32_e32 v64, 2, v64
	v_xor_b32_e32 v64, 0x80, v64
	ds_bpermute_b32 v67, v64, v79
	v_mov_b32_e32 v64, v221
	s_nop 0
	v_lshlrev_b32_e32 v64, 2, v64
	v_xor_b32_e32 v64, 0x80, v64
	ds_bpermute_b32 v72, v64, v48
	v_mov_b32_e32 v64, v221
	s_nop 0
	v_lshlrev_b32_e32 v64, 2, v64
	v_xor_b32_e32 v64, 0x80, v64
	ds_bpermute_b32 v73, v64, v32
	s_waitcnt lgkmcnt(3)
	v_cndmask_b32_e64 v64, v66, v68, s[0:1]
	v_mul_f32_e32 v64, v136, v64
	v_fmac_f32_e32 v64, v92, v137
	v_fmac_f32_e32 v64, v93, v139
	v_mul_f32_e32 v65, 0xbfb8aa3b, v64
	v_exp_f32_e32 v65, v65
	s_waitcnt lgkmcnt(2)
	v_cndmask_b32_e64 v68, v67, v69, s[0:1]
	s_waitcnt lgkmcnt(1)
	v_cndmask_b32_e64 v69, v72, v70, s[0:1]
	s_waitcnt lgkmcnt(0)
	v_cndmask_b32_e64 v70, v73, v71, s[0:1]
	v_add_f32_e32 v65, 1.0, v65
	v_rcp_f32_e32 v74, v65
	v_mul_f32_e32 v68, v138, v68
	v_fmac_f32_e32 v68, v76, v140
	v_fmac_f32_e32 v68, v77, v141
	v_mul_f32_e32 v71, v64, v74
	v_mov_b32_e32 v64, v71
	v_mul_f32_e32 v71, v93, v137
	v_fmac_f32_e32 v71, v92, v136
	v_mul_f32_e32 v64, v68, v64
	v_fmac_f32_e32 v71, v94, v139
	v_cvt_pk_bf16_f32 v68, v64, s0
	v_mul_f32_e32 v64, 0xbfb8aa3b, v71
	v_exp_f32_e32 v74, v64
	s_mov_b32 s12, 0x4d000
	v_add_co_u32_e32 v64, vcc, s12, v130
	s_nop 1
	v_addc_co_u32_e32 v65, vcc, 0, v131, vcc
	global_store_short v[64:65], v68, off
	v_add_f32_e32 v64, 1.0, v74
	v_rcp_f32_e32 v68, v64
	v_mul_f32_e32 v74, v77, v140
	v_fmac_f32_e32 v74, v76, v138
	v_fmac_f32_e32 v74, v78, v141
	v_mul_f32_e32 v65, v71, v68
	v_mov_b32_e32 v64, v65
	v_mul_f32_e32 v71, v94, v137
	v_fmac_f32_e32 v71, v93, v136
	v_mul_f32_e32 v64, v74, v64
	v_fmac_f32_e32 v71, v95, v139
	v_cvt_pk_bf16_f32 v68, v64, s0
	v_mul_f32_e32 v64, 0xbfb8aa3b, v71
	v_exp_f32_e32 v74, v64
	s_mov_b32 s12, 0x4e000
	v_add_co_u32_e32 v64, vcc, s12, v130
	s_nop 1
	v_addc_co_u32_e32 v65, vcc, 0, v131, vcc
	global_store_short v[64:65], v68, off offset:1536
	v_add_f32_e32 v64, 1.0, v74
	v_rcp_f32_e32 v68, v64
	v_mul_f32_e32 v74, v78, v140
	v_fmac_f32_e32 v74, v77, v138
	v_fmac_f32_e32 v74, v79, v141
	v_mul_f32_e32 v65, v71, v68
	v_mov_b32_e32 v64, v65
	v_mul_f32_e32 v71, v95, v137
	v_fmac_f32_e32 v71, v94, v136
	v_mul_f32_e32 v64, v74, v64
	v_fmac_f32_e32 v71, v139, v69
	v_cvt_pk_bf16_f32 v68, v64, s0
	v_mul_f32_e32 v64, 0xbfb8aa3b, v71
	v_exp_f32_e32 v69, v64
	s_mov_b32 s12, 0x4f000
	v_add_co_u32_e32 v64, vcc, s12, v130
	s_nop 1
	v_addc_co_u32_e32 v65, vcc, 0, v131, vcc
	global_store_short v[64:65], v68, off offset:3072
	v_add_f32_e32 v64, 1.0, v69
	v_rcp_f32_e32 v68, v64
	v_mul_f32_e32 v69, v79, v140
	v_fmac_f32_e32 v69, v78, v138
	v_fmac_f32_e32 v69, v141, v70
	v_mul_f32_e32 v65, v71, v68
	v_mov_b32_e32 v64, v65
	v_mul_f32_e32 v64, v69, v64
	s_mov_b32 s12, 0x51000
	v_cvt_pk_bf16_f32 v68, v64, s0
	v_add_co_u32_e32 v64, vcc, s12, v130
	s_nop 1
	v_addc_co_u32_e32 v65, vcc, 0, v131, vcc
	global_store_short v[64:65], v68, off offset:512
	v_mov_b32_e32 v64, v221
	s_nop 0
	v_lshlrev_b32_e32 v64, 2, v64
	v_xor_b32_e32 v64, 0x80, v64
	ds_bpermute_b32 v68, v64, v51
	v_mov_b32_e32 v64, v221
	s_nop 0
	v_lshlrev_b32_e32 v64, 2, v64
	v_xor_b32_e32 v64, 0x80, v64
	ds_bpermute_b32 v69, v64, v35
	v_mov_b32_e32 v64, v221
	s_nop 0
	v_lshlrev_b32_e32 v64, 2, v64
	v_xor_b32_e32 v64, 0x80, v64
	ds_bpermute_b32 v70, v64, v52
	v_mov_b32_e32 v64, v221
	s_nop 0
	v_lshlrev_b32_e32 v64, 2, v64
	v_xor_b32_e32 v64, 0x80, v64
	ds_bpermute_b32 v71, v64, v36
	s_waitcnt lgkmcnt(3)
	v_cndmask_b32_e64 v64, v68, v66, s[0:1]
	v_mul_f32_e32 v64, v136, v64
	v_fmac_f32_e32 v64, v48, v137
	v_fmac_f32_e32 v64, v49, v139
	v_mul_f32_e32 v65, 0xbfb8aa3b, v64
	v_exp_f32_e32 v65, v65
	s_waitcnt lgkmcnt(2)
	v_cndmask_b32_e64 v66, v69, v67, s[0:1]
	s_waitcnt lgkmcnt(1)
	v_cndmask_b32_e64 v67, v70, v72, s[0:1]
	s_waitcnt lgkmcnt(0)
	v_cndmask_b32_e64 v72, v71, v73, s[0:1]
	v_add_f32_e32 v65, 1.0, v65
	v_rcp_f32_e32 v74, v65
	v_mul_f32_e32 v66, v138, v66
	v_fmac_f32_e32 v66, v32, v140
	v_fmac_f32_e32 v66, v33, v141
	v_mul_f32_e32 v73, v64, v74
	v_mov_b32_e32 v64, v73
	v_mul_f32_e32 v73, v49, v137
	v_fmac_f32_e32 v73, v48, v136
	v_fmac_f32_e32 v73, v50, v139
	v_mul_f32_e32 v48, 0xbfb8aa3b, v73
	v_exp_f32_e32 v48, v48
	v_mul_f32_e32 v64, v66, v64
	s_mov_b32 s12, 0x58000
	v_cvt_pk_bf16_f32 v66, v64, s0
	v_add_co_u32_e32 v64, vcc, s12, v130
	v_add_f32_e32 v48, 1.0, v48
	s_nop 0
	v_addc_co_u32_e32 v65, vcc, 0, v131, vcc
	global_store_short v[64:65], v66, off
	v_rcp_f32_e32 v65, v48
	v_mul_f32_e32 v66, v33, v140
	v_fmac_f32_e32 v66, v32, v138
	v_fmac_f32_e32 v66, v34, v141
	v_mul_f32_e32 v64, v50, v137
	v_fmac_f32_e32 v64, v49, v136
	v_mul_f32_e32 v32, v73, v65
	v_fmac_f32_e32 v64, v51, v139
	v_mul_f32_e32 v48, 0xbfb8aa3b, v64
	v_exp_f32_e32 v65, v48
	s_mov_b32 s12, 0x59000
	v_mul_f32_e32 v32, v66, v32
	v_add_co_u32_e32 v48, vcc, s12, v130
	v_cvt_pk_bf16_f32 v32, v32, s0
	s_nop 0
	v_addc_co_u32_e32 v49, vcc, 0, v131, vcc
	global_store_short v[48:49], v32, off offset:1536
	v_add_f32_e32 v32, 1.0, v65
	v_rcp_f32_e32 v49, v32
	v_mul_f32_e32 v65, v34, v140
	v_fmac_f32_e32 v65, v33, v138
	v_fmac_f32_e32 v65, v35, v141
	v_mul_f32_e32 v33, v64, v49
	v_mul_f32_e32 v49, v51, v137
	v_mov_b32_e32 v32, v33
	v_fmac_f32_e32 v49, v50, v136
	v_mul_f32_e32 v32, v65, v32
	v_fmac_f32_e32 v49, v139, v67
	v_cvt_pk_bf16_f32 v48, v32, s0
	v_mul_f32_e32 v32, 0xbfb8aa3b, v49
	v_exp_f32_e32 v50, v32
	s_mov_b32 s12, 0x5a000
	v_add_co_u32_e32 v32, vcc, s12, v130
	v_mul_f32_e32 v35, v35, v140
	s_nop 0
	v_addc_co_u32_e32 v33, vcc, 0, v131, vcc
	global_store_short v[32:33], v48, off offset:3072
	v_add_f32_e32 v32, 1.0, v50
	v_rcp_f32_e32 v48, v32
	v_fmac_f32_e32 v35, v34, v138
	v_fmac_f32_e32 v35, v141, v72
	s_mov_b32 s12, 0x5c000
	v_mul_f32_e32 v33, v49, v48
	v_mov_b32_e32 v32, v33
	v_mul_f32_e32 v32, v35, v32
	v_cvt_pk_bf16_f32 v34, v32, s0
	v_add_co_u32_e32 v32, vcc, s12, v130
	s_nop 1
	v_addc_co_u32_e32 v33, vcc, 0, v131, vcc
	global_store_short v[32:33], v34, off offset:512
	v_mov_b32_e32 v32, v221
	s_nop 0
	v_lshlrev_b32_e32 v32, 2, v32
	v_xor_b32_e32 v32, 0x80, v32
	ds_bpermute_b32 v34, v32, v55
	v_mov_b32_e32 v32, v221
	s_nop 0
	v_lshlrev_b32_e32 v32, 2, v32
	v_xor_b32_e32 v32, 0x80, v32
	ds_bpermute_b32 v35, v32, v39
	v_mov_b32_e32 v32, v221
	s_waitcnt lgkmcnt(0)
	v_cndmask_b32_e64 v50, v35, v69, s[0:1]
	v_lshlrev_b32_e32 v32, 2, v32
	v_xor_b32_e32 v32, 0x80, v32
	ds_bpermute_b32 v48, v32, v56
	v_mov_b32_e32 v32, v221
	v_mul_f32_e32 v50, v138, v50
	v_lshlrev_b32_e32 v32, 2, v32
	v_xor_b32_e32 v32, 0x80, v32
	ds_bpermute_b32 v49, v32, v40
	v_cndmask_b32_e64 v32, v34, v68, s[0:1]
	v_mul_f32_e32 v32, v136, v32
	v_fmac_f32_e32 v32, v52, v137
	v_fmac_f32_e32 v32, v53, v139
	v_mul_f32_e32 v33, 0xbfb8aa3b, v32
	v_exp_f32_e32 v33, v33
	v_fmac_f32_e32 v50, v36, v140
	v_fmac_f32_e32 v50, v37, v141
	s_waitcnt lgkmcnt(1)
	v_cndmask_b32_e64 v51, v48, v70, s[0:1]
	v_add_f32_e32 v33, 1.0, v33
	v_rcp_f32_e32 v66, v33
	s_mov_b32 s12, 0x63000
	s_waitcnt lgkmcnt(0)
	v_cndmask_b32_e64 v64, v49, v71, s[0:1]
	v_mul_f32_e32 v65, v32, v66
	v_mov_b32_e32 v32, v65
	v_mul_f32_e32 v65, v53, v137
	v_fmac_f32_e32 v65, v52, v136
	v_mul_f32_e32 v32, v50, v32
	v_fmac_f32_e32 v65, v54, v139
	v_cvt_pk_bf16_f32 v50, v32, s0
	v_mul_f32_e32 v32, 0xbfb8aa3b, v65
	v_exp_f32_e32 v52, v32
	v_add_co_u32_e32 v32, vcc, s12, v130
	s_nop 1
	v_addc_co_u32_e32 v33, vcc, 0, v131, vcc
	global_store_short v[32:33], v50, off
	v_add_f32_e32 v32, 1.0, v52
	v_rcp_f32_e32 v50, v32
	v_mul_f32_e32 v52, v37, v140
	v_fmac_f32_e32 v52, v36, v138
	v_fmac_f32_e32 v52, v38, v141
	v_mul_f32_e32 v33, v65, v50
	v_mul_f32_e32 v50, v54, v137
	v_mov_b32_e32 v32, v33
	v_fmac_f32_e32 v50, v53, v136
	v_mul_f32_e32 v32, v52, v32
	v_fmac_f32_e32 v50, v55, v139
	v_cvt_pk_bf16_f32 v36, v32, s0
	v_mul_f32_e32 v32, 0xbfb8aa3b, v50
	v_exp_f32_e32 v52, v32
	s_mov_b32 s12, 0x64000
	v_add_co_u32_e32 v32, vcc, s12, v130
	s_nop 1
	v_addc_co_u32_e32 v33, vcc, 0, v131, vcc
	global_store_short v[32:33], v36, off offset:1536
	v_add_f32_e32 v32, 1.0, v52
	v_rcp_f32_e32 v36, v32
	v_mul_f32_e32 v52, v38, v140
	v_fmac_f32_e32 v52, v37, v138
	v_fmac_f32_e32 v52, v39, v141
	v_mul_f32_e32 v33, v50, v36
	v_mul_f32_e32 v37, v55, v137
	v_mov_b32_e32 v32, v33
	v_fmac_f32_e32 v37, v54, v136
	v_mul_f32_e32 v32, v52, v32
	v_fmac_f32_e32 v37, v139, v51
	v_cvt_pk_bf16_f32 v36, v32, s0
	v_mul_f32_e32 v32, 0xbfb8aa3b, v37
	v_exp_f32_e32 v50, v32
	s_mov_b32 s12, 0x65000
	v_add_co_u32_e32 v32, vcc, s12, v130
	v_mul_f32_e32 v39, v39, v140
	s_nop 0
	v_addc_co_u32_e32 v33, vcc, 0, v131, vcc
	global_store_short v[32:33], v36, off offset:3072
	v_add_f32_e32 v32, 1.0, v50
	v_rcp_f32_e32 v36, v32
	v_fmac_f32_e32 v39, v38, v138
	v_fmac_f32_e32 v39, v141, v64
	s_mov_b32 s12, 0x67000
	v_mul_f32_e32 v33, v37, v36
	v_mov_b32_e32 v32, v33
	v_mul_f32_e32 v32, v39, v32
	v_cvt_pk_bf16_f32 v36, v32, s0
	v_add_co_u32_e32 v32, vcc, s12, v130
	s_nop 1
	v_addc_co_u32_e32 v33, vcc, 0, v131, vcc
	global_store_short v[32:33], v36, off offset:512
	v_mov_b32_e32 v32, v221
	s_nop 0
	v_lshlrev_b32_e32 v32, 2, v32
	v_xor_b32_e32 v32, 0x80, v32
	ds_bpermute_b32 v36, v32, v59
	v_mov_b32_e32 v32, v221
	s_nop 0
	v_lshlrev_b32_e32 v32, 2, v32
	v_xor_b32_e32 v32, 0x80, v32
	ds_bpermute_b32 v37, v32, v43
	v_mov_b32_e32 v32, v221
	s_nop 0
	v_lshlrev_b32_e32 v32, 2, v32
	v_xor_b32_e32 v32, 0x80, v32
	ds_bpermute_b32 v38, v32, v60
	v_mov_b32_e32 v32, v221
	s_nop 0
	v_lshlrev_b32_e32 v32, 2, v32
	v_xor_b32_e32 v32, 0x80, v32
	ds_bpermute_b32 v39, v32, v44
	s_waitcnt lgkmcnt(3)
	v_cndmask_b32_e64 v32, v36, v34, s[0:1]
	v_mul_f32_e32 v32, v136, v32
	v_fmac_f32_e32 v32, v56, v137
	v_fmac_f32_e32 v32, v57, v139
	v_mul_f32_e32 v33, 0xbfb8aa3b, v32
	v_exp_f32_e32 v33, v33
	s_waitcnt lgkmcnt(2)
	v_cndmask_b32_e64 v34, v37, v35, s[0:1]
	s_waitcnt lgkmcnt(1)
	v_cndmask_b32_e64 v35, v38, v48, s[0:1]
	s_waitcnt lgkmcnt(0)
	v_cndmask_b32_e64 v48, v39, v49, s[0:1]
	v_add_f32_e32 v33, 1.0, v33
	v_rcp_f32_e32 v50, v33
	v_mul_f32_e32 v34, v138, v34
	v_fmac_f32_e32 v34, v40, v140
	v_fmac_f32_e32 v34, v41, v141
	v_mul_f32_e32 v49, v32, v50
	v_mov_b32_e32 v32, v49
	v_mul_f32_e32 v49, v57, v137
	v_fmac_f32_e32 v49, v56, v136
	v_mul_f32_e32 v32, v34, v32
	v_fmac_f32_e32 v49, v58, v139
	v_cvt_pk_bf16_f32 v34, v32, s0
	v_mul_f32_e32 v32, 0xbfb8aa3b, v49
	v_exp_f32_e32 v50, v32
	s_mov_b32 s12, 0x6e000
	v_add_co_u32_e32 v32, vcc, s12, v130
	s_nop 1
	v_addc_co_u32_e32 v33, vcc, 0, v131, vcc
	global_store_short v[32:33], v34, off
	v_add_f32_e32 v32, 1.0, v50
	v_rcp_f32_e32 v34, v32
	v_mul_f32_e32 v50, v41, v140
	v_fmac_f32_e32 v50, v40, v138
	v_fmac_f32_e32 v50, v42, v141
	v_mul_f32_e32 v33, v49, v34
	v_mul_f32_e32 v40, v58, v137
	v_mov_b32_e32 v32, v33
	v_fmac_f32_e32 v40, v57, v136
	v_mul_f32_e32 v32, v50, v32
	v_fmac_f32_e32 v40, v59, v139
	v_cvt_pk_bf16_f32 v34, v32, s0
	v_mul_f32_e32 v32, 0xbfb8aa3b, v40
	v_exp_f32_e32 v49, v32
	s_mov_b32 s12, 0x6f000
	v_add_co_u32_e32 v32, vcc, s12, v130
	s_nop 1
	v_addc_co_u32_e32 v33, vcc, 0, v131, vcc
	global_store_short v[32:33], v34, off offset:1536
	v_add_f32_e32 v32, 1.0, v49
	v_rcp_f32_e32 v34, v32
	v_mul_f32_e32 v49, v42, v140
	v_fmac_f32_e32 v49, v41, v138
	v_fmac_f32_e32 v49, v43, v141
	v_mul_f32_e32 v33, v40, v34
	v_mov_b32_e32 v32, v33
	v_mul_f32_e32 v40, v59, v137
	v_fmac_f32_e32 v40, v58, v136
	v_mul_f32_e32 v32, v49, v32
	v_fmac_f32_e32 v40, v139, v35
	v_cvt_pk_bf16_f32 v34, v32, s0
	v_mul_f32_e32 v32, 0xbfb8aa3b, v40
	v_exp_f32_e32 v35, v32
	s_mov_b32 s12, 0x70000
	v_add_co_u32_e32 v32, vcc, s12, v130
	s_nop 1
	v_addc_co_u32_e32 v33, vcc, 0, v131, vcc
	global_store_short v[32:33], v34, off offset:3072
	v_add_f32_e32 v32, 1.0, v35
	v_rcp_f32_e32 v34, v32
	v_mul_f32_e32 v35, v43, v140
	v_fmac_f32_e32 v35, v42, v138
	v_fmac_f32_e32 v35, v141, v48
	v_mul_f32_e32 v33, v40, v34
	v_mov_b32_e32 v32, v33
	v_mul_f32_e32 v32, v35, v32
	s_mov_b32 s12, 0x72000
	v_cvt_pk_bf16_f32 v34, v32, s0
	v_add_co_u32_e32 v32, vcc, s12, v130
	s_nop 1
	v_addc_co_u32_e32 v33, vcc, 0, v131, vcc
	global_store_short v[32:33], v34, off offset:512
	v_mov_b32_e32 v32, v221
	s_nop 0
	v_lshlrev_b32_e32 v32, 2, v32
	v_xor_b32_e32 v32, 0x80, v32
	ds_bpermute_b32 v34, v32, v63
	v_mov_b32_e32 v32, v221
	s_nop 0
	v_lshlrev_b32_e32 v32, 2, v32
	v_xor_b32_e32 v32, 0x80, v32
	ds_bpermute_b32 v35, v32, v47
	v_mov_b32_e32 v32, v221
	s_nop 0
	v_lshlrev_b32_e32 v32, 2, v32
	v_xor_b32_e32 v32, 0x80, v32
	ds_bpermute_b32 v40, v32, v16
	v_mov_b32_e32 v32, v221
	s_nop 0
	v_lshlrev_b32_e32 v32, 2, v32
	v_xor_b32_e32 v32, 0x80, v32
	ds_bpermute_b32 v41, v32, v0
	s_waitcnt lgkmcnt(3)
	v_cndmask_b32_e64 v32, v34, v36, s[0:1]
	v_mul_f32_e32 v32, v136, v32
	v_fmac_f32_e32 v32, v60, v137
	v_fmac_f32_e32 v32, v61, v139
	v_mul_f32_e32 v33, 0xbfb8aa3b, v32
	v_exp_f32_e32 v33, v33
	s_waitcnt lgkmcnt(2)
	v_cndmask_b32_e64 v36, v35, v37, s[0:1]
	s_waitcnt lgkmcnt(1)
	v_cndmask_b32_e64 v37, v40, v38, s[0:1]
	s_waitcnt lgkmcnt(0)
	v_cndmask_b32_e64 v38, v41, v39, s[0:1]
	v_add_f32_e32 v33, 1.0, v33
	v_rcp_f32_e32 v42, v33
	v_mul_f32_e32 v36, v138, v36
	v_fmac_f32_e32 v36, v44, v140
	v_fmac_f32_e32 v36, v45, v141
	v_mul_f32_e32 v39, v32, v42
	v_mov_b32_e32 v32, v39
	v_mul_f32_e32 v39, v61, v137
	v_fmac_f32_e32 v39, v60, v136
	v_mul_f32_e32 v32, v36, v32
	v_fmac_f32_e32 v39, v62, v139
	v_cvt_pk_bf16_f32 v36, v32, s0
	v_mul_f32_e32 v32, 0xbfb8aa3b, v39
	v_exp_f32_e32 v42, v32
	s_mov_b32 s12, 0x79000
	v_add_co_u32_e32 v32, vcc, s12, v130
	s_nop 1
	v_addc_co_u32_e32 v33, vcc, 0, v131, vcc
	global_store_short v[32:33], v36, off
	v_add_f32_e32 v32, 1.0, v42
	v_rcp_f32_e32 v36, v32
	v_mul_f32_e32 v42, v45, v140
	v_fmac_f32_e32 v42, v44, v138
	v_fmac_f32_e32 v42, v46, v141
	v_mul_f32_e32 v33, v39, v36
	v_mov_b32_e32 v32, v33
	v_mul_f32_e32 v39, v62, v137
	v_fmac_f32_e32 v39, v61, v136
	v_mul_f32_e32 v32, v42, v32
	v_fmac_f32_e32 v39, v63, v139
	v_cvt_pk_bf16_f32 v36, v32, s0
	v_mul_f32_e32 v32, 0xbfb8aa3b, v39
	v_exp_f32_e32 v42, v32
	s_mov_b32 s12, 0x7a000
	v_add_co_u32_e32 v32, vcc, s12, v130
	s_nop 1
	v_addc_co_u32_e32 v33, vcc, 0, v131, vcc
	global_store_short v[32:33], v36, off offset:1536
	v_add_f32_e32 v32, 1.0, v42
	v_rcp_f32_e32 v36, v32
	v_mul_f32_e32 v42, v46, v140
	v_fmac_f32_e32 v42, v45, v138
	v_fmac_f32_e32 v42, v47, v141
	v_mul_f32_e32 v33, v39, v36
	v_mov_b32_e32 v32, v33
	v_mul_f32_e32 v39, v63, v137
	v_fmac_f32_e32 v39, v62, v136
	v_mul_f32_e32 v32, v42, v32
	v_fmac_f32_e32 v39, v139, v37
	v_cvt_pk_bf16_f32 v36, v32, s0
	v_mul_f32_e32 v32, 0xbfb8aa3b, v39
	v_exp_f32_e32 v37, v32
	s_mov_b32 s12, 0x7b000
	v_add_co_u32_e32 v32, vcc, s12, v130
	s_nop 1
	v_addc_co_u32_e32 v33, vcc, 0, v131, vcc
	global_store_short v[32:33], v36, off offset:3072
	v_add_f32_e32 v32, 1.0, v37
	v_rcp_f32_e32 v36, v32
	v_mul_f32_e32 v37, v47, v140
	v_fmac_f32_e32 v37, v46, v138
	v_fmac_f32_e32 v37, v141, v38
	v_mul_f32_e32 v33, v39, v36
	v_mov_b32_e32 v32, v33
	v_mul_f32_e32 v32, v37, v32
	s_mov_b32 s12, 0x7d000
	v_cvt_pk_bf16_f32 v36, v32, s0
	v_add_co_u32_e32 v32, vcc, s12, v130
	s_nop 1
	v_addc_co_u32_e32 v33, vcc, 0, v131, vcc
	global_store_short v[32:33], v36, off offset:512
	v_mov_b32_e32 v32, v221
	s_nop 0
	v_lshlrev_b32_e32 v32, 2, v32
	v_xor_b32_e32 v32, 0x80, v32
	ds_bpermute_b32 v36, v32, v19
	v_mov_b32_e32 v32, v221
	s_nop 0
	v_lshlrev_b32_e32 v32, 2, v32
	v_xor_b32_e32 v32, 0x80, v32
	ds_bpermute_b32 v37, v32, v3
	v_mov_b32_e32 v32, v221
	s_nop 0
	v_lshlrev_b32_e32 v32, 2, v32
	v_xor_b32_e32 v32, 0x80, v32
	ds_bpermute_b32 v38, v32, v20
	v_mov_b32_e32 v32, v221
	s_nop 0
	v_lshlrev_b32_e32 v32, 2, v32
	v_xor_b32_e32 v32, 0x80, v32
	ds_bpermute_b32 v39, v32, v4
	s_waitcnt lgkmcnt(3)
	v_cndmask_b32_e64 v32, v36, v34, s[0:1]
	v_mul_f32_e32 v32, v136, v32
	v_fmac_f32_e32 v32, v16, v137
	v_fmac_f32_e32 v32, v17, v139
	v_mul_f32_e32 v33, 0xbfb8aa3b, v32
	v_exp_f32_e32 v33, v33
	s_waitcnt lgkmcnt(2)
	v_cndmask_b32_e64 v34, v37, v35, s[0:1]
	s_waitcnt lgkmcnt(1)
	v_cndmask_b32_e64 v35, v38, v40, s[0:1]
	s_waitcnt lgkmcnt(0)
	v_cndmask_b32_e64 v40, v39, v41, s[0:1]
	v_add_f32_e32 v33, 1.0, v33
	v_rcp_f32_e32 v42, v33
	v_mul_f32_e32 v34, v138, v34
	v_fmac_f32_e32 v34, v0, v140
	v_fmac_f32_e32 v34, v1, v141
	v_mul_f32_e32 v41, v32, v42
	v_mov_b32_e32 v32, v41
	v_mul_f32_e32 v41, v17, v137
	v_fmac_f32_e32 v41, v16, v136
	v_fmac_f32_e32 v41, v18, v139
	v_mul_f32_e32 v16, 0xbfb8aa3b, v41
	v_exp_f32_e32 v16, v16
	v_mul_f32_e32 v32, v34, v32
	s_mov_b32 s12, 0x84000
	v_cvt_pk_bf16_f32 v34, v32, s0
	v_add_co_u32_e32 v32, vcc, s12, v130
	v_add_f32_e32 v16, 1.0, v16
	s_nop 0
	v_addc_co_u32_e32 v33, vcc, 0, v131, vcc
	global_store_short v[32:33], v34, off
	v_rcp_f32_e32 v33, v16
	v_mul_f32_e32 v34, v1, v140
	v_fmac_f32_e32 v34, v0, v138
	v_fmac_f32_e32 v34, v2, v141
	v_mul_f32_e32 v32, v18, v137
	v_fmac_f32_e32 v32, v17, v136
	v_mul_f32_e32 v0, v41, v33
	v_fmac_f32_e32 v32, v19, v139
	v_mul_f32_e32 v16, 0xbfb8aa3b, v32
	v_exp_f32_e32 v33, v16
	s_mov_b32 s12, 0x85000
	v_mul_f32_e32 v0, v34, v0
	v_add_co_u32_e32 v16, vcc, s12, v130
	v_cvt_pk_bf16_f32 v0, v0, s0
	s_nop 0
	v_addc_co_u32_e32 v17, vcc, 0, v131, vcc
	global_store_short v[16:17], v0, off offset:1536
	v_add_f32_e32 v0, 1.0, v33
	v_rcp_f32_e32 v17, v0
	v_mul_f32_e32 v33, v2, v140
	v_fmac_f32_e32 v33, v1, v138
	v_fmac_f32_e32 v33, v3, v141
	v_mul_f32_e32 v1, v32, v17
	v_mul_f32_e32 v17, v19, v137
	v_mov_b32_e32 v0, v1
	v_fmac_f32_e32 v17, v18, v136
	v_mul_f32_e32 v0, v33, v0
	v_fmac_f32_e32 v17, v139, v35
	v_cvt_pk_bf16_f32 v16, v0, s0
	v_mul_f32_e32 v0, 0xbfb8aa3b, v17
	v_exp_f32_e32 v18, v0
	s_mov_b32 s12, 0x86000
	v_add_co_u32_e32 v0, vcc, s12, v130
	v_mul_f32_e32 v3, v3, v140
	s_nop 0
	v_addc_co_u32_e32 v1, vcc, 0, v131, vcc
	global_store_short v[0:1], v16, off offset:3072
	v_add_f32_e32 v0, 1.0, v18
	v_rcp_f32_e32 v16, v0
	v_fmac_f32_e32 v3, v2, v138
	v_fmac_f32_e32 v3, v141, v40
	s_mov_b32 s12, 0x88000
	v_mul_f32_e32 v1, v17, v16
	v_mov_b32_e32 v0, v1
	v_mul_f32_e32 v0, v3, v0
	v_cvt_pk_bf16_f32 v2, v0, s0
	v_add_co_u32_e32 v0, vcc, s12, v130
	s_nop 1
	v_addc_co_u32_e32 v1, vcc, 0, v131, vcc
	global_store_short v[0:1], v2, off offset:512
	v_mov_b32_e32 v0, v221
	s_nop 0
	v_lshlrev_b32_e32 v0, 2, v0
	v_xor_b32_e32 v0, 0x80, v0
	ds_bpermute_b32 v2, v0, v23
	v_mov_b32_e32 v0, v221
	s_nop 0
	v_lshlrev_b32_e32 v0, 2, v0
	v_xor_b32_e32 v0, 0x80, v0
	ds_bpermute_b32 v3, v0, v7
	v_mov_b32_e32 v0, v221
	s_waitcnt lgkmcnt(0)
	v_cndmask_b32_e64 v18, v3, v37, s[0:1]
	v_lshlrev_b32_e32 v0, 2, v0
	v_xor_b32_e32 v0, 0x80, v0
	ds_bpermute_b32 v16, v0, v24
	v_mov_b32_e32 v0, v221
	v_mul_f32_e32 v18, v138, v18
	v_lshlrev_b32_e32 v0, 2, v0
	v_xor_b32_e32 v0, 0x80, v0
	ds_bpermute_b32 v17, v0, v8
	v_cndmask_b32_e64 v0, v2, v36, s[0:1]
	v_mul_f32_e32 v0, v136, v0
	v_fmac_f32_e32 v0, v20, v137
	v_fmac_f32_e32 v0, v21, v139
	v_mul_f32_e32 v1, 0xbfb8aa3b, v0
	v_exp_f32_e32 v1, v1
	v_fmac_f32_e32 v18, v4, v140
	v_fmac_f32_e32 v18, v5, v141
	s_waitcnt lgkmcnt(1)
	v_cndmask_b32_e64 v19, v16, v38, s[0:1]
	v_add_f32_e32 v1, 1.0, v1
	v_rcp_f32_e32 v34, v1
	s_mov_b32 s12, 0x8f000
	s_waitcnt lgkmcnt(0)
	v_cndmask_b32_e64 v32, v17, v39, s[0:1]
	v_mul_f32_e32 v33, v0, v34
	v_mov_b32_e32 v0, v33
	v_mul_f32_e32 v33, v21, v137
	v_fmac_f32_e32 v33, v20, v136
	v_mul_f32_e32 v0, v18, v0
	v_fmac_f32_e32 v33, v22, v139
	v_cvt_pk_bf16_f32 v18, v0, s0
	v_mul_f32_e32 v0, 0xbfb8aa3b, v33
	v_exp_f32_e32 v20, v0
	v_add_co_u32_e32 v0, vcc, s12, v130
	s_nop 1
	v_addc_co_u32_e32 v1, vcc, 0, v131, vcc
	global_store_short v[0:1], v18, off
	v_add_f32_e32 v0, 1.0, v20
	v_rcp_f32_e32 v18, v0
	v_mul_f32_e32 v20, v5, v140
	v_fmac_f32_e32 v20, v4, v138
	v_fmac_f32_e32 v20, v6, v141
	v_mul_f32_e32 v1, v33, v18
	v_mul_f32_e32 v18, v22, v137
	v_mov_b32_e32 v0, v1
	v_fmac_f32_e32 v18, v21, v136
	v_mul_f32_e32 v0, v20, v0
	v_fmac_f32_e32 v18, v23, v139
	v_cvt_pk_bf16_f32 v4, v0, s0
	v_mul_f32_e32 v0, 0xbfb8aa3b, v18
	v_exp_f32_e32 v20, v0
	s_mov_b32 s12, 0x90000
	v_add_co_u32_e32 v0, vcc, s12, v130
	s_nop 1
	v_addc_co_u32_e32 v1, vcc, 0, v131, vcc
	global_store_short v[0:1], v4, off offset:1536
	v_add_f32_e32 v0, 1.0, v20
	v_rcp_f32_e32 v4, v0
	v_mul_f32_e32 v20, v6, v140
	v_fmac_f32_e32 v20, v5, v138
	v_fmac_f32_e32 v20, v7, v141
	v_mul_f32_e32 v1, v18, v4
	v_mul_f32_e32 v5, v23, v137
	v_mov_b32_e32 v0, v1
	v_fmac_f32_e32 v5, v22, v136
	v_mul_f32_e32 v0, v20, v0
	v_fmac_f32_e32 v5, v139, v19
	v_cvt_pk_bf16_f32 v4, v0, s0
	v_mul_f32_e32 v0, 0xbfb8aa3b, v5
	v_exp_f32_e32 v18, v0
	s_mov_b32 s12, 0x91000
	v_add_co_u32_e32 v0, vcc, s12, v130
	v_mul_f32_e32 v7, v7, v140
	s_nop 0
	v_addc_co_u32_e32 v1, vcc, 0, v131, vcc
	global_store_short v[0:1], v4, off offset:3072
	v_add_f32_e32 v0, 1.0, v18
	v_rcp_f32_e32 v4, v0
	v_fmac_f32_e32 v7, v6, v138
	v_fmac_f32_e32 v7, v141, v32
	s_mov_b32 s12, 0x93000
	v_mul_f32_e32 v1, v5, v4
	v_mov_b32_e32 v0, v1
	v_mul_f32_e32 v0, v7, v0
	v_cvt_pk_bf16_f32 v4, v0, s0
	v_add_co_u32_e32 v0, vcc, s12, v130
	s_nop 1
	v_addc_co_u32_e32 v1, vcc, 0, v131, vcc
	global_store_short v[0:1], v4, off offset:512
	v_mov_b32_e32 v0, v221
	s_nop 0
	v_lshlrev_b32_e32 v0, 2, v0
	v_xor_b32_e32 v0, 0x80, v0
	ds_bpermute_b32 v4, v0, v27
	v_mov_b32_e32 v0, v221
	s_nop 0
	v_lshlrev_b32_e32 v0, 2, v0
	v_xor_b32_e32 v0, 0x80, v0
	ds_bpermute_b32 v5, v0, v11
	v_mov_b32_e32 v0, v221
	s_nop 0
	v_lshlrev_b32_e32 v0, 2, v0
	v_xor_b32_e32 v0, 0x80, v0
	ds_bpermute_b32 v6, v0, v28
	v_mov_b32_e32 v0, v221
	s_nop 0
	v_lshlrev_b32_e32 v0, 2, v0
	v_xor_b32_e32 v0, 0x80, v0
	ds_bpermute_b32 v7, v0, v12
	s_waitcnt lgkmcnt(3)
	v_cndmask_b32_e64 v0, v4, v2, s[0:1]
	v_mul_f32_e32 v0, v136, v0
	v_fmac_f32_e32 v0, v24, v137
	v_fmac_f32_e32 v0, v25, v139
	v_mul_f32_e32 v1, 0xbfb8aa3b, v0
	v_exp_f32_e32 v1, v1
	s_waitcnt lgkmcnt(2)
	v_cndmask_b32_e64 v2, v5, v3, s[0:1]
	s_waitcnt lgkmcnt(1)
	v_cndmask_b32_e64 v3, v6, v16, s[0:1]
	s_waitcnt lgkmcnt(0)
	v_cndmask_b32_e64 v16, v7, v17, s[0:1]
	v_add_f32_e32 v1, 1.0, v1
	v_rcp_f32_e32 v18, v1
	v_mul_f32_e32 v2, v138, v2
	v_fmac_f32_e32 v2, v8, v140
	v_fmac_f32_e32 v2, v9, v141
	v_mul_f32_e32 v17, v0, v18
	v_mov_b32_e32 v0, v17
	v_mul_f32_e32 v17, v25, v137
	v_fmac_f32_e32 v17, v24, v136
	v_mul_f32_e32 v0, v2, v0
	v_fmac_f32_e32 v17, v26, v139
	v_cvt_pk_bf16_f32 v2, v0, s0
	v_mul_f32_e32 v0, 0xbfb8aa3b, v17
	v_exp_f32_e32 v18, v0
	s_mov_b32 s12, 0x9a000
	v_add_co_u32_e32 v0, vcc, s12, v130
	s_nop 1
	v_addc_co_u32_e32 v1, vcc, 0, v131, vcc
	global_store_short v[0:1], v2, off
	v_add_f32_e32 v0, 1.0, v18
	v_rcp_f32_e32 v2, v0
	v_mul_f32_e32 v18, v9, v140
	v_fmac_f32_e32 v18, v8, v138
	v_fmac_f32_e32 v18, v10, v141
	v_mul_f32_e32 v1, v17, v2
	v_mul_f32_e32 v8, v26, v137
	v_mov_b32_e32 v0, v1
	v_fmac_f32_e32 v8, v25, v136
	v_mul_f32_e32 v0, v18, v0
	v_fmac_f32_e32 v8, v27, v139
	v_cvt_pk_bf16_f32 v2, v0, s0
	v_mul_f32_e32 v0, 0xbfb8aa3b, v8
	v_exp_f32_e32 v17, v0
	s_mov_b32 s12, 0x9b000
	v_add_co_u32_e32 v0, vcc, s12, v130
	s_nop 1
	v_addc_co_u32_e32 v1, vcc, 0, v131, vcc
	global_store_short v[0:1], v2, off offset:1536
	v_add_f32_e32 v0, 1.0, v17
	v_rcp_f32_e32 v2, v0
	v_mul_f32_e32 v17, v10, v140
	v_fmac_f32_e32 v17, v9, v138
	v_fmac_f32_e32 v17, v11, v141
	v_mul_f32_e32 v1, v8, v2
	v_mov_b32_e32 v0, v1
	v_mul_f32_e32 v8, v27, v137
	v_fmac_f32_e32 v8, v26, v136
	v_mul_f32_e32 v0, v17, v0
	v_fmac_f32_e32 v8, v139, v3
	v_cvt_pk_bf16_f32 v2, v0, s0
	v_mul_f32_e32 v0, 0xbfb8aa3b, v8
	v_exp_f32_e32 v3, v0
	s_mov_b32 s12, 0x9c000
	v_add_co_u32_e32 v0, vcc, s12, v130
	s_nop 1
	v_addc_co_u32_e32 v1, vcc, 0, v131, vcc
	global_store_short v[0:1], v2, off offset:3072
	v_add_f32_e32 v0, 1.0, v3
	v_rcp_f32_e32 v2, v0
	v_mul_f32_e32 v3, v11, v140
	v_fmac_f32_e32 v3, v10, v138
	v_fmac_f32_e32 v3, v141, v16
	v_mul_f32_e32 v1, v8, v2
	v_mov_b32_e32 v0, v1
	v_mul_f32_e32 v0, v3, v0
	s_mov_b32 s12, 0x9e000
	v_cvt_pk_bf16_f32 v2, v0, s0
	v_add_co_u32_e32 v0, vcc, s12, v130
	s_nop 1
	v_addc_co_u32_e32 v1, vcc, 0, v131, vcc
	global_store_short v[0:1], v2, off offset:512
	v_mov_b32_e32 v0, v221
	v_mov_b32_e32 v1, v221
	v_lshlrev_b32_e32 v0, 2, v0
	v_xor_b32_e32 v0, 0x80, v0
	ds_bpermute_b32 v0, v0, v31
	s_waitcnt lgkmcnt(0)
	v_cndmask_b32_e64 v0, v0, v4, s[0:1]
	v_mul_f32_e32 v0, v136, v0
	v_fmac_f32_e32 v0, v28, v137
	v_fmac_f32_e32 v0, v29, v139
	v_mul_f32_e32 v2, 0xbfb8aa3b, v0
	v_exp_f32_e32 v2, v2
	v_lshlrev_b32_e32 v1, 2, v1
	v_xor_b32_e32 v1, 0x80, v1
	ds_bpermute_b32 v1, v1, v15
	v_add_f32_e32 v2, 1.0, v2
	v_rcp_f32_e32 v4, v2
	s_waitcnt lgkmcnt(0)
	v_cndmask_b32_e64 v1, v1, v5, s[0:1]
	v_mul_f32_e32 v1, v138, v1
	v_fmac_f32_e32 v1, v12, v140
	v_mul_f32_e32 v3, v0, v4
	v_mov_b32_e32 v0, v3
	v_mul_f32_e32 v3, v29, v137
	v_fmac_f32_e32 v1, v13, v141
	v_fmac_f32_e32 v3, v28, v136
	v_mul_f32_e32 v0, v1, v0
	v_fmac_f32_e32 v3, v139, v30
	v_cvt_pk_bf16_f32 v2, v0, s0
	v_mul_f32_e32 v0, 0xbfb8aa3b, v3
	v_exp_f32_e32 v4, v0
	s_mov_b32 s12, 0xa5000
	v_add_co_u32_e32 v0, vcc, s12, v130
	s_nop 1
	v_addc_co_u32_e32 v1, vcc, 0, v131, vcc
	global_store_short v[0:1], v2, off
	v_add_f32_e32 v0, 1.0, v4
	v_rcp_f32_e32 v2, v0
	v_mul_f32_e32 v4, v13, v140
	v_fmac_f32_e32 v4, v12, v138
	v_fmac_f32_e32 v4, v141, v14
	v_mul_f32_e32 v1, v3, v2
	v_mov_b32_e32 v0, v1
	v_mul_f32_e32 v3, v137, v30
	v_fmac_f32_e32 v3, v29, v136
	v_mul_f32_e32 v0, v4, v0
	v_fmac_f32_e32 v3, v139, v31
	v_cvt_pk_bf16_f32 v2, v0, s0
	v_mul_f32_e32 v0, 0xbfb8aa3b, v3
	v_exp_f32_e32 v4, v0
	s_mov_b32 s12, 0xa6000
	v_add_co_u32_e32 v0, vcc, s12, v130
	s_nop 1
	v_addc_co_u32_e32 v1, vcc, 0, v131, vcc
	global_store_short v[0:1], v2, off offset:1536
	v_add_f32_e32 v0, 1.0, v4
	v_rcp_f32_e32 v2, v0
	v_mul_f32_e32 v4, v140, v14
	v_fmac_f32_e32 v4, v13, v138
	v_fmac_f32_e32 v4, v141, v15
	v_mul_f32_e32 v1, v3, v2
	v_mov_b32_e32 v0, v1
	v_mul_f32_e32 v0, v4, v0
	v_mul_f32_e32 v3, v136, v30
	v_cvt_pk_bf16_f32 v2, v0, s0
	v_cndmask_b32_e64 v0, 0, v6, s[0:1]
	v_fmac_f32_e32 v3, v137, v31
	v_fmac_f32_e32 v3, v139, v0
	v_mul_f32_e32 v0, 0xbfb8aa3b, v3
	v_exp_f32_e32 v4, v0
	s_mov_b32 s12, 0xa7000
	v_add_co_u32_e32 v0, vcc, s12, v130
	v_mul_f32_e32 v5, v138, v14
	s_nop 0
	v_addc_co_u32_e32 v1, vcc, 0, v131, vcc
	global_store_short v[0:1], v2, off offset:3072
	v_add_f32_e32 v1, 1.0, v4
	v_rcp_f32_e32 v4, v1
	v_cndmask_b32_e64 v0, 0, v7, s[0:1]
	v_fmac_f32_e32 v5, v140, v15
	v_fmac_f32_e32 v5, v141, v0
	v_mul_f32_e32 v0, v3, v4
	v_readlane_b32 s12, v252, 7
	v_mul_f32_e32 v0, v5, v0
	s_add_i32 s14, s14, s12
	s_add_i32 s15, s15, s12
	v_readlane_b32 s12, v252, 8
	v_cvt_pk_bf16_f32 v2, v0, s0
	v_add_co_u32_e32 v0, vcc, 0xa9000, v130
	s_add_i32 s17, s17, s12
	s_nop 0
	v_addc_co_u32_e32 v1, vcc, 0, v131, vcc
	s_cmpk_lt_i32 s14, 0xb0
	global_store_short v[0:1], v2, off offset:512
	s_cbranch_scc0 .LBB0_2345
